# gdn prep forward substitution: FMA pairs of the two partial sums packed as v_pk_fma_f32 (same f32 math and order)
# speedup vs baseline: 1.0108x; 1.0108x over previous
.LBB0_1186:
	s_or_b64 exec, exec, s[8:9]
	s_waitcnt lgkmcnt(14)
	v_mul_f32_e32 v2, v0, v6
	v_and_b32_e32 v0, 0xffffc000, v70
	v_cndmask_b32_e32 v6, 0, v246, vcc
	v_add3_u32 v6, v133, v27, v6
	v_add_u32_e32 v74, v135, v0
	ds_read_b32 v73, v6
	s_waitcnt lgkmcnt(0)
	s_barrier
	ds_read_b128 v[144:147], v74 offset:256
	s_waitcnt lgkmcnt(0)
	v_mul_f32_e32 v6, v2, v144
	v_fma_f32 v3, v3, v5, -v6
	v_add_f32_e32 v3, 0, v3
	ds_read_b128 v[144:147], v74 offset:512
	s_waitcnt lgkmcnt(0)
	v_mul_f32_e32 v5, v2, v144
	v_fma_f32 v4, v4, v8, -v5
	v_fma_f32 v5, -v145, v3, 0
	v_add_f32_e32 v4, v4, v5
	ds_read_b128 v[144:147], v74 offset:768
	s_waitcnt lgkmcnt(0)
	v_mul_f32_e32 v5, v2, v144
	v_fma_f32 v5, v7, v10, -v5
	v_fma_f32 v6, -v3, v145, 0
	v_fma_f32 v5, -v146, v4, v5
	v_add_f32_e32 v5, v6, v5
	ds_read_b128 v[144:147], v74 offset:1024
	s_waitcnt lgkmcnt(0)
	v_mul_f32_e32 v6, v2, v144
	v_fma_f32 v160, v9, v12, -v6
	v_fma_f32 v161, -v3, v145, 0
	v_pk_fma_f32 v[160:161], v[146:147], v[4:5], v[160:161] neg_lo:[1,0,0] neg_hi:[1,0,0]
	v_add_f32_e32 v6, v160, v161
	ds_read_b128 v[144:147], v74 offset:1280
	ds_read_b128 v[148:151], v74 offset:1296
	s_waitcnt lgkmcnt(1)
	v_mul_f32_e32 v7, v2, v144
	v_fma_f32 v160, v11, v15, -v7
	v_fma_f32 v161, -v3, v145, 0
	v_pk_fma_f32 v[160:161], v[146:147], v[4:5], v[160:161] neg_lo:[1,0,0] neg_hi:[1,0,0]
	s_waitcnt lgkmcnt(0)
	v_fma_f32 v160, -v6, v148, v160
	v_add_f32_e32 v7, v160, v161
	ds_read_b128 v[8:11], v74 offset:1536
	ds_read_b128 v[144:147], v74 offset:1552
	s_waitcnt lgkmcnt(1)
	v_mul_f32_e32 v8, v2, v8
	v_fma_f32 v160, v13, v17, -v8
	v_fma_f32 v161, -v3, v9, 0
	v_pk_fma_f32 v[160:161], v[10:11], v[4:5], v[160:161] neg_lo:[1,0,0] neg_hi:[1,0,0]
	s_waitcnt lgkmcnt(0)
	v_pk_fma_f32 v[160:161], v[144:145], v[6:7], v[160:161] neg_lo:[1,0,0] neg_hi:[1,0,0]
	v_add_f32_e32 v8, v160, v161
	ds_read_b128 v[10:13], v74 offset:1792
	ds_read_b128 v[144:147], v74 offset:1808
	s_waitcnt lgkmcnt(1)
	v_mul_f32_e32 v9, v2, v10
	v_fma_f32 v160, v14, v123, -v9
	v_fma_f32 v161, -v3, v11, 0
	v_pk_fma_f32 v[160:161], v[12:13], v[4:5], v[160:161] neg_lo:[1,0,0] neg_hi:[1,0,0]
	s_waitcnt lgkmcnt(0)
	v_pk_fma_f32 v[160:161], v[144:145], v[6:7], v[160:161] neg_lo:[1,0,0] neg_hi:[1,0,0]
	v_fma_f32 v160, -v8, v146, v160
	v_add_f32_e32 v9, v160, v161
	ds_read_b128 v[10:13], v74 offset:2048
	ds_read_b128 v[144:147], v74 offset:2064
	s_waitcnt lgkmcnt(1)
	v_mul_f32_e32 v10, v2, v10
	v_fma_f32 v160, v16, v129, -v10
	v_fma_f32 v161, -v3, v11, 0
	v_pk_fma_f32 v[160:161], v[12:13], v[4:5], v[160:161] neg_lo:[1,0,0] neg_hi:[1,0,0]
	s_waitcnt lgkmcnt(0)
	v_pk_fma_f32 v[160:161], v[144:145], v[6:7], v[160:161] neg_lo:[1,0,0] neg_hi:[1,0,0]
	v_pk_fma_f32 v[160:161], v[146:147], v[8:9], v[160:161] neg_lo:[1,0,0] neg_hi:[1,0,0]
	v_add_f32_e32 v10, v160, v161
	ds_read_b128 v[12:15], v74 offset:2304
	ds_read_b128 v[144:147], v74 offset:2320
	ds_read_b128 v[148:151], v74 offset:2336
	s_waitcnt lgkmcnt(2)
	v_mul_f32_e32 v11, v2, v12
	v_fma_f32 v160, v18, v136, -v11
	v_fma_f32 v161, -v3, v13, 0
	v_pk_fma_f32 v[160:161], v[14:15], v[4:5], v[160:161] neg_lo:[1,0,0] neg_hi:[1,0,0]
	s_waitcnt lgkmcnt(1)
	v_pk_fma_f32 v[160:161], v[144:145], v[6:7], v[160:161] neg_lo:[1,0,0] neg_hi:[1,0,0]
	v_pk_fma_f32 v[160:161], v[146:147], v[8:9], v[160:161] neg_lo:[1,0,0] neg_hi:[1,0,0]
	s_waitcnt lgkmcnt(0)
	v_fma_f32 v160, -v10, v148, v160
	v_add_f32_e32 v11, v160, v161
	ds_read_b128 v[12:15], v74 offset:2560
	ds_read_b128 v[144:147], v74 offset:2576
	ds_read_b128 v[148:151], v74 offset:2592
	s_waitcnt lgkmcnt(2)
	v_mul_f32_e32 v12, v2, v12
	v_fma_f32 v160, v121, v138, -v12
	v_fma_f32 v161, -v3, v13, 0
	v_pk_fma_f32 v[160:161], v[14:15], v[4:5], v[160:161] neg_lo:[1,0,0] neg_hi:[1,0,0]
	s_waitcnt lgkmcnt(1)
	v_pk_fma_f32 v[160:161], v[144:145], v[6:7], v[160:161] neg_lo:[1,0,0] neg_hi:[1,0,0]
	v_pk_fma_f32 v[160:161], v[146:147], v[8:9], v[160:161] neg_lo:[1,0,0] neg_hi:[1,0,0]
	s_waitcnt lgkmcnt(0)
	v_pk_fma_f32 v[160:161], v[148:149], v[10:11], v[160:161] neg_lo:[1,0,0] neg_hi:[1,0,0]
	v_add_f32_e32 v12, v160, v161
	ds_read_b128 v[14:17], v74 offset:2816
	ds_read_b128 v[144:147], v74 offset:2832
	ds_read_b128 v[148:151], v74 offset:2848
	s_waitcnt lgkmcnt(2)
	v_mul_f32_e32 v13, v2, v14
	v_fma_f32 v160, v124, v140, -v13
	v_fma_f32 v161, -v3, v15, 0
	v_pk_fma_f32 v[160:161], v[16:17], v[4:5], v[160:161] neg_lo:[1,0,0] neg_hi:[1,0,0]
	s_waitcnt lgkmcnt(1)
	v_pk_fma_f32 v[160:161], v[144:145], v[6:7], v[160:161] neg_lo:[1,0,0] neg_hi:[1,0,0]
	v_pk_fma_f32 v[160:161], v[146:147], v[8:9], v[160:161] neg_lo:[1,0,0] neg_hi:[1,0,0]
	s_waitcnt lgkmcnt(0)
	v_pk_fma_f32 v[160:161], v[148:149], v[10:11], v[160:161] neg_lo:[1,0,0] neg_hi:[1,0,0]
	v_fma_f32 v160, -v12, v150, v160
	v_add_f32_e32 v13, v160, v161
	ds_read_b128 v[14:17], v74 offset:3072
	ds_read_b128 v[144:147], v74 offset:3088
	ds_read_b128 v[148:151], v74 offset:3104
	s_waitcnt lgkmcnt(2)
	v_mul_f32_e32 v14, v2, v14
	v_fma_f32 v160, v126, v142, -v14
	v_fma_f32 v161, -v3, v15, 0
	v_pk_fma_f32 v[160:161], v[16:17], v[4:5], v[160:161] neg_lo:[1,0,0] neg_hi:[1,0,0]
	s_waitcnt lgkmcnt(1)
	v_pk_fma_f32 v[160:161], v[144:145], v[6:7], v[160:161] neg_lo:[1,0,0] neg_hi:[1,0,0]
	v_pk_fma_f32 v[160:161], v[146:147], v[8:9], v[160:161] neg_lo:[1,0,0] neg_hi:[1,0,0]
	s_waitcnt lgkmcnt(0)
	v_pk_fma_f32 v[160:161], v[148:149], v[10:11], v[160:161] neg_lo:[1,0,0] neg_hi:[1,0,0]
	v_pk_fma_f32 v[160:161], v[150:151], v[12:13], v[160:161] neg_lo:[1,0,0] neg_hi:[1,0,0]
	v_add_f32_e32 v14, v160, v161
	ds_read_b128 v[144:147], v74 offset:3328
	ds_read_b128 v[148:151], v74 offset:3344
	ds_read_b128 v[152:155], v74 offset:3360
	ds_read_b128 v[156:159], v74 offset:3376
	s_waitcnt lgkmcnt(3)
	v_mul_f32_e32 v15, v2, v144
	v_fma_f32 v160, v127, v143, -v15
	v_fma_f32 v161, -v3, v145, 0
	v_pk_fma_f32 v[160:161], v[146:147], v[4:5], v[160:161] neg_lo:[1,0,0] neg_hi:[1,0,0]
	s_waitcnt lgkmcnt(2)
	v_pk_fma_f32 v[160:161], v[148:149], v[6:7], v[160:161] neg_lo:[1,0,0] neg_hi:[1,0,0]
	v_pk_fma_f32 v[160:161], v[150:151], v[8:9], v[160:161] neg_lo:[1,0,0] neg_hi:[1,0,0]
	s_waitcnt lgkmcnt(1)
	v_pk_fma_f32 v[160:161], v[152:153], v[10:11], v[160:161] neg_lo:[1,0,0] neg_hi:[1,0,0]
	v_pk_fma_f32 v[160:161], v[154:155], v[12:13], v[160:161] neg_lo:[1,0,0] neg_hi:[1,0,0]
	s_waitcnt lgkmcnt(0)
	v_fma_f32 v160, -v14, v156, v160
	v_add_f32_e32 v15, v160, v161
	ds_read_b128 v[142:145], v74 offset:3584
	ds_read_b128 v[146:149], v74 offset:3600
	ds_read_b128 v[150:153], v74 offset:3616
	ds_read_b128 v[154:157], v74 offset:3632
	s_waitcnt lgkmcnt(3)
	v_mul_f32_e32 v16, v2, v142
	v_fma_f32 v160, v125, v141, -v16
	v_fma_f32 v161, -v3, v143, 0
	v_pk_fma_f32 v[160:161], v[144:145], v[4:5], v[160:161] neg_lo:[1,0,0] neg_hi:[1,0,0]
	s_waitcnt lgkmcnt(2)
	v_pk_fma_f32 v[160:161], v[146:147], v[6:7], v[160:161] neg_lo:[1,0,0] neg_hi:[1,0,0]
	v_pk_fma_f32 v[160:161], v[148:149], v[8:9], v[160:161] neg_lo:[1,0,0] neg_hi:[1,0,0]
	s_waitcnt lgkmcnt(1)
	v_pk_fma_f32 v[160:161], v[150:151], v[10:11], v[160:161] neg_lo:[1,0,0] neg_hi:[1,0,0]
	v_pk_fma_f32 v[160:161], v[152:153], v[12:13], v[160:161] neg_lo:[1,0,0] neg_hi:[1,0,0]
	s_waitcnt lgkmcnt(0)
	v_pk_fma_f32 v[160:161], v[154:155], v[14:15], v[160:161] neg_lo:[1,0,0] neg_hi:[1,0,0]
	v_add_f32_e32 v16, v160, v161
	ds_read_b128 v[124:127], v74 offset:3840
	ds_read_b128 v[140:143], v74 offset:3856
	ds_read_b128 v[144:147], v74 offset:3872
	ds_read_b128 v[148:151], v74 offset:3888
	s_waitcnt lgkmcnt(3)
	v_mul_f32_e32 v17, v2, v124
	v_fma_f32 v160, v122, v139, -v17
	v_fma_f32 v161, -v3, v125, 0
	v_pk_fma_f32 v[160:161], v[126:127], v[4:5], v[160:161] neg_lo:[1,0,0] neg_hi:[1,0,0]
	s_waitcnt lgkmcnt(2)
	v_pk_fma_f32 v[160:161], v[140:141], v[6:7], v[160:161] neg_lo:[1,0,0] neg_hi:[1,0,0]
	v_pk_fma_f32 v[160:161], v[142:143], v[8:9], v[160:161] neg_lo:[1,0,0] neg_hi:[1,0,0]
	s_waitcnt lgkmcnt(1)
	v_pk_fma_f32 v[160:161], v[144:145], v[10:11], v[160:161] neg_lo:[1,0,0] neg_hi:[1,0,0]
	v_pk_fma_f32 v[160:161], v[146:147], v[12:13], v[160:161] neg_lo:[1,0,0] neg_hi:[1,0,0]
	s_waitcnt lgkmcnt(0)
	v_pk_fma_f32 v[160:161], v[148:149], v[14:15], v[160:161] neg_lo:[1,0,0] neg_hi:[1,0,0]
	v_fma_f32 v160, -v16, v150, v160
	v_add_f32_e32 v17, v160, v161
	ds_read_b128 v[122:125], v74 offset:4096
	ds_read_b128 v[138:141], v74 offset:4112
	ds_read_b128 v[142:145], v74 offset:4128
	ds_read_b128 v[146:149], v74 offset:4144
	s_waitcnt lgkmcnt(3)
	v_mul_f32_e32 v18, v2, v122
	v_fma_f32 v160, v119, v137, -v18
	v_fma_f32 v161, -v3, v123, 0
	v_pk_fma_f32 v[160:161], v[124:125], v[4:5], v[160:161] neg_lo:[1,0,0] neg_hi:[1,0,0]
	s_waitcnt lgkmcnt(2)
	v_pk_fma_f32 v[160:161], v[138:139], v[6:7], v[160:161] neg_lo:[1,0,0] neg_hi:[1,0,0]
	v_pk_fma_f32 v[160:161], v[140:141], v[8:9], v[160:161] neg_lo:[1,0,0] neg_hi:[1,0,0]
	s_waitcnt lgkmcnt(1)
	v_pk_fma_f32 v[160:161], v[142:143], v[10:11], v[160:161] neg_lo:[1,0,0] neg_hi:[1,0,0]
	v_pk_fma_f32 v[160:161], v[144:145], v[12:13], v[160:161] neg_lo:[1,0,0] neg_hi:[1,0,0]
	s_waitcnt lgkmcnt(0)
	v_pk_fma_f32 v[160:161], v[146:147], v[14:15], v[160:161] neg_lo:[1,0,0] neg_hi:[1,0,0]
	v_pk_fma_f32 v[160:161], v[148:149], v[16:17], v[160:161] neg_lo:[1,0,0] neg_hi:[1,0,0]
	v_add_f32_e32 v18, v160, v161
	ds_read_b128 v[122:125], v74 offset:4352
	ds_read_b128 v[136:139], v74 offset:4368
	ds_read_b128 v[140:143], v74 offset:4384
	ds_read_b128 v[144:147], v74 offset:4400
	ds_read_b128 v[148:151], v74 offset:4416
	s_waitcnt lgkmcnt(4)
	v_mul_f32_e32 v27, v2, v122
	v_fma_f32 v160, v19, v134, -v27
	v_fma_f32 v161, -v3, v123, 0
	v_pk_fma_f32 v[160:161], v[124:125], v[4:5], v[160:161] neg_lo:[1,0,0] neg_hi:[1,0,0]
	s_waitcnt lgkmcnt(3)
	v_pk_fma_f32 v[160:161], v[136:137], v[6:7], v[160:161] neg_lo:[1,0,0] neg_hi:[1,0,0]
	v_pk_fma_f32 v[160:161], v[138:139], v[8:9], v[160:161] neg_lo:[1,0,0] neg_hi:[1,0,0]
	s_waitcnt lgkmcnt(2)
	v_pk_fma_f32 v[160:161], v[140:141], v[10:11], v[160:161] neg_lo:[1,0,0] neg_hi:[1,0,0]
	v_pk_fma_f32 v[160:161], v[142:143], v[12:13], v[160:161] neg_lo:[1,0,0] neg_hi:[1,0,0]
	s_waitcnt lgkmcnt(1)
	v_pk_fma_f32 v[160:161], v[144:145], v[14:15], v[160:161] neg_lo:[1,0,0] neg_hi:[1,0,0]
	v_pk_fma_f32 v[160:161], v[146:147], v[16:17], v[160:161] neg_lo:[1,0,0] neg_hi:[1,0,0]
	s_waitcnt lgkmcnt(0)
	v_fma_f32 v160, -v18, v148, v160
	v_add_f32_e32 v19, v160, v161
	ds_read_b128 v[122:125], v74 offset:4608
	ds_read_b128 v[134:137], v74 offset:4624
	ds_read_b128 v[138:141], v74 offset:4640
	ds_read_b128 v[142:145], v74 offset:4656
	ds_read_b128 v[146:149], v74 offset:4672
	s_waitcnt lgkmcnt(4)
	v_mul_f32_e32 v27, v2, v122
	v_fma_f32 v160, v20, v128, -v27
	v_fma_f32 v161, -v3, v123, 0
	v_pk_fma_f32 v[160:161], v[124:125], v[4:5], v[160:161] neg_lo:[1,0,0] neg_hi:[1,0,0]
	s_waitcnt lgkmcnt(3)
	v_pk_fma_f32 v[160:161], v[134:135], v[6:7], v[160:161] neg_lo:[1,0,0] neg_hi:[1,0,0]
	v_pk_fma_f32 v[160:161], v[136:137], v[8:9], v[160:161] neg_lo:[1,0,0] neg_hi:[1,0,0]
	s_waitcnt lgkmcnt(2)
	v_pk_fma_f32 v[160:161], v[138:139], v[10:11], v[160:161] neg_lo:[1,0,0] neg_hi:[1,0,0]
	v_pk_fma_f32 v[160:161], v[140:141], v[12:13], v[160:161] neg_lo:[1,0,0] neg_hi:[1,0,0]
	s_waitcnt lgkmcnt(1)
	v_pk_fma_f32 v[160:161], v[142:143], v[14:15], v[160:161] neg_lo:[1,0,0] neg_hi:[1,0,0]
	v_pk_fma_f32 v[160:161], v[144:145], v[16:17], v[160:161] neg_lo:[1,0,0] neg_hi:[1,0,0]
	s_waitcnt lgkmcnt(0)
	v_pk_fma_f32 v[160:161], v[146:147], v[18:19], v[160:161] neg_lo:[1,0,0] neg_hi:[1,0,0]
	v_add_f32_e32 v20, v160, v161
	ds_read_b128 v[122:125], v74 offset:4864
	ds_read_b128 v[126:129], v74 offset:4880
	ds_read_b128 v[134:137], v74 offset:4896
	ds_read_b128 v[138:141], v74 offset:4912
	ds_read_b128 v[142:145], v74 offset:4928
	s_waitcnt lgkmcnt(4)
	v_mul_f32_e32 v27, v2, v122
	v_fma_f32 v160, v21, v120, -v27
	v_fma_f32 v161, -v3, v123, 0
	v_pk_fma_f32 v[160:161], v[124:125], v[4:5], v[160:161] neg_lo:[1,0,0] neg_hi:[1,0,0]
	s_waitcnt lgkmcnt(3)
	v_pk_fma_f32 v[160:161], v[126:127], v[6:7], v[160:161] neg_lo:[1,0,0] neg_hi:[1,0,0]
	v_pk_fma_f32 v[160:161], v[128:129], v[8:9], v[160:161] neg_lo:[1,0,0] neg_hi:[1,0,0]
	s_waitcnt lgkmcnt(2)
	v_pk_fma_f32 v[160:161], v[134:135], v[10:11], v[160:161] neg_lo:[1,0,0] neg_hi:[1,0,0]
	v_pk_fma_f32 v[160:161], v[136:137], v[12:13], v[160:161] neg_lo:[1,0,0] neg_hi:[1,0,0]
	s_waitcnt lgkmcnt(1)
	v_pk_fma_f32 v[160:161], v[138:139], v[14:15], v[160:161] neg_lo:[1,0,0] neg_hi:[1,0,0]
	v_pk_fma_f32 v[160:161], v[140:141], v[16:17], v[160:161] neg_lo:[1,0,0] neg_hi:[1,0,0]
	s_waitcnt lgkmcnt(0)
	v_pk_fma_f32 v[160:161], v[142:143], v[18:19], v[160:161] neg_lo:[1,0,0] neg_hi:[1,0,0]
	v_fma_f32 v160, -v20, v144, v160
	v_add_f32_e32 v21, v160, v161
	ds_read_b128 v[120:123], v74 offset:5120
	ds_read_b128 v[124:127], v74 offset:5136
	ds_read_b128 v[134:137], v74 offset:5152
	ds_read_b128 v[138:141], v74 offset:5168
	ds_read_b128 v[142:145], v74 offset:5184
	s_waitcnt lgkmcnt(4)
	v_mul_f32_e32 v27, v2, v120
	v_fma_f32 v160, v22, v118, -v27
	v_fma_f32 v161, -v3, v121, 0
	v_pk_fma_f32 v[160:161], v[122:123], v[4:5], v[160:161] neg_lo:[1,0,0] neg_hi:[1,0,0]
	s_waitcnt lgkmcnt(3)
	v_pk_fma_f32 v[160:161], v[124:125], v[6:7], v[160:161] neg_lo:[1,0,0] neg_hi:[1,0,0]
	v_pk_fma_f32 v[160:161], v[126:127], v[8:9], v[160:161] neg_lo:[1,0,0] neg_hi:[1,0,0]
	s_waitcnt lgkmcnt(2)
	v_pk_fma_f32 v[160:161], v[134:135], v[10:11], v[160:161] neg_lo:[1,0,0] neg_hi:[1,0,0]
	v_pk_fma_f32 v[160:161], v[136:137], v[12:13], v[160:161] neg_lo:[1,0,0] neg_hi:[1,0,0]
	s_waitcnt lgkmcnt(1)
	v_pk_fma_f32 v[160:161], v[138:139], v[14:15], v[160:161] neg_lo:[1,0,0] neg_hi:[1,0,0]
	v_pk_fma_f32 v[160:161], v[140:141], v[16:17], v[160:161] neg_lo:[1,0,0] neg_hi:[1,0,0]
	s_waitcnt lgkmcnt(0)
	v_pk_fma_f32 v[160:161], v[142:143], v[18:19], v[160:161] neg_lo:[1,0,0] neg_hi:[1,0,0]
	v_pk_fma_f32 v[160:161], v[144:145], v[20:21], v[160:161] neg_lo:[1,0,0] neg_hi:[1,0,0]
	v_add_f32_e32 v22, v160, v161
	ds_read_b128 v[118:121], v74 offset:5376
	ds_read_b128 v[122:125], v74 offset:5392
	ds_read_b128 v[126:129], v74 offset:5408
	ds_read_b128 v[134:137], v74 offset:5424
	ds_read_b128 v[138:141], v74 offset:5440
	ds_read_b128 v[142:145], v74 offset:5456
	s_waitcnt lgkmcnt(5)
	v_mul_f32_e32 v27, v2, v118
	v_fma_f32 v160, v23, v117, -v27
	v_fma_f32 v161, -v3, v119, 0
	v_pk_fma_f32 v[160:161], v[120:121], v[4:5], v[160:161] neg_lo:[1,0,0] neg_hi:[1,0,0]
	s_waitcnt lgkmcnt(4)
	v_pk_fma_f32 v[160:161], v[122:123], v[6:7], v[160:161] neg_lo:[1,0,0] neg_hi:[1,0,0]
	v_pk_fma_f32 v[160:161], v[124:125], v[8:9], v[160:161] neg_lo:[1,0,0] neg_hi:[1,0,0]
	s_waitcnt lgkmcnt(3)
	v_pk_fma_f32 v[160:161], v[126:127], v[10:11], v[160:161] neg_lo:[1,0,0] neg_hi:[1,0,0]
	v_pk_fma_f32 v[160:161], v[128:129], v[12:13], v[160:161] neg_lo:[1,0,0] neg_hi:[1,0,0]
	s_waitcnt lgkmcnt(2)
	v_pk_fma_f32 v[160:161], v[134:135], v[14:15], v[160:161] neg_lo:[1,0,0] neg_hi:[1,0,0]
	v_pk_fma_f32 v[160:161], v[136:137], v[16:17], v[160:161] neg_lo:[1,0,0] neg_hi:[1,0,0]
	s_waitcnt lgkmcnt(1)
	v_pk_fma_f32 v[160:161], v[138:139], v[18:19], v[160:161] neg_lo:[1,0,0] neg_hi:[1,0,0]
	v_pk_fma_f32 v[160:161], v[140:141], v[20:21], v[160:161] neg_lo:[1,0,0] neg_hi:[1,0,0]
	s_waitcnt lgkmcnt(0)
	v_fma_f32 v160, -v22, v142, v160
	v_add_f32_e32 v23, v160, v161
	ds_read_b128 v[118:121], v74 offset:5632
	ds_read_b128 v[122:125], v74 offset:5648
	ds_read_b128 v[126:129], v74 offset:5664
	ds_read_b128 v[134:137], v74 offset:5680
	ds_read_b128 v[138:141], v74 offset:5696
	ds_read_b128 v[142:145], v74 offset:5712
	s_waitcnt lgkmcnt(5)
	v_mul_f32_e32 v27, v2, v118
	v_fma_f32 v160, v24, v116, -v27
	v_fma_f32 v161, -v3, v119, 0
	v_pk_fma_f32 v[160:161], v[120:121], v[4:5], v[160:161] neg_lo:[1,0,0] neg_hi:[1,0,0]
	s_waitcnt lgkmcnt(4)
	v_pk_fma_f32 v[160:161], v[122:123], v[6:7], v[160:161] neg_lo:[1,0,0] neg_hi:[1,0,0]
	v_pk_fma_f32 v[160:161], v[124:125], v[8:9], v[160:161] neg_lo:[1,0,0] neg_hi:[1,0,0]
	s_waitcnt lgkmcnt(3)
	v_pk_fma_f32 v[160:161], v[126:127], v[10:11], v[160:161] neg_lo:[1,0,0] neg_hi:[1,0,0]
	v_pk_fma_f32 v[160:161], v[128:129], v[12:13], v[160:161] neg_lo:[1,0,0] neg_hi:[1,0,0]
	s_waitcnt lgkmcnt(2)
	v_pk_fma_f32 v[160:161], v[134:135], v[14:15], v[160:161] neg_lo:[1,0,0] neg_hi:[1,0,0]
	v_pk_fma_f32 v[160:161], v[136:137], v[16:17], v[160:161] neg_lo:[1,0,0] neg_hi:[1,0,0]
	s_waitcnt lgkmcnt(1)
	v_pk_fma_f32 v[160:161], v[138:139], v[18:19], v[160:161] neg_lo:[1,0,0] neg_hi:[1,0,0]
	v_pk_fma_f32 v[160:161], v[140:141], v[20:21], v[160:161] neg_lo:[1,0,0] neg_hi:[1,0,0]
	s_waitcnt lgkmcnt(0)
	v_pk_fma_f32 v[160:161], v[142:143], v[22:23], v[160:161] neg_lo:[1,0,0] neg_hi:[1,0,0]
	v_add_f32_e32 v24, v160, v161
	ds_read_b128 v[116:119], v74 offset:5888
	ds_read_b128 v[120:123], v74 offset:5904
	ds_read_b128 v[124:127], v74 offset:5920
	ds_read_b128 v[134:137], v74 offset:5936
	ds_read_b128 v[138:141], v74 offset:5952
	ds_read_b128 v[142:145], v74 offset:5968
	s_waitcnt lgkmcnt(5)
	v_mul_f32_e32 v27, v2, v116
	v_fma_f32 v160, v25, v115, -v27
	v_fma_f32 v161, -v3, v117, 0
	v_pk_fma_f32 v[160:161], v[118:119], v[4:5], v[160:161] neg_lo:[1,0,0] neg_hi:[1,0,0]
	s_waitcnt lgkmcnt(4)
	v_pk_fma_f32 v[160:161], v[120:121], v[6:7], v[160:161] neg_lo:[1,0,0] neg_hi:[1,0,0]
	v_pk_fma_f32 v[160:161], v[122:123], v[8:9], v[160:161] neg_lo:[1,0,0] neg_hi:[1,0,0]
	s_waitcnt lgkmcnt(3)
	v_pk_fma_f32 v[160:161], v[124:125], v[10:11], v[160:161] neg_lo:[1,0,0] neg_hi:[1,0,0]
	v_pk_fma_f32 v[160:161], v[126:127], v[12:13], v[160:161] neg_lo:[1,0,0] neg_hi:[1,0,0]
	s_waitcnt lgkmcnt(2)
	v_pk_fma_f32 v[160:161], v[134:135], v[14:15], v[160:161] neg_lo:[1,0,0] neg_hi:[1,0,0]
	v_pk_fma_f32 v[160:161], v[136:137], v[16:17], v[160:161] neg_lo:[1,0,0] neg_hi:[1,0,0]
	s_waitcnt lgkmcnt(1)
	v_pk_fma_f32 v[160:161], v[138:139], v[18:19], v[160:161] neg_lo:[1,0,0] neg_hi:[1,0,0]
	v_pk_fma_f32 v[160:161], v[140:141], v[20:21], v[160:161] neg_lo:[1,0,0] neg_hi:[1,0,0]
	s_waitcnt lgkmcnt(0)
	v_pk_fma_f32 v[160:161], v[142:143], v[22:23], v[160:161] neg_lo:[1,0,0] neg_hi:[1,0,0]
	v_fma_f32 v160, -v24, v144, v160
	v_add_f32_e32 v25, v160, v161
	ds_read_b128 v[116:119], v74 offset:6144
	ds_read_b128 v[120:123], v74 offset:6160
	ds_read_b128 v[124:127], v74 offset:6176
	ds_read_b128 v[134:137], v74 offset:6192
	ds_read_b128 v[138:141], v74 offset:6208
	ds_read_b128 v[142:145], v74 offset:6224
	s_waitcnt lgkmcnt(5)
	v_mul_f32_e32 v27, v2, v116
	v_fma_f32 v160, v26, v114, -v27
	v_fma_f32 v161, -v3, v117, 0
	v_pk_fma_f32 v[160:161], v[118:119], v[4:5], v[160:161] neg_lo:[1,0,0] neg_hi:[1,0,0]
	s_waitcnt lgkmcnt(4)
	v_pk_fma_f32 v[160:161], v[120:121], v[6:7], v[160:161] neg_lo:[1,0,0] neg_hi:[1,0,0]
	v_pk_fma_f32 v[160:161], v[122:123], v[8:9], v[160:161] neg_lo:[1,0,0] neg_hi:[1,0,0]
	s_waitcnt lgkmcnt(3)
	v_pk_fma_f32 v[160:161], v[124:125], v[10:11], v[160:161] neg_lo:[1,0,0] neg_hi:[1,0,0]
	v_pk_fma_f32 v[160:161], v[126:127], v[12:13], v[160:161] neg_lo:[1,0,0] neg_hi:[1,0,0]
	s_waitcnt lgkmcnt(2)
	v_pk_fma_f32 v[160:161], v[134:135], v[14:15], v[160:161] neg_lo:[1,0,0] neg_hi:[1,0,0]
	v_pk_fma_f32 v[160:161], v[136:137], v[16:17], v[160:161] neg_lo:[1,0,0] neg_hi:[1,0,0]
	s_waitcnt lgkmcnt(1)
	v_pk_fma_f32 v[160:161], v[138:139], v[18:19], v[160:161] neg_lo:[1,0,0] neg_hi:[1,0,0]
	v_pk_fma_f32 v[160:161], v[140:141], v[20:21], v[160:161] neg_lo:[1,0,0] neg_hi:[1,0,0]
	s_waitcnt lgkmcnt(0)
	v_pk_fma_f32 v[160:161], v[142:143], v[22:23], v[160:161] neg_lo:[1,0,0] neg_hi:[1,0,0]
	v_pk_fma_f32 v[160:161], v[144:145], v[24:25], v[160:161] neg_lo:[1,0,0] neg_hi:[1,0,0]
	v_add_f32_e32 v26, v160, v161
	ds_read_b128 v[114:117], v74 offset:6400
	ds_read_b128 v[118:121], v74 offset:6416
	ds_read_b128 v[122:125], v74 offset:6432
	ds_read_b128 v[126:129], v74 offset:6448
	ds_read_b128 v[134:137], v74 offset:6464
	ds_read_b128 v[138:141], v74 offset:6480
	ds_read_b128 v[142:145], v74 offset:6496
	s_waitcnt lgkmcnt(6)
	v_mul_f32_e32 v27, v2, v114
	v_fma_f32 v160, v111, v113, -v27
	v_fma_f32 v161, -v3, v115, 0
	v_pk_fma_f32 v[160:161], v[116:117], v[4:5], v[160:161] neg_lo:[1,0,0] neg_hi:[1,0,0]
	s_waitcnt lgkmcnt(5)
	v_pk_fma_f32 v[160:161], v[118:119], v[6:7], v[160:161] neg_lo:[1,0,0] neg_hi:[1,0,0]
	v_pk_fma_f32 v[160:161], v[120:121], v[8:9], v[160:161] neg_lo:[1,0,0] neg_hi:[1,0,0]
	s_waitcnt lgkmcnt(4)
	v_pk_fma_f32 v[160:161], v[122:123], v[10:11], v[160:161] neg_lo:[1,0,0] neg_hi:[1,0,0]
	v_pk_fma_f32 v[160:161], v[124:125], v[12:13], v[160:161] neg_lo:[1,0,0] neg_hi:[1,0,0]
	s_waitcnt lgkmcnt(3)
	v_pk_fma_f32 v[160:161], v[126:127], v[14:15], v[160:161] neg_lo:[1,0,0] neg_hi:[1,0,0]
	v_pk_fma_f32 v[160:161], v[128:129], v[16:17], v[160:161] neg_lo:[1,0,0] neg_hi:[1,0,0]
	s_waitcnt lgkmcnt(2)
	v_pk_fma_f32 v[160:161], v[134:135], v[18:19], v[160:161] neg_lo:[1,0,0] neg_hi:[1,0,0]
	v_pk_fma_f32 v[160:161], v[136:137], v[20:21], v[160:161] neg_lo:[1,0,0] neg_hi:[1,0,0]
	s_waitcnt lgkmcnt(1)
	v_pk_fma_f32 v[160:161], v[138:139], v[22:23], v[160:161] neg_lo:[1,0,0] neg_hi:[1,0,0]
	v_pk_fma_f32 v[160:161], v[140:141], v[24:25], v[160:161] neg_lo:[1,0,0] neg_hi:[1,0,0]
	s_waitcnt lgkmcnt(0)
	v_fma_f32 v160, -v26, v142, v160
	v_add_f32_e32 v27, v160, v161
	ds_read_b128 v[114:117], v74 offset:6656
	ds_read_b128 v[118:121], v74 offset:6672
	ds_read_b128 v[122:125], v74 offset:6688
	ds_read_b128 v[126:129], v74 offset:6704
	ds_read_b128 v[134:137], v74 offset:6720
	ds_read_b128 v[138:141], v74 offset:6736
	ds_read_b128 v[142:145], v74 offset:6752
	s_waitcnt lgkmcnt(6)
	v_mul_f32_e32 v111, v2, v114
	v_fma_f32 v160, v28, v112, -v111
	v_fma_f32 v161, -v3, v115, 0
	v_pk_fma_f32 v[160:161], v[116:117], v[4:5], v[160:161] neg_lo:[1,0,0] neg_hi:[1,0,0]
	s_waitcnt lgkmcnt(5)
	v_pk_fma_f32 v[160:161], v[118:119], v[6:7], v[160:161] neg_lo:[1,0,0] neg_hi:[1,0,0]
	v_pk_fma_f32 v[160:161], v[120:121], v[8:9], v[160:161] neg_lo:[1,0,0] neg_hi:[1,0,0]
	s_waitcnt lgkmcnt(4)
	v_pk_fma_f32 v[160:161], v[122:123], v[10:11], v[160:161] neg_lo:[1,0,0] neg_hi:[1,0,0]
	v_pk_fma_f32 v[160:161], v[124:125], v[12:13], v[160:161] neg_lo:[1,0,0] neg_hi:[1,0,0]
	s_waitcnt lgkmcnt(3)
	v_pk_fma_f32 v[160:161], v[126:127], v[14:15], v[160:161] neg_lo:[1,0,0] neg_hi:[1,0,0]
	v_pk_fma_f32 v[160:161], v[128:129], v[16:17], v[160:161] neg_lo:[1,0,0] neg_hi:[1,0,0]
	s_waitcnt lgkmcnt(2)
	v_pk_fma_f32 v[160:161], v[134:135], v[18:19], v[160:161] neg_lo:[1,0,0] neg_hi:[1,0,0]
	v_pk_fma_f32 v[160:161], v[136:137], v[20:21], v[160:161] neg_lo:[1,0,0] neg_hi:[1,0,0]
	s_waitcnt lgkmcnt(1)
	v_pk_fma_f32 v[160:161], v[138:139], v[22:23], v[160:161] neg_lo:[1,0,0] neg_hi:[1,0,0]
	v_pk_fma_f32 v[160:161], v[140:141], v[24:25], v[160:161] neg_lo:[1,0,0] neg_hi:[1,0,0]
	s_waitcnt lgkmcnt(0)
	v_pk_fma_f32 v[160:161], v[142:143], v[26:27], v[160:161] neg_lo:[1,0,0] neg_hi:[1,0,0]
	v_add_f32_e32 v28, v160, v161
	ds_read_b128 v[112:115], v74 offset:6912
	ds_read_b128 v[116:119], v74 offset:6928
	ds_read_b128 v[120:123], v74 offset:6944
	ds_read_b128 v[124:127], v74 offset:6960
	ds_read_b128 v[134:137], v74 offset:6976
	ds_read_b128 v[138:141], v74 offset:6992
	ds_read_b128 v[142:145], v74 offset:7008
	s_waitcnt lgkmcnt(6)
	v_mul_f32_e32 v111, v2, v112
	v_fma_f32 v160, v29, v110, -v111
	v_fma_f32 v161, -v3, v113, 0
	v_pk_fma_f32 v[160:161], v[114:115], v[4:5], v[160:161] neg_lo:[1,0,0] neg_hi:[1,0,0]
	s_waitcnt lgkmcnt(5)
	v_pk_fma_f32 v[160:161], v[116:117], v[6:7], v[160:161] neg_lo:[1,0,0] neg_hi:[1,0,0]
	v_pk_fma_f32 v[160:161], v[118:119], v[8:9], v[160:161] neg_lo:[1,0,0] neg_hi:[1,0,0]
	s_waitcnt lgkmcnt(4)
	v_pk_fma_f32 v[160:161], v[120:121], v[10:11], v[160:161] neg_lo:[1,0,0] neg_hi:[1,0,0]
	v_pk_fma_f32 v[160:161], v[122:123], v[12:13], v[160:161] neg_lo:[1,0,0] neg_hi:[1,0,0]
	s_waitcnt lgkmcnt(3)
	v_pk_fma_f32 v[160:161], v[124:125], v[14:15], v[160:161] neg_lo:[1,0,0] neg_hi:[1,0,0]
	v_pk_fma_f32 v[160:161], v[126:127], v[16:17], v[160:161] neg_lo:[1,0,0] neg_hi:[1,0,0]
	s_waitcnt lgkmcnt(2)
	v_pk_fma_f32 v[160:161], v[134:135], v[18:19], v[160:161] neg_lo:[1,0,0] neg_hi:[1,0,0]
	v_pk_fma_f32 v[160:161], v[136:137], v[20:21], v[160:161] neg_lo:[1,0,0] neg_hi:[1,0,0]
	s_waitcnt lgkmcnt(1)
	v_pk_fma_f32 v[160:161], v[138:139], v[22:23], v[160:161] neg_lo:[1,0,0] neg_hi:[1,0,0]
	v_pk_fma_f32 v[160:161], v[140:141], v[24:25], v[160:161] neg_lo:[1,0,0] neg_hi:[1,0,0]
	s_waitcnt lgkmcnt(0)
	v_pk_fma_f32 v[160:161], v[142:143], v[26:27], v[160:161] neg_lo:[1,0,0] neg_hi:[1,0,0]
	v_fma_f32 v160, -v28, v144, v160
	v_add_f32_e32 v29, v160, v161
	ds_read_b128 v[110:113], v74 offset:7168
	ds_read_b128 v[114:117], v74 offset:7184
	ds_read_b128 v[118:121], v74 offset:7200
	ds_read_b128 v[122:125], v74 offset:7216
	ds_read_b128 v[126:129], v74 offset:7232
	ds_read_b128 v[134:137], v74 offset:7248
	ds_read_b128 v[138:141], v74 offset:7264
	s_waitcnt lgkmcnt(6)
	v_mul_f32_e32 v110, v2, v110
	v_fma_f32 v160, v30, v109, -v110
	v_fma_f32 v161, -v3, v111, 0
	v_pk_fma_f32 v[160:161], v[112:113], v[4:5], v[160:161] neg_lo:[1,0,0] neg_hi:[1,0,0]
	s_waitcnt lgkmcnt(5)
	v_pk_fma_f32 v[160:161], v[114:115], v[6:7], v[160:161] neg_lo:[1,0,0] neg_hi:[1,0,0]
	v_pk_fma_f32 v[160:161], v[116:117], v[8:9], v[160:161] neg_lo:[1,0,0] neg_hi:[1,0,0]
	s_waitcnt lgkmcnt(4)
	v_pk_fma_f32 v[160:161], v[118:119], v[10:11], v[160:161] neg_lo:[1,0,0] neg_hi:[1,0,0]
	v_pk_fma_f32 v[160:161], v[120:121], v[12:13], v[160:161] neg_lo:[1,0,0] neg_hi:[1,0,0]
	s_waitcnt lgkmcnt(3)
	v_pk_fma_f32 v[160:161], v[122:123], v[14:15], v[160:161] neg_lo:[1,0,0] neg_hi:[1,0,0]
	v_pk_fma_f32 v[160:161], v[124:125], v[16:17], v[160:161] neg_lo:[1,0,0] neg_hi:[1,0,0]
	s_waitcnt lgkmcnt(2)
	v_pk_fma_f32 v[160:161], v[126:127], v[18:19], v[160:161] neg_lo:[1,0,0] neg_hi:[1,0,0]
	v_pk_fma_f32 v[160:161], v[128:129], v[20:21], v[160:161] neg_lo:[1,0,0] neg_hi:[1,0,0]
	s_waitcnt lgkmcnt(1)
	v_pk_fma_f32 v[160:161], v[134:135], v[22:23], v[160:161] neg_lo:[1,0,0] neg_hi:[1,0,0]
	v_pk_fma_f32 v[160:161], v[136:137], v[24:25], v[160:161] neg_lo:[1,0,0] neg_hi:[1,0,0]
	s_waitcnt lgkmcnt(0)
	v_pk_fma_f32 v[160:161], v[138:139], v[26:27], v[160:161] neg_lo:[1,0,0] neg_hi:[1,0,0]
	v_pk_fma_f32 v[160:161], v[140:141], v[28:29], v[160:161] neg_lo:[1,0,0] neg_hi:[1,0,0]
	v_add_f32_e32 v30, v160, v161
	ds_read_b128 v[110:113], v74 offset:7424
	ds_read_b128 v[114:117], v74 offset:7440
	ds_read_b128 v[118:121], v74 offset:7456
	ds_read_b128 v[122:125], v74 offset:7472
	ds_read_b128 v[126:129], v74 offset:7488
	ds_read_b128 v[134:137], v74 offset:7504
	ds_read_b128 v[138:141], v74 offset:7520
	ds_read_b128 v[142:145], v74 offset:7536
	s_waitcnt lgkmcnt(7)
	v_mul_f32_e32 v109, v2, v110
	v_fma_f32 v160, v31, v108, -v109
	v_fma_f32 v161, -v3, v111, 0
	v_pk_fma_f32 v[160:161], v[112:113], v[4:5], v[160:161] neg_lo:[1,0,0] neg_hi:[1,0,0]
	s_waitcnt lgkmcnt(6)
	v_pk_fma_f32 v[160:161], v[114:115], v[6:7], v[160:161] neg_lo:[1,0,0] neg_hi:[1,0,0]
	v_pk_fma_f32 v[160:161], v[116:117], v[8:9], v[160:161] neg_lo:[1,0,0] neg_hi:[1,0,0]
	s_waitcnt lgkmcnt(5)
	v_pk_fma_f32 v[160:161], v[118:119], v[10:11], v[160:161] neg_lo:[1,0,0] neg_hi:[1,0,0]
	v_pk_fma_f32 v[160:161], v[120:121], v[12:13], v[160:161] neg_lo:[1,0,0] neg_hi:[1,0,0]
	s_waitcnt lgkmcnt(4)
	v_pk_fma_f32 v[160:161], v[122:123], v[14:15], v[160:161] neg_lo:[1,0,0] neg_hi:[1,0,0]
	v_pk_fma_f32 v[160:161], v[124:125], v[16:17], v[160:161] neg_lo:[1,0,0] neg_hi:[1,0,0]
	s_waitcnt lgkmcnt(3)
	v_pk_fma_f32 v[160:161], v[126:127], v[18:19], v[160:161] neg_lo:[1,0,0] neg_hi:[1,0,0]
	v_pk_fma_f32 v[160:161], v[128:129], v[20:21], v[160:161] neg_lo:[1,0,0] neg_hi:[1,0,0]
	s_waitcnt lgkmcnt(2)
	v_pk_fma_f32 v[160:161], v[134:135], v[22:23], v[160:161] neg_lo:[1,0,0] neg_hi:[1,0,0]
	v_pk_fma_f32 v[160:161], v[136:137], v[24:25], v[160:161] neg_lo:[1,0,0] neg_hi:[1,0,0]
	s_waitcnt lgkmcnt(1)
	v_pk_fma_f32 v[160:161], v[138:139], v[26:27], v[160:161] neg_lo:[1,0,0] neg_hi:[1,0,0]
	v_pk_fma_f32 v[160:161], v[140:141], v[28:29], v[160:161] neg_lo:[1,0,0] neg_hi:[1,0,0]
	s_waitcnt lgkmcnt(0)
	v_fma_f32 v160, -v30, v142, v160
	v_add_f32_e32 v31, v160, v161
	ds_read_b128 v[108:111], v74 offset:7680
	ds_read_b128 v[112:115], v74 offset:7696
	ds_read_b128 v[116:119], v74 offset:7712
	ds_read_b128 v[120:123], v74 offset:7728
	ds_read_b128 v[124:127], v74 offset:7744
	ds_read_b128 v[134:137], v74 offset:7760
	ds_read_b128 v[138:141], v74 offset:7776
	ds_read_b128 v[142:145], v74 offset:7792
	s_waitcnt lgkmcnt(7)
	v_mul_f32_e32 v108, v2, v108
	v_fma_f32 v160, v32, v107, -v108
	v_fma_f32 v161, -v3, v109, 0
	v_pk_fma_f32 v[160:161], v[110:111], v[4:5], v[160:161] neg_lo:[1,0,0] neg_hi:[1,0,0]
	s_waitcnt lgkmcnt(6)
	v_pk_fma_f32 v[160:161], v[112:113], v[6:7], v[160:161] neg_lo:[1,0,0] neg_hi:[1,0,0]
	v_pk_fma_f32 v[160:161], v[114:115], v[8:9], v[160:161] neg_lo:[1,0,0] neg_hi:[1,0,0]
	s_waitcnt lgkmcnt(5)
	v_pk_fma_f32 v[160:161], v[116:117], v[10:11], v[160:161] neg_lo:[1,0,0] neg_hi:[1,0,0]
	v_pk_fma_f32 v[160:161], v[118:119], v[12:13], v[160:161] neg_lo:[1,0,0] neg_hi:[1,0,0]
	s_waitcnt lgkmcnt(4)
	v_pk_fma_f32 v[160:161], v[120:121], v[14:15], v[160:161] neg_lo:[1,0,0] neg_hi:[1,0,0]
	v_pk_fma_f32 v[160:161], v[122:123], v[16:17], v[160:161] neg_lo:[1,0,0] neg_hi:[1,0,0]
	s_waitcnt lgkmcnt(3)
	v_pk_fma_f32 v[160:161], v[124:125], v[18:19], v[160:161] neg_lo:[1,0,0] neg_hi:[1,0,0]
	v_pk_fma_f32 v[160:161], v[126:127], v[20:21], v[160:161] neg_lo:[1,0,0] neg_hi:[1,0,0]
	s_waitcnt lgkmcnt(2)
	v_pk_fma_f32 v[160:161], v[134:135], v[22:23], v[160:161] neg_lo:[1,0,0] neg_hi:[1,0,0]
	v_pk_fma_f32 v[160:161], v[136:137], v[24:25], v[160:161] neg_lo:[1,0,0] neg_hi:[1,0,0]
	s_waitcnt lgkmcnt(1)
	v_pk_fma_f32 v[160:161], v[138:139], v[26:27], v[160:161] neg_lo:[1,0,0] neg_hi:[1,0,0]
	v_pk_fma_f32 v[160:161], v[140:141], v[28:29], v[160:161] neg_lo:[1,0,0] neg_hi:[1,0,0]
	s_waitcnt lgkmcnt(0)
	v_pk_fma_f32 v[160:161], v[142:143], v[30:31], v[160:161] neg_lo:[1,0,0] neg_hi:[1,0,0]
	v_add_f32_e32 v32, v160, v161
	ds_read_b128 v[108:111], v74 offset:7936
	ds_read_b128 v[112:115], v74 offset:7952
	ds_read_b128 v[116:119], v74 offset:7968
	ds_read_b128 v[120:123], v74 offset:7984
	ds_read_b128 v[124:127], v74 offset:8000
	ds_read_b128 v[134:137], v74 offset:8016
	ds_read_b128 v[138:141], v74 offset:8032
	ds_read_b128 v[142:145], v74 offset:8048
	s_waitcnt lgkmcnt(7)
	v_mul_f32_e32 v107, v2, v108
	v_fma_f32 v160, v33, v106, -v107
	v_fma_f32 v161, -v3, v109, 0
	v_pk_fma_f32 v[160:161], v[110:111], v[4:5], v[160:161] neg_lo:[1,0,0] neg_hi:[1,0,0]
	s_waitcnt lgkmcnt(6)
	v_pk_fma_f32 v[160:161], v[112:113], v[6:7], v[160:161] neg_lo:[1,0,0] neg_hi:[1,0,0]
	v_pk_fma_f32 v[160:161], v[114:115], v[8:9], v[160:161] neg_lo:[1,0,0] neg_hi:[1,0,0]
	s_waitcnt lgkmcnt(5)
	v_pk_fma_f32 v[160:161], v[116:117], v[10:11], v[160:161] neg_lo:[1,0,0] neg_hi:[1,0,0]
	v_pk_fma_f32 v[160:161], v[118:119], v[12:13], v[160:161] neg_lo:[1,0,0] neg_hi:[1,0,0]
	s_waitcnt lgkmcnt(4)
	v_pk_fma_f32 v[160:161], v[120:121], v[14:15], v[160:161] neg_lo:[1,0,0] neg_hi:[1,0,0]
	v_pk_fma_f32 v[160:161], v[122:123], v[16:17], v[160:161] neg_lo:[1,0,0] neg_hi:[1,0,0]
	s_waitcnt lgkmcnt(3)
	v_pk_fma_f32 v[160:161], v[124:125], v[18:19], v[160:161] neg_lo:[1,0,0] neg_hi:[1,0,0]
	v_pk_fma_f32 v[160:161], v[126:127], v[20:21], v[160:161] neg_lo:[1,0,0] neg_hi:[1,0,0]
	s_waitcnt lgkmcnt(2)
	v_pk_fma_f32 v[160:161], v[134:135], v[22:23], v[160:161] neg_lo:[1,0,0] neg_hi:[1,0,0]
	v_pk_fma_f32 v[160:161], v[136:137], v[24:25], v[160:161] neg_lo:[1,0,0] neg_hi:[1,0,0]
	s_waitcnt lgkmcnt(1)
	v_pk_fma_f32 v[160:161], v[138:139], v[26:27], v[160:161] neg_lo:[1,0,0] neg_hi:[1,0,0]
	v_pk_fma_f32 v[160:161], v[140:141], v[28:29], v[160:161] neg_lo:[1,0,0] neg_hi:[1,0,0]
	s_waitcnt lgkmcnt(0)
	v_pk_fma_f32 v[160:161], v[142:143], v[30:31], v[160:161] neg_lo:[1,0,0] neg_hi:[1,0,0]
	v_fma_f32 v160, -v32, v144, v160
	v_add_f32_e32 v33, v160, v161
	ds_read_b128 v[106:109], v74 offset:8192
	ds_read_b128 v[110:113], v74 offset:8208
	ds_read_b128 v[114:117], v74 offset:8224
	ds_read_b128 v[118:121], v74 offset:8240
	ds_read_b128 v[122:125], v74 offset:8256
	ds_read_b128 v[126:129], v74 offset:8272
	ds_read_b128 v[134:137], v74 offset:8288
	ds_read_b128 v[138:141], v74 offset:8304
	s_waitcnt lgkmcnt(7)
	v_mul_f32_e32 v106, v2, v106
	v_fma_f32 v160, v34, v105, -v106
	v_fma_f32 v161, -v3, v107, 0
	v_pk_fma_f32 v[160:161], v[108:109], v[4:5], v[160:161] neg_lo:[1,0,0] neg_hi:[1,0,0]
	s_waitcnt lgkmcnt(6)
	v_pk_fma_f32 v[160:161], v[110:111], v[6:7], v[160:161] neg_lo:[1,0,0] neg_hi:[1,0,0]
	v_pk_fma_f32 v[160:161], v[112:113], v[8:9], v[160:161] neg_lo:[1,0,0] neg_hi:[1,0,0]
	s_waitcnt lgkmcnt(5)
	v_pk_fma_f32 v[160:161], v[114:115], v[10:11], v[160:161] neg_lo:[1,0,0] neg_hi:[1,0,0]
	v_pk_fma_f32 v[160:161], v[116:117], v[12:13], v[160:161] neg_lo:[1,0,0] neg_hi:[1,0,0]
	s_waitcnt lgkmcnt(4)
	v_pk_fma_f32 v[160:161], v[118:119], v[14:15], v[160:161] neg_lo:[1,0,0] neg_hi:[1,0,0]
	v_pk_fma_f32 v[160:161], v[120:121], v[16:17], v[160:161] neg_lo:[1,0,0] neg_hi:[1,0,0]
	s_waitcnt lgkmcnt(3)
	v_pk_fma_f32 v[160:161], v[122:123], v[18:19], v[160:161] neg_lo:[1,0,0] neg_hi:[1,0,0]
	v_pk_fma_f32 v[160:161], v[124:125], v[20:21], v[160:161] neg_lo:[1,0,0] neg_hi:[1,0,0]
	s_waitcnt lgkmcnt(2)
	v_pk_fma_f32 v[160:161], v[126:127], v[22:23], v[160:161] neg_lo:[1,0,0] neg_hi:[1,0,0]
	v_pk_fma_f32 v[160:161], v[128:129], v[24:25], v[160:161] neg_lo:[1,0,0] neg_hi:[1,0,0]
	s_waitcnt lgkmcnt(1)
	v_pk_fma_f32 v[160:161], v[134:135], v[26:27], v[160:161] neg_lo:[1,0,0] neg_hi:[1,0,0]
	v_pk_fma_f32 v[160:161], v[136:137], v[28:29], v[160:161] neg_lo:[1,0,0] neg_hi:[1,0,0]
	s_waitcnt lgkmcnt(0)
	v_pk_fma_f32 v[160:161], v[138:139], v[30:31], v[160:161] neg_lo:[1,0,0] neg_hi:[1,0,0]
	v_pk_fma_f32 v[160:161], v[140:141], v[32:33], v[160:161] neg_lo:[1,0,0] neg_hi:[1,0,0]
	v_add_f32_e32 v34, v160, v161
	ds_read_b128 v[106:109], v74 offset:8448
	ds_read_b128 v[110:113], v74 offset:8464
	ds_read_b128 v[114:117], v74 offset:8480
	ds_read_b128 v[118:121], v74 offset:8496
	ds_read_b128 v[122:125], v74 offset:8512
	ds_read_b128 v[126:129], v74 offset:8528
	ds_read_b128 v[134:137], v74 offset:8544
	ds_read_b128 v[138:141], v74 offset:8560
	ds_read_b128 v[142:145], v74 offset:8576
	s_waitcnt lgkmcnt(8)
	v_mul_f32_e32 v105, v2, v106
	v_fma_f32 v160, v35, v104, -v105
	v_fma_f32 v161, -v3, v107, 0
	v_pk_fma_f32 v[160:161], v[108:109], v[4:5], v[160:161] neg_lo:[1,0,0] neg_hi:[1,0,0]
	s_waitcnt lgkmcnt(7)
	v_pk_fma_f32 v[160:161], v[110:111], v[6:7], v[160:161] neg_lo:[1,0,0] neg_hi:[1,0,0]
	v_pk_fma_f32 v[160:161], v[112:113], v[8:9], v[160:161] neg_lo:[1,0,0] neg_hi:[1,0,0]
	s_waitcnt lgkmcnt(6)
	v_pk_fma_f32 v[160:161], v[114:115], v[10:11], v[160:161] neg_lo:[1,0,0] neg_hi:[1,0,0]
	v_pk_fma_f32 v[160:161], v[116:117], v[12:13], v[160:161] neg_lo:[1,0,0] neg_hi:[1,0,0]
	s_waitcnt lgkmcnt(5)
	v_pk_fma_f32 v[160:161], v[118:119], v[14:15], v[160:161] neg_lo:[1,0,0] neg_hi:[1,0,0]
	v_pk_fma_f32 v[160:161], v[120:121], v[16:17], v[160:161] neg_lo:[1,0,0] neg_hi:[1,0,0]
	s_waitcnt lgkmcnt(4)
	v_pk_fma_f32 v[160:161], v[122:123], v[18:19], v[160:161] neg_lo:[1,0,0] neg_hi:[1,0,0]
	v_pk_fma_f32 v[160:161], v[124:125], v[20:21], v[160:161] neg_lo:[1,0,0] neg_hi:[1,0,0]
	s_waitcnt lgkmcnt(3)
	v_pk_fma_f32 v[160:161], v[126:127], v[22:23], v[160:161] neg_lo:[1,0,0] neg_hi:[1,0,0]
	v_pk_fma_f32 v[160:161], v[128:129], v[24:25], v[160:161] neg_lo:[1,0,0] neg_hi:[1,0,0]
	s_waitcnt lgkmcnt(2)
	v_pk_fma_f32 v[160:161], v[134:135], v[26:27], v[160:161] neg_lo:[1,0,0] neg_hi:[1,0,0]
	v_pk_fma_f32 v[160:161], v[136:137], v[28:29], v[160:161] neg_lo:[1,0,0] neg_hi:[1,0,0]
	s_waitcnt lgkmcnt(1)
	v_pk_fma_f32 v[160:161], v[138:139], v[30:31], v[160:161] neg_lo:[1,0,0] neg_hi:[1,0,0]
	v_pk_fma_f32 v[160:161], v[140:141], v[32:33], v[160:161] neg_lo:[1,0,0] neg_hi:[1,0,0]
	s_waitcnt lgkmcnt(0)
	v_fma_f32 v160, -v34, v142, v160
	v_add_f32_e32 v35, v160, v161
	ds_read_b128 v[104:107], v74 offset:8704
	ds_read_b128 v[108:111], v74 offset:8720
	ds_read_b128 v[112:115], v74 offset:8736
	ds_read_b128 v[116:119], v74 offset:8752
	ds_read_b128 v[120:123], v74 offset:8768
	ds_read_b128 v[124:127], v74 offset:8784
	ds_read_b128 v[134:137], v74 offset:8800
	ds_read_b128 v[138:141], v74 offset:8816
	ds_read_b128 v[142:145], v74 offset:8832
	s_waitcnt lgkmcnt(8)
	v_mul_f32_e32 v104, v2, v104
	v_fma_f32 v160, v36, v103, -v104
	v_fma_f32 v161, -v3, v105, 0
	v_pk_fma_f32 v[160:161], v[106:107], v[4:5], v[160:161] neg_lo:[1,0,0] neg_hi:[1,0,0]
	s_waitcnt lgkmcnt(7)
	v_pk_fma_f32 v[160:161], v[108:109], v[6:7], v[160:161] neg_lo:[1,0,0] neg_hi:[1,0,0]
	v_pk_fma_f32 v[160:161], v[110:111], v[8:9], v[160:161] neg_lo:[1,0,0] neg_hi:[1,0,0]
	s_waitcnt lgkmcnt(6)
	v_pk_fma_f32 v[160:161], v[112:113], v[10:11], v[160:161] neg_lo:[1,0,0] neg_hi:[1,0,0]
	v_pk_fma_f32 v[160:161], v[114:115], v[12:13], v[160:161] neg_lo:[1,0,0] neg_hi:[1,0,0]
	s_waitcnt lgkmcnt(5)
	v_pk_fma_f32 v[160:161], v[116:117], v[14:15], v[160:161] neg_lo:[1,0,0] neg_hi:[1,0,0]
	v_pk_fma_f32 v[160:161], v[118:119], v[16:17], v[160:161] neg_lo:[1,0,0] neg_hi:[1,0,0]
	s_waitcnt lgkmcnt(4)
	v_pk_fma_f32 v[160:161], v[120:121], v[18:19], v[160:161] neg_lo:[1,0,0] neg_hi:[1,0,0]
	v_pk_fma_f32 v[160:161], v[122:123], v[20:21], v[160:161] neg_lo:[1,0,0] neg_hi:[1,0,0]
	s_waitcnt lgkmcnt(3)
	v_pk_fma_f32 v[160:161], v[124:125], v[22:23], v[160:161] neg_lo:[1,0,0] neg_hi:[1,0,0]
	v_pk_fma_f32 v[160:161], v[126:127], v[24:25], v[160:161] neg_lo:[1,0,0] neg_hi:[1,0,0]
	s_waitcnt lgkmcnt(2)
	v_pk_fma_f32 v[160:161], v[134:135], v[26:27], v[160:161] neg_lo:[1,0,0] neg_hi:[1,0,0]
	v_pk_fma_f32 v[160:161], v[136:137], v[28:29], v[160:161] neg_lo:[1,0,0] neg_hi:[1,0,0]
	s_waitcnt lgkmcnt(1)
	v_pk_fma_f32 v[160:161], v[138:139], v[30:31], v[160:161] neg_lo:[1,0,0] neg_hi:[1,0,0]
	v_pk_fma_f32 v[160:161], v[140:141], v[32:33], v[160:161] neg_lo:[1,0,0] neg_hi:[1,0,0]
	s_waitcnt lgkmcnt(0)
	v_pk_fma_f32 v[160:161], v[142:143], v[34:35], v[160:161] neg_lo:[1,0,0] neg_hi:[1,0,0]
	v_add_f32_e32 v36, v160, v161
	ds_read_b128 v[104:107], v74 offset:8960
	ds_read_b128 v[108:111], v74 offset:8976
	ds_read_b128 v[112:115], v74 offset:8992
	ds_read_b128 v[116:119], v74 offset:9008
	ds_read_b128 v[120:123], v74 offset:9024
	ds_read_b128 v[124:127], v74 offset:9040
	ds_read_b128 v[134:137], v74 offset:9056
	ds_read_b128 v[138:141], v74 offset:9072
	ds_read_b128 v[142:145], v74 offset:9088
	s_waitcnt lgkmcnt(8)
	v_mul_f32_e32 v103, v2, v104
	v_fma_f32 v160, v37, v102, -v103
	v_fma_f32 v161, -v3, v105, 0
	v_pk_fma_f32 v[160:161], v[106:107], v[4:5], v[160:161] neg_lo:[1,0,0] neg_hi:[1,0,0]
	s_waitcnt lgkmcnt(7)
	v_pk_fma_f32 v[160:161], v[108:109], v[6:7], v[160:161] neg_lo:[1,0,0] neg_hi:[1,0,0]
	v_pk_fma_f32 v[160:161], v[110:111], v[8:9], v[160:161] neg_lo:[1,0,0] neg_hi:[1,0,0]
	s_waitcnt lgkmcnt(6)
	v_pk_fma_f32 v[160:161], v[112:113], v[10:11], v[160:161] neg_lo:[1,0,0] neg_hi:[1,0,0]
	v_pk_fma_f32 v[160:161], v[114:115], v[12:13], v[160:161] neg_lo:[1,0,0] neg_hi:[1,0,0]
	s_waitcnt lgkmcnt(5)
	v_pk_fma_f32 v[160:161], v[116:117], v[14:15], v[160:161] neg_lo:[1,0,0] neg_hi:[1,0,0]
	v_pk_fma_f32 v[160:161], v[118:119], v[16:17], v[160:161] neg_lo:[1,0,0] neg_hi:[1,0,0]
	s_waitcnt lgkmcnt(4)
	v_pk_fma_f32 v[160:161], v[120:121], v[18:19], v[160:161] neg_lo:[1,0,0] neg_hi:[1,0,0]
	v_pk_fma_f32 v[160:161], v[122:123], v[20:21], v[160:161] neg_lo:[1,0,0] neg_hi:[1,0,0]
	s_waitcnt lgkmcnt(3)
	v_pk_fma_f32 v[160:161], v[124:125], v[22:23], v[160:161] neg_lo:[1,0,0] neg_hi:[1,0,0]
	v_pk_fma_f32 v[160:161], v[126:127], v[24:25], v[160:161] neg_lo:[1,0,0] neg_hi:[1,0,0]
	s_waitcnt lgkmcnt(2)
	v_pk_fma_f32 v[160:161], v[134:135], v[26:27], v[160:161] neg_lo:[1,0,0] neg_hi:[1,0,0]
	v_pk_fma_f32 v[160:161], v[136:137], v[28:29], v[160:161] neg_lo:[1,0,0] neg_hi:[1,0,0]
	s_waitcnt lgkmcnt(1)
	v_pk_fma_f32 v[160:161], v[138:139], v[30:31], v[160:161] neg_lo:[1,0,0] neg_hi:[1,0,0]
	v_pk_fma_f32 v[160:161], v[140:141], v[32:33], v[160:161] neg_lo:[1,0,0] neg_hi:[1,0,0]
	s_waitcnt lgkmcnt(0)
	v_pk_fma_f32 v[160:161], v[142:143], v[34:35], v[160:161] neg_lo:[1,0,0] neg_hi:[1,0,0]
	v_fma_f32 v160, -v36, v144, v160
	v_add_f32_e32 v37, v160, v161
	ds_read_b128 v[102:105], v74 offset:9216
	ds_read_b128 v[106:109], v74 offset:9232
	ds_read_b128 v[110:113], v74 offset:9248
	ds_read_b128 v[114:117], v74 offset:9264
	ds_read_b128 v[118:121], v74 offset:9280
	ds_read_b128 v[122:125], v74 offset:9296
	ds_read_b128 v[126:129], v74 offset:9312
	ds_read_b128 v[134:137], v74 offset:9328
	ds_read_b128 v[138:141], v74 offset:9344
	s_waitcnt lgkmcnt(8)
	v_mul_f32_e32 v102, v2, v102
	v_fma_f32 v160, v38, v101, -v102
	v_fma_f32 v161, -v3, v103, 0
	v_pk_fma_f32 v[160:161], v[104:105], v[4:5], v[160:161] neg_lo:[1,0,0] neg_hi:[1,0,0]
	s_waitcnt lgkmcnt(7)
	v_pk_fma_f32 v[160:161], v[106:107], v[6:7], v[160:161] neg_lo:[1,0,0] neg_hi:[1,0,0]
	v_pk_fma_f32 v[160:161], v[108:109], v[8:9], v[160:161] neg_lo:[1,0,0] neg_hi:[1,0,0]
	s_waitcnt lgkmcnt(6)
	v_pk_fma_f32 v[160:161], v[110:111], v[10:11], v[160:161] neg_lo:[1,0,0] neg_hi:[1,0,0]
	v_pk_fma_f32 v[160:161], v[112:113], v[12:13], v[160:161] neg_lo:[1,0,0] neg_hi:[1,0,0]
	s_waitcnt lgkmcnt(5)
	v_pk_fma_f32 v[160:161], v[114:115], v[14:15], v[160:161] neg_lo:[1,0,0] neg_hi:[1,0,0]
	v_pk_fma_f32 v[160:161], v[116:117], v[16:17], v[160:161] neg_lo:[1,0,0] neg_hi:[1,0,0]
	s_waitcnt lgkmcnt(4)
	v_pk_fma_f32 v[160:161], v[118:119], v[18:19], v[160:161] neg_lo:[1,0,0] neg_hi:[1,0,0]
	v_pk_fma_f32 v[160:161], v[120:121], v[20:21], v[160:161] neg_lo:[1,0,0] neg_hi:[1,0,0]
	s_waitcnt lgkmcnt(3)
	v_pk_fma_f32 v[160:161], v[122:123], v[22:23], v[160:161] neg_lo:[1,0,0] neg_hi:[1,0,0]
	v_pk_fma_f32 v[160:161], v[124:125], v[24:25], v[160:161] neg_lo:[1,0,0] neg_hi:[1,0,0]
	s_waitcnt lgkmcnt(2)
	v_pk_fma_f32 v[160:161], v[126:127], v[26:27], v[160:161] neg_lo:[1,0,0] neg_hi:[1,0,0]
	v_pk_fma_f32 v[160:161], v[128:129], v[28:29], v[160:161] neg_lo:[1,0,0] neg_hi:[1,0,0]
	s_waitcnt lgkmcnt(1)
	v_pk_fma_f32 v[160:161], v[134:135], v[30:31], v[160:161] neg_lo:[1,0,0] neg_hi:[1,0,0]
	v_pk_fma_f32 v[160:161], v[136:137], v[32:33], v[160:161] neg_lo:[1,0,0] neg_hi:[1,0,0]
	s_waitcnt lgkmcnt(0)
	v_pk_fma_f32 v[160:161], v[138:139], v[34:35], v[160:161] neg_lo:[1,0,0] neg_hi:[1,0,0]
	v_pk_fma_f32 v[160:161], v[140:141], v[36:37], v[160:161] neg_lo:[1,0,0] neg_hi:[1,0,0]
	v_add_f32_e32 v38, v160, v161
	ds_read_b128 v[102:105], v74 offset:9472
	ds_read_b128 v[106:109], v74 offset:9488
	ds_read_b128 v[110:113], v74 offset:9504
	ds_read_b128 v[114:117], v74 offset:9520
	ds_read_b128 v[118:121], v74 offset:9536
	ds_read_b128 v[122:125], v74 offset:9552
	ds_read_b128 v[126:129], v74 offset:9568
	ds_read_b128 v[134:137], v74 offset:9584
	ds_read_b128 v[138:141], v74 offset:9600
	ds_read_b128 v[142:145], v74 offset:9616
	s_waitcnt lgkmcnt(9)
	v_mul_f32_e32 v101, v2, v102
	v_fma_f32 v160, v39, v100, -v101
	v_fma_f32 v161, -v3, v103, 0
	v_pk_fma_f32 v[160:161], v[104:105], v[4:5], v[160:161] neg_lo:[1,0,0] neg_hi:[1,0,0]
	s_waitcnt lgkmcnt(8)
	v_pk_fma_f32 v[160:161], v[106:107], v[6:7], v[160:161] neg_lo:[1,0,0] neg_hi:[1,0,0]
	v_pk_fma_f32 v[160:161], v[108:109], v[8:9], v[160:161] neg_lo:[1,0,0] neg_hi:[1,0,0]
	s_waitcnt lgkmcnt(7)
	v_pk_fma_f32 v[160:161], v[110:111], v[10:11], v[160:161] neg_lo:[1,0,0] neg_hi:[1,0,0]
	v_pk_fma_f32 v[160:161], v[112:113], v[12:13], v[160:161] neg_lo:[1,0,0] neg_hi:[1,0,0]
	s_waitcnt lgkmcnt(6)
	v_pk_fma_f32 v[160:161], v[114:115], v[14:15], v[160:161] neg_lo:[1,0,0] neg_hi:[1,0,0]
	v_pk_fma_f32 v[160:161], v[116:117], v[16:17], v[160:161] neg_lo:[1,0,0] neg_hi:[1,0,0]
	s_waitcnt lgkmcnt(5)
	v_pk_fma_f32 v[160:161], v[118:119], v[18:19], v[160:161] neg_lo:[1,0,0] neg_hi:[1,0,0]
	v_pk_fma_f32 v[160:161], v[120:121], v[20:21], v[160:161] neg_lo:[1,0,0] neg_hi:[1,0,0]
	s_waitcnt lgkmcnt(4)
	v_pk_fma_f32 v[160:161], v[122:123], v[22:23], v[160:161] neg_lo:[1,0,0] neg_hi:[1,0,0]
	v_pk_fma_f32 v[160:161], v[124:125], v[24:25], v[160:161] neg_lo:[1,0,0] neg_hi:[1,0,0]
	s_waitcnt lgkmcnt(3)
	v_pk_fma_f32 v[160:161], v[126:127], v[26:27], v[160:161] neg_lo:[1,0,0] neg_hi:[1,0,0]
	v_pk_fma_f32 v[160:161], v[128:129], v[28:29], v[160:161] neg_lo:[1,0,0] neg_hi:[1,0,0]
	s_waitcnt lgkmcnt(2)
	v_pk_fma_f32 v[160:161], v[134:135], v[30:31], v[160:161] neg_lo:[1,0,0] neg_hi:[1,0,0]
	v_pk_fma_f32 v[160:161], v[136:137], v[32:33], v[160:161] neg_lo:[1,0,0] neg_hi:[1,0,0]
	s_waitcnt lgkmcnt(1)
	v_pk_fma_f32 v[160:161], v[138:139], v[34:35], v[160:161] neg_lo:[1,0,0] neg_hi:[1,0,0]
	v_pk_fma_f32 v[160:161], v[140:141], v[36:37], v[160:161] neg_lo:[1,0,0] neg_hi:[1,0,0]
	s_waitcnt lgkmcnt(0)
	v_fma_f32 v160, -v38, v142, v160
	v_add_f32_e32 v39, v160, v161
	ds_read_b128 v[100:103], v74 offset:9728
	ds_read_b128 v[104:107], v74 offset:9744
	ds_read_b128 v[108:111], v74 offset:9760
	ds_read_b128 v[112:115], v74 offset:9776
	ds_read_b128 v[116:119], v74 offset:9792
	ds_read_b128 v[120:123], v74 offset:9808
	ds_read_b128 v[124:127], v74 offset:9824
	ds_read_b128 v[134:137], v74 offset:9840
	ds_read_b128 v[138:141], v74 offset:9856
	ds_read_b128 v[142:145], v74 offset:9872
	s_waitcnt lgkmcnt(9)
	v_mul_f32_e32 v100, v2, v100
	v_fma_f32 v160, v40, v99, -v100
	v_fma_f32 v161, -v3, v101, 0
	v_pk_fma_f32 v[160:161], v[102:103], v[4:5], v[160:161] neg_lo:[1,0,0] neg_hi:[1,0,0]
	s_waitcnt lgkmcnt(8)
	v_pk_fma_f32 v[160:161], v[104:105], v[6:7], v[160:161] neg_lo:[1,0,0] neg_hi:[1,0,0]
	v_pk_fma_f32 v[160:161], v[106:107], v[8:9], v[160:161] neg_lo:[1,0,0] neg_hi:[1,0,0]
	s_waitcnt lgkmcnt(7)
	v_pk_fma_f32 v[160:161], v[108:109], v[10:11], v[160:161] neg_lo:[1,0,0] neg_hi:[1,0,0]
	v_pk_fma_f32 v[160:161], v[110:111], v[12:13], v[160:161] neg_lo:[1,0,0] neg_hi:[1,0,0]
	s_waitcnt lgkmcnt(6)
	v_pk_fma_f32 v[160:161], v[112:113], v[14:15], v[160:161] neg_lo:[1,0,0] neg_hi:[1,0,0]
	v_pk_fma_f32 v[160:161], v[114:115], v[16:17], v[160:161] neg_lo:[1,0,0] neg_hi:[1,0,0]
	s_waitcnt lgkmcnt(5)
	v_pk_fma_f32 v[160:161], v[116:117], v[18:19], v[160:161] neg_lo:[1,0,0] neg_hi:[1,0,0]
	v_pk_fma_f32 v[160:161], v[118:119], v[20:21], v[160:161] neg_lo:[1,0,0] neg_hi:[1,0,0]
	s_waitcnt lgkmcnt(4)
	v_pk_fma_f32 v[160:161], v[120:121], v[22:23], v[160:161] neg_lo:[1,0,0] neg_hi:[1,0,0]
	v_pk_fma_f32 v[160:161], v[122:123], v[24:25], v[160:161] neg_lo:[1,0,0] neg_hi:[1,0,0]
	s_waitcnt lgkmcnt(3)
	v_pk_fma_f32 v[160:161], v[124:125], v[26:27], v[160:161] neg_lo:[1,0,0] neg_hi:[1,0,0]
	v_pk_fma_f32 v[160:161], v[126:127], v[28:29], v[160:161] neg_lo:[1,0,0] neg_hi:[1,0,0]
	s_waitcnt lgkmcnt(2)
	v_pk_fma_f32 v[160:161], v[134:135], v[30:31], v[160:161] neg_lo:[1,0,0] neg_hi:[1,0,0]
	v_pk_fma_f32 v[160:161], v[136:137], v[32:33], v[160:161] neg_lo:[1,0,0] neg_hi:[1,0,0]
	s_waitcnt lgkmcnt(1)
	v_pk_fma_f32 v[160:161], v[138:139], v[34:35], v[160:161] neg_lo:[1,0,0] neg_hi:[1,0,0]
	v_pk_fma_f32 v[160:161], v[140:141], v[36:37], v[160:161] neg_lo:[1,0,0] neg_hi:[1,0,0]
	s_waitcnt lgkmcnt(0)
	v_pk_fma_f32 v[160:161], v[142:143], v[38:39], v[160:161] neg_lo:[1,0,0] neg_hi:[1,0,0]
	v_add_f32_e32 v40, v160, v161
	ds_read_b128 v[100:103], v74 offset:9984
	ds_read_b128 v[104:107], v74 offset:10000
	ds_read_b128 v[108:111], v74 offset:10016
	ds_read_b128 v[112:115], v74 offset:10032
	ds_read_b128 v[116:119], v74 offset:10048
	ds_read_b128 v[120:123], v74 offset:10064
	ds_read_b128 v[124:127], v74 offset:10080
	ds_read_b128 v[134:137], v74 offset:10096
	ds_read_b128 v[138:141], v74 offset:10112
	ds_read_b128 v[142:145], v74 offset:10128
	s_waitcnt lgkmcnt(9)
	v_mul_f32_e32 v99, v2, v100
	v_fma_f32 v160, v41, v98, -v99
	v_fma_f32 v161, -v3, v101, 0
	v_pk_fma_f32 v[160:161], v[102:103], v[4:5], v[160:161] neg_lo:[1,0,0] neg_hi:[1,0,0]
	s_waitcnt lgkmcnt(8)
	v_pk_fma_f32 v[160:161], v[104:105], v[6:7], v[160:161] neg_lo:[1,0,0] neg_hi:[1,0,0]
	v_pk_fma_f32 v[160:161], v[106:107], v[8:9], v[160:161] neg_lo:[1,0,0] neg_hi:[1,0,0]
	s_waitcnt lgkmcnt(7)
	v_pk_fma_f32 v[160:161], v[108:109], v[10:11], v[160:161] neg_lo:[1,0,0] neg_hi:[1,0,0]
	v_pk_fma_f32 v[160:161], v[110:111], v[12:13], v[160:161] neg_lo:[1,0,0] neg_hi:[1,0,0]
	s_waitcnt lgkmcnt(6)
	v_pk_fma_f32 v[160:161], v[112:113], v[14:15], v[160:161] neg_lo:[1,0,0] neg_hi:[1,0,0]
	v_pk_fma_f32 v[160:161], v[114:115], v[16:17], v[160:161] neg_lo:[1,0,0] neg_hi:[1,0,0]
	s_waitcnt lgkmcnt(5)
	v_pk_fma_f32 v[160:161], v[116:117], v[18:19], v[160:161] neg_lo:[1,0,0] neg_hi:[1,0,0]
	v_pk_fma_f32 v[160:161], v[118:119], v[20:21], v[160:161] neg_lo:[1,0,0] neg_hi:[1,0,0]
	s_waitcnt lgkmcnt(4)
	v_pk_fma_f32 v[160:161], v[120:121], v[22:23], v[160:161] neg_lo:[1,0,0] neg_hi:[1,0,0]
	v_pk_fma_f32 v[160:161], v[122:123], v[24:25], v[160:161] neg_lo:[1,0,0] neg_hi:[1,0,0]
	s_waitcnt lgkmcnt(3)
	v_pk_fma_f32 v[160:161], v[124:125], v[26:27], v[160:161] neg_lo:[1,0,0] neg_hi:[1,0,0]
	v_pk_fma_f32 v[160:161], v[126:127], v[28:29], v[160:161] neg_lo:[1,0,0] neg_hi:[1,0,0]
	s_waitcnt lgkmcnt(2)
	v_pk_fma_f32 v[160:161], v[134:135], v[30:31], v[160:161] neg_lo:[1,0,0] neg_hi:[1,0,0]
	v_pk_fma_f32 v[160:161], v[136:137], v[32:33], v[160:161] neg_lo:[1,0,0] neg_hi:[1,0,0]
	s_waitcnt lgkmcnt(1)
	v_pk_fma_f32 v[160:161], v[138:139], v[34:35], v[160:161] neg_lo:[1,0,0] neg_hi:[1,0,0]
	v_pk_fma_f32 v[160:161], v[140:141], v[36:37], v[160:161] neg_lo:[1,0,0] neg_hi:[1,0,0]
	s_waitcnt lgkmcnt(0)
	v_pk_fma_f32 v[160:161], v[142:143], v[38:39], v[160:161] neg_lo:[1,0,0] neg_hi:[1,0,0]
	v_fma_f32 v160, -v40, v144, v160
	v_add_f32_e32 v41, v160, v161
	ds_read_b128 v[98:101], v74 offset:10240
	ds_read_b128 v[102:105], v74 offset:10256
	ds_read_b128 v[106:109], v74 offset:10272
	ds_read_b128 v[110:113], v74 offset:10288
	ds_read_b128 v[114:117], v74 offset:10304
	ds_read_b128 v[118:121], v74 offset:10320
	ds_read_b128 v[122:125], v74 offset:10336
	ds_read_b128 v[126:129], v74 offset:10352
	ds_read_b128 v[134:137], v74 offset:10368
	ds_read_b128 v[138:141], v74 offset:10384
	s_waitcnt lgkmcnt(9)
	v_mul_f32_e32 v98, v2, v98
	v_fma_f32 v160, v42, v97, -v98
	v_fma_f32 v161, -v3, v99, 0
	v_pk_fma_f32 v[160:161], v[100:101], v[4:5], v[160:161] neg_lo:[1,0,0] neg_hi:[1,0,0]
	s_waitcnt lgkmcnt(8)
	v_pk_fma_f32 v[160:161], v[102:103], v[6:7], v[160:161] neg_lo:[1,0,0] neg_hi:[1,0,0]
	v_pk_fma_f32 v[160:161], v[104:105], v[8:9], v[160:161] neg_lo:[1,0,0] neg_hi:[1,0,0]
	s_waitcnt lgkmcnt(7)
	v_pk_fma_f32 v[160:161], v[106:107], v[10:11], v[160:161] neg_lo:[1,0,0] neg_hi:[1,0,0]
	v_pk_fma_f32 v[160:161], v[108:109], v[12:13], v[160:161] neg_lo:[1,0,0] neg_hi:[1,0,0]
	s_waitcnt lgkmcnt(6)
	v_pk_fma_f32 v[160:161], v[110:111], v[14:15], v[160:161] neg_lo:[1,0,0] neg_hi:[1,0,0]
	v_pk_fma_f32 v[160:161], v[112:113], v[16:17], v[160:161] neg_lo:[1,0,0] neg_hi:[1,0,0]
	s_waitcnt lgkmcnt(5)
	v_pk_fma_f32 v[160:161], v[114:115], v[18:19], v[160:161] neg_lo:[1,0,0] neg_hi:[1,0,0]
	v_pk_fma_f32 v[160:161], v[116:117], v[20:21], v[160:161] neg_lo:[1,0,0] neg_hi:[1,0,0]
	s_waitcnt lgkmcnt(4)
	v_pk_fma_f32 v[160:161], v[118:119], v[22:23], v[160:161] neg_lo:[1,0,0] neg_hi:[1,0,0]
	v_pk_fma_f32 v[160:161], v[120:121], v[24:25], v[160:161] neg_lo:[1,0,0] neg_hi:[1,0,0]
	s_waitcnt lgkmcnt(3)
	v_pk_fma_f32 v[160:161], v[122:123], v[26:27], v[160:161] neg_lo:[1,0,0] neg_hi:[1,0,0]
	v_pk_fma_f32 v[160:161], v[124:125], v[28:29], v[160:161] neg_lo:[1,0,0] neg_hi:[1,0,0]
	s_waitcnt lgkmcnt(2)
	v_pk_fma_f32 v[160:161], v[126:127], v[30:31], v[160:161] neg_lo:[1,0,0] neg_hi:[1,0,0]
	v_pk_fma_f32 v[160:161], v[128:129], v[32:33], v[160:161] neg_lo:[1,0,0] neg_hi:[1,0,0]
	s_waitcnt lgkmcnt(1)
	v_pk_fma_f32 v[160:161], v[134:135], v[34:35], v[160:161] neg_lo:[1,0,0] neg_hi:[1,0,0]
	v_pk_fma_f32 v[160:161], v[136:137], v[36:37], v[160:161] neg_lo:[1,0,0] neg_hi:[1,0,0]
	s_waitcnt lgkmcnt(0)
	v_pk_fma_f32 v[160:161], v[138:139], v[38:39], v[160:161] neg_lo:[1,0,0] neg_hi:[1,0,0]
	v_pk_fma_f32 v[160:161], v[140:141], v[40:41], v[160:161] neg_lo:[1,0,0] neg_hi:[1,0,0]
	v_add_f32_e32 v42, v160, v161
	ds_read_b128 v[98:101], v74 offset:10496
	ds_read_b128 v[102:105], v74 offset:10512
	ds_read_b128 v[106:109], v74 offset:10528
	ds_read_b128 v[110:113], v74 offset:10544
	ds_read_b128 v[114:117], v74 offset:10560
	ds_read_b128 v[118:121], v74 offset:10576
	ds_read_b128 v[122:125], v74 offset:10592
	ds_read_b128 v[126:129], v74 offset:10608
	ds_read_b128 v[134:137], v74 offset:10624
	ds_read_b128 v[138:141], v74 offset:10640
	ds_read_b128 v[142:145], v74 offset:10656
	s_waitcnt lgkmcnt(10)
	v_mul_f32_e32 v97, v2, v98
	v_fma_f32 v160, v43, v96, -v97
	v_fma_f32 v161, -v3, v99, 0
	v_pk_fma_f32 v[160:161], v[100:101], v[4:5], v[160:161] neg_lo:[1,0,0] neg_hi:[1,0,0]
	s_waitcnt lgkmcnt(9)
	v_pk_fma_f32 v[160:161], v[102:103], v[6:7], v[160:161] neg_lo:[1,0,0] neg_hi:[1,0,0]
	v_pk_fma_f32 v[160:161], v[104:105], v[8:9], v[160:161] neg_lo:[1,0,0] neg_hi:[1,0,0]
	s_waitcnt lgkmcnt(8)
	v_pk_fma_f32 v[160:161], v[106:107], v[10:11], v[160:161] neg_lo:[1,0,0] neg_hi:[1,0,0]
	v_pk_fma_f32 v[160:161], v[108:109], v[12:13], v[160:161] neg_lo:[1,0,0] neg_hi:[1,0,0]
	s_waitcnt lgkmcnt(7)
	v_pk_fma_f32 v[160:161], v[110:111], v[14:15], v[160:161] neg_lo:[1,0,0] neg_hi:[1,0,0]
	v_pk_fma_f32 v[160:161], v[112:113], v[16:17], v[160:161] neg_lo:[1,0,0] neg_hi:[1,0,0]
	s_waitcnt lgkmcnt(6)
	v_pk_fma_f32 v[160:161], v[114:115], v[18:19], v[160:161] neg_lo:[1,0,0] neg_hi:[1,0,0]
	v_pk_fma_f32 v[160:161], v[116:117], v[20:21], v[160:161] neg_lo:[1,0,0] neg_hi:[1,0,0]
	s_waitcnt lgkmcnt(5)
	v_pk_fma_f32 v[160:161], v[118:119], v[22:23], v[160:161] neg_lo:[1,0,0] neg_hi:[1,0,0]
	v_pk_fma_f32 v[160:161], v[120:121], v[24:25], v[160:161] neg_lo:[1,0,0] neg_hi:[1,0,0]
	s_waitcnt lgkmcnt(4)
	v_pk_fma_f32 v[160:161], v[122:123], v[26:27], v[160:161] neg_lo:[1,0,0] neg_hi:[1,0,0]
	v_pk_fma_f32 v[160:161], v[124:125], v[28:29], v[160:161] neg_lo:[1,0,0] neg_hi:[1,0,0]
	s_waitcnt lgkmcnt(3)
	v_pk_fma_f32 v[160:161], v[126:127], v[30:31], v[160:161] neg_lo:[1,0,0] neg_hi:[1,0,0]
	v_pk_fma_f32 v[160:161], v[128:129], v[32:33], v[160:161] neg_lo:[1,0,0] neg_hi:[1,0,0]
	s_waitcnt lgkmcnt(2)
	v_pk_fma_f32 v[160:161], v[134:135], v[34:35], v[160:161] neg_lo:[1,0,0] neg_hi:[1,0,0]
	v_pk_fma_f32 v[160:161], v[136:137], v[36:37], v[160:161] neg_lo:[1,0,0] neg_hi:[1,0,0]
	s_waitcnt lgkmcnt(1)
	v_pk_fma_f32 v[160:161], v[138:139], v[38:39], v[160:161] neg_lo:[1,0,0] neg_hi:[1,0,0]
	v_pk_fma_f32 v[160:161], v[140:141], v[40:41], v[160:161] neg_lo:[1,0,0] neg_hi:[1,0,0]
	s_waitcnt lgkmcnt(0)
	v_fma_f32 v160, -v42, v142, v160
	v_add_f32_e32 v43, v160, v161
	ds_read_b128 v[96:99], v74 offset:10752
	ds_read_b128 v[100:103], v74 offset:10768
	ds_read_b128 v[104:107], v74 offset:10784
	ds_read_b128 v[108:111], v74 offset:10800
	ds_read_b128 v[112:115], v74 offset:10816
	ds_read_b128 v[116:119], v74 offset:10832
	ds_read_b128 v[120:123], v74 offset:10848
	ds_read_b128 v[124:127], v74 offset:10864
	ds_read_b128 v[134:137], v74 offset:10880
	ds_read_b128 v[138:141], v74 offset:10896
	ds_read_b128 v[142:145], v74 offset:10912
	s_waitcnt lgkmcnt(10)
	v_mul_f32_e32 v96, v2, v96
	v_fma_f32 v160, v44, v95, -v96
	v_fma_f32 v161, -v3, v97, 0
	v_pk_fma_f32 v[160:161], v[98:99], v[4:5], v[160:161] neg_lo:[1,0,0] neg_hi:[1,0,0]
	s_waitcnt lgkmcnt(9)
	v_pk_fma_f32 v[160:161], v[100:101], v[6:7], v[160:161] neg_lo:[1,0,0] neg_hi:[1,0,0]
	v_pk_fma_f32 v[160:161], v[102:103], v[8:9], v[160:161] neg_lo:[1,0,0] neg_hi:[1,0,0]
	s_waitcnt lgkmcnt(8)
	v_pk_fma_f32 v[160:161], v[104:105], v[10:11], v[160:161] neg_lo:[1,0,0] neg_hi:[1,0,0]
	v_pk_fma_f32 v[160:161], v[106:107], v[12:13], v[160:161] neg_lo:[1,0,0] neg_hi:[1,0,0]
	s_waitcnt lgkmcnt(7)
	v_pk_fma_f32 v[160:161], v[108:109], v[14:15], v[160:161] neg_lo:[1,0,0] neg_hi:[1,0,0]
	v_pk_fma_f32 v[160:161], v[110:111], v[16:17], v[160:161] neg_lo:[1,0,0] neg_hi:[1,0,0]
	s_waitcnt lgkmcnt(6)
	v_pk_fma_f32 v[160:161], v[112:113], v[18:19], v[160:161] neg_lo:[1,0,0] neg_hi:[1,0,0]
	v_pk_fma_f32 v[160:161], v[114:115], v[20:21], v[160:161] neg_lo:[1,0,0] neg_hi:[1,0,0]
	s_waitcnt lgkmcnt(5)
	v_pk_fma_f32 v[160:161], v[116:117], v[22:23], v[160:161] neg_lo:[1,0,0] neg_hi:[1,0,0]
	v_pk_fma_f32 v[160:161], v[118:119], v[24:25], v[160:161] neg_lo:[1,0,0] neg_hi:[1,0,0]
	s_waitcnt lgkmcnt(4)
	v_pk_fma_f32 v[160:161], v[120:121], v[26:27], v[160:161] neg_lo:[1,0,0] neg_hi:[1,0,0]
	v_pk_fma_f32 v[160:161], v[122:123], v[28:29], v[160:161] neg_lo:[1,0,0] neg_hi:[1,0,0]
	s_waitcnt lgkmcnt(3)
	v_pk_fma_f32 v[160:161], v[124:125], v[30:31], v[160:161] neg_lo:[1,0,0] neg_hi:[1,0,0]
	v_pk_fma_f32 v[160:161], v[126:127], v[32:33], v[160:161] neg_lo:[1,0,0] neg_hi:[1,0,0]
	s_waitcnt lgkmcnt(2)
	v_pk_fma_f32 v[160:161], v[134:135], v[34:35], v[160:161] neg_lo:[1,0,0] neg_hi:[1,0,0]
	v_pk_fma_f32 v[160:161], v[136:137], v[36:37], v[160:161] neg_lo:[1,0,0] neg_hi:[1,0,0]
	s_waitcnt lgkmcnt(1)
	v_pk_fma_f32 v[160:161], v[138:139], v[38:39], v[160:161] neg_lo:[1,0,0] neg_hi:[1,0,0]
	v_pk_fma_f32 v[160:161], v[140:141], v[40:41], v[160:161] neg_lo:[1,0,0] neg_hi:[1,0,0]
	s_waitcnt lgkmcnt(0)
	v_pk_fma_f32 v[160:161], v[142:143], v[42:43], v[160:161] neg_lo:[1,0,0] neg_hi:[1,0,0]
	v_add_f32_e32 v44, v160, v161
	ds_read_b128 v[96:99], v74 offset:11008
	ds_read_b128 v[100:103], v74 offset:11024
	ds_read_b128 v[104:107], v74 offset:11040
	ds_read_b128 v[108:111], v74 offset:11056
	ds_read_b128 v[112:115], v74 offset:11072
	ds_read_b128 v[116:119], v74 offset:11088
	ds_read_b128 v[120:123], v74 offset:11104
	ds_read_b128 v[124:127], v74 offset:11120
	ds_read_b128 v[134:137], v74 offset:11136
	ds_read_b128 v[138:141], v74 offset:11152
	ds_read_b128 v[142:145], v74 offset:11168
	s_waitcnt lgkmcnt(10)
	v_mul_f32_e32 v95, v2, v96
	v_fma_f32 v160, v45, v94, -v95
	v_fma_f32 v161, -v3, v97, 0
	v_pk_fma_f32 v[160:161], v[98:99], v[4:5], v[160:161] neg_lo:[1,0,0] neg_hi:[1,0,0]
	s_waitcnt lgkmcnt(9)
	v_pk_fma_f32 v[160:161], v[100:101], v[6:7], v[160:161] neg_lo:[1,0,0] neg_hi:[1,0,0]
	v_pk_fma_f32 v[160:161], v[102:103], v[8:9], v[160:161] neg_lo:[1,0,0] neg_hi:[1,0,0]
	s_waitcnt lgkmcnt(8)
	v_pk_fma_f32 v[160:161], v[104:105], v[10:11], v[160:161] neg_lo:[1,0,0] neg_hi:[1,0,0]
	v_pk_fma_f32 v[160:161], v[106:107], v[12:13], v[160:161] neg_lo:[1,0,0] neg_hi:[1,0,0]
	s_waitcnt lgkmcnt(7)
	v_pk_fma_f32 v[160:161], v[108:109], v[14:15], v[160:161] neg_lo:[1,0,0] neg_hi:[1,0,0]
	v_pk_fma_f32 v[160:161], v[110:111], v[16:17], v[160:161] neg_lo:[1,0,0] neg_hi:[1,0,0]
	s_waitcnt lgkmcnt(6)
	v_pk_fma_f32 v[160:161], v[112:113], v[18:19], v[160:161] neg_lo:[1,0,0] neg_hi:[1,0,0]
	v_pk_fma_f32 v[160:161], v[114:115], v[20:21], v[160:161] neg_lo:[1,0,0] neg_hi:[1,0,0]
	s_waitcnt lgkmcnt(5)
	v_pk_fma_f32 v[160:161], v[116:117], v[22:23], v[160:161] neg_lo:[1,0,0] neg_hi:[1,0,0]
	v_pk_fma_f32 v[160:161], v[118:119], v[24:25], v[160:161] neg_lo:[1,0,0] neg_hi:[1,0,0]
	s_waitcnt lgkmcnt(4)
	v_pk_fma_f32 v[160:161], v[120:121], v[26:27], v[160:161] neg_lo:[1,0,0] neg_hi:[1,0,0]
	v_pk_fma_f32 v[160:161], v[122:123], v[28:29], v[160:161] neg_lo:[1,0,0] neg_hi:[1,0,0]
	s_waitcnt lgkmcnt(3)
	v_pk_fma_f32 v[160:161], v[124:125], v[30:31], v[160:161] neg_lo:[1,0,0] neg_hi:[1,0,0]
	v_pk_fma_f32 v[160:161], v[126:127], v[32:33], v[160:161] neg_lo:[1,0,0] neg_hi:[1,0,0]
	s_waitcnt lgkmcnt(2)
	v_pk_fma_f32 v[160:161], v[134:135], v[34:35], v[160:161] neg_lo:[1,0,0] neg_hi:[1,0,0]
	v_pk_fma_f32 v[160:161], v[136:137], v[36:37], v[160:161] neg_lo:[1,0,0] neg_hi:[1,0,0]
	s_waitcnt lgkmcnt(1)
	v_pk_fma_f32 v[160:161], v[138:139], v[38:39], v[160:161] neg_lo:[1,0,0] neg_hi:[1,0,0]
	v_pk_fma_f32 v[160:161], v[140:141], v[40:41], v[160:161] neg_lo:[1,0,0] neg_hi:[1,0,0]
	s_waitcnt lgkmcnt(0)
	v_pk_fma_f32 v[160:161], v[142:143], v[42:43], v[160:161] neg_lo:[1,0,0] neg_hi:[1,0,0]
	v_fma_f32 v160, -v44, v144, v160
	v_add_f32_e32 v45, v160, v161
	ds_read_b128 v[94:97], v74 offset:11264
	ds_read_b128 v[98:101], v74 offset:11280
	ds_read_b128 v[102:105], v74 offset:11296
	ds_read_b128 v[106:109], v74 offset:11312
	ds_read_b128 v[110:113], v74 offset:11328
	ds_read_b128 v[114:117], v74 offset:11344
	ds_read_b128 v[118:121], v74 offset:11360
	ds_read_b128 v[122:125], v74 offset:11376
	ds_read_b128 v[126:129], v74 offset:11392
	ds_read_b128 v[134:137], v74 offset:11408
	ds_read_b128 v[138:141], v74 offset:11424
	s_waitcnt lgkmcnt(10)
	v_mul_f32_e32 v94, v2, v94
	v_fma_f32 v160, v46, v93, -v94
	v_fma_f32 v161, -v3, v95, 0
	v_pk_fma_f32 v[160:161], v[96:97], v[4:5], v[160:161] neg_lo:[1,0,0] neg_hi:[1,0,0]
	s_waitcnt lgkmcnt(9)
	v_pk_fma_f32 v[160:161], v[98:99], v[6:7], v[160:161] neg_lo:[1,0,0] neg_hi:[1,0,0]
	v_pk_fma_f32 v[160:161], v[100:101], v[8:9], v[160:161] neg_lo:[1,0,0] neg_hi:[1,0,0]
	s_waitcnt lgkmcnt(8)
	v_pk_fma_f32 v[160:161], v[102:103], v[10:11], v[160:161] neg_lo:[1,0,0] neg_hi:[1,0,0]
	v_pk_fma_f32 v[160:161], v[104:105], v[12:13], v[160:161] neg_lo:[1,0,0] neg_hi:[1,0,0]
	s_waitcnt lgkmcnt(7)
	v_pk_fma_f32 v[160:161], v[106:107], v[14:15], v[160:161] neg_lo:[1,0,0] neg_hi:[1,0,0]
	v_pk_fma_f32 v[160:161], v[108:109], v[16:17], v[160:161] neg_lo:[1,0,0] neg_hi:[1,0,0]
	s_waitcnt lgkmcnt(6)
	v_pk_fma_f32 v[160:161], v[110:111], v[18:19], v[160:161] neg_lo:[1,0,0] neg_hi:[1,0,0]
	v_pk_fma_f32 v[160:161], v[112:113], v[20:21], v[160:161] neg_lo:[1,0,0] neg_hi:[1,0,0]
	s_waitcnt lgkmcnt(5)
	v_pk_fma_f32 v[160:161], v[114:115], v[22:23], v[160:161] neg_lo:[1,0,0] neg_hi:[1,0,0]
	v_pk_fma_f32 v[160:161], v[116:117], v[24:25], v[160:161] neg_lo:[1,0,0] neg_hi:[1,0,0]
	s_waitcnt lgkmcnt(4)
	v_pk_fma_f32 v[160:161], v[118:119], v[26:27], v[160:161] neg_lo:[1,0,0] neg_hi:[1,0,0]
	v_pk_fma_f32 v[160:161], v[120:121], v[28:29], v[160:161] neg_lo:[1,0,0] neg_hi:[1,0,0]
	s_waitcnt lgkmcnt(3)
	v_pk_fma_f32 v[160:161], v[122:123], v[30:31], v[160:161] neg_lo:[1,0,0] neg_hi:[1,0,0]
	v_pk_fma_f32 v[160:161], v[124:125], v[32:33], v[160:161] neg_lo:[1,0,0] neg_hi:[1,0,0]
	s_waitcnt lgkmcnt(2)
	v_pk_fma_f32 v[160:161], v[126:127], v[34:35], v[160:161] neg_lo:[1,0,0] neg_hi:[1,0,0]
	v_pk_fma_f32 v[160:161], v[128:129], v[36:37], v[160:161] neg_lo:[1,0,0] neg_hi:[1,0,0]
	s_waitcnt lgkmcnt(1)
	v_pk_fma_f32 v[160:161], v[134:135], v[38:39], v[160:161] neg_lo:[1,0,0] neg_hi:[1,0,0]
	v_pk_fma_f32 v[160:161], v[136:137], v[40:41], v[160:161] neg_lo:[1,0,0] neg_hi:[1,0,0]
	s_waitcnt lgkmcnt(0)
	v_pk_fma_f32 v[160:161], v[138:139], v[42:43], v[160:161] neg_lo:[1,0,0] neg_hi:[1,0,0]
	v_pk_fma_f32 v[160:161], v[140:141], v[44:45], v[160:161] neg_lo:[1,0,0] neg_hi:[1,0,0]
	v_add_f32_e32 v46, v160, v161
	ds_read_b128 v[94:97], v74 offset:11520
	ds_read_b128 v[98:101], v74 offset:11536
	ds_read_b128 v[102:105], v74 offset:11552
	ds_read_b128 v[106:109], v74 offset:11568
	ds_read_b128 v[110:113], v74 offset:11584
	ds_read_b128 v[114:117], v74 offset:11600
	ds_read_b128 v[118:121], v74 offset:11616
	ds_read_b128 v[122:125], v74 offset:11632
	ds_read_b128 v[126:129], v74 offset:11648
	ds_read_b128 v[134:137], v74 offset:11664
	ds_read_b128 v[138:141], v74 offset:11680
	ds_read_b128 v[142:145], v74 offset:11696
	s_waitcnt lgkmcnt(11)
	v_mul_f32_e32 v93, v2, v94
	v_fma_f32 v160, v47, v92, -v93
	v_fma_f32 v161, -v3, v95, 0
	v_pk_fma_f32 v[160:161], v[96:97], v[4:5], v[160:161] neg_lo:[1,0,0] neg_hi:[1,0,0]
	s_waitcnt lgkmcnt(10)
	v_pk_fma_f32 v[160:161], v[98:99], v[6:7], v[160:161] neg_lo:[1,0,0] neg_hi:[1,0,0]
	v_pk_fma_f32 v[160:161], v[100:101], v[8:9], v[160:161] neg_lo:[1,0,0] neg_hi:[1,0,0]
	s_waitcnt lgkmcnt(9)
	v_pk_fma_f32 v[160:161], v[102:103], v[10:11], v[160:161] neg_lo:[1,0,0] neg_hi:[1,0,0]
	v_pk_fma_f32 v[160:161], v[104:105], v[12:13], v[160:161] neg_lo:[1,0,0] neg_hi:[1,0,0]
	s_waitcnt lgkmcnt(8)
	v_pk_fma_f32 v[160:161], v[106:107], v[14:15], v[160:161] neg_lo:[1,0,0] neg_hi:[1,0,0]
	v_pk_fma_f32 v[160:161], v[108:109], v[16:17], v[160:161] neg_lo:[1,0,0] neg_hi:[1,0,0]
	s_waitcnt lgkmcnt(7)
	v_pk_fma_f32 v[160:161], v[110:111], v[18:19], v[160:161] neg_lo:[1,0,0] neg_hi:[1,0,0]
	v_pk_fma_f32 v[160:161], v[112:113], v[20:21], v[160:161] neg_lo:[1,0,0] neg_hi:[1,0,0]
	s_waitcnt lgkmcnt(6)
	v_pk_fma_f32 v[160:161], v[114:115], v[22:23], v[160:161] neg_lo:[1,0,0] neg_hi:[1,0,0]
	v_pk_fma_f32 v[160:161], v[116:117], v[24:25], v[160:161] neg_lo:[1,0,0] neg_hi:[1,0,0]
	s_waitcnt lgkmcnt(5)
	v_pk_fma_f32 v[160:161], v[118:119], v[26:27], v[160:161] neg_lo:[1,0,0] neg_hi:[1,0,0]
	v_pk_fma_f32 v[160:161], v[120:121], v[28:29], v[160:161] neg_lo:[1,0,0] neg_hi:[1,0,0]
	s_waitcnt lgkmcnt(4)
	v_pk_fma_f32 v[160:161], v[122:123], v[30:31], v[160:161] neg_lo:[1,0,0] neg_hi:[1,0,0]
	v_pk_fma_f32 v[160:161], v[124:125], v[32:33], v[160:161] neg_lo:[1,0,0] neg_hi:[1,0,0]
	s_waitcnt lgkmcnt(3)
	v_pk_fma_f32 v[160:161], v[126:127], v[34:35], v[160:161] neg_lo:[1,0,0] neg_hi:[1,0,0]
	v_pk_fma_f32 v[160:161], v[128:129], v[36:37], v[160:161] neg_lo:[1,0,0] neg_hi:[1,0,0]
	s_waitcnt lgkmcnt(2)
	v_pk_fma_f32 v[160:161], v[134:135], v[38:39], v[160:161] neg_lo:[1,0,0] neg_hi:[1,0,0]
	v_pk_fma_f32 v[160:161], v[136:137], v[40:41], v[160:161] neg_lo:[1,0,0] neg_hi:[1,0,0]
	s_waitcnt lgkmcnt(1)
	v_pk_fma_f32 v[160:161], v[138:139], v[42:43], v[160:161] neg_lo:[1,0,0] neg_hi:[1,0,0]
	v_pk_fma_f32 v[160:161], v[140:141], v[44:45], v[160:161] neg_lo:[1,0,0] neg_hi:[1,0,0]
	s_waitcnt lgkmcnt(0)
	v_fma_f32 v160, -v46, v142, v160
	v_add_f32_e32 v47, v160, v161
	ds_read_b128 v[92:95], v74 offset:11776
	ds_read_b128 v[96:99], v74 offset:11792
	ds_read_b128 v[100:103], v74 offset:11808
	ds_read_b128 v[104:107], v74 offset:11824
	ds_read_b128 v[108:111], v74 offset:11840
	ds_read_b128 v[112:115], v74 offset:11856
	ds_read_b128 v[116:119], v74 offset:11872
	ds_read_b128 v[120:123], v74 offset:11888
	ds_read_b128 v[124:127], v74 offset:11904
	ds_read_b128 v[134:137], v74 offset:11920
	ds_read_b128 v[138:141], v74 offset:11936
	ds_read_b128 v[142:145], v74 offset:11952
	s_waitcnt lgkmcnt(11)
	v_mul_f32_e32 v92, v2, v92
	v_fma_f32 v160, v48, v91, -v92
	v_fma_f32 v161, -v3, v93, 0
	v_pk_fma_f32 v[160:161], v[94:95], v[4:5], v[160:161] neg_lo:[1,0,0] neg_hi:[1,0,0]
	s_waitcnt lgkmcnt(10)
	v_pk_fma_f32 v[160:161], v[96:97], v[6:7], v[160:161] neg_lo:[1,0,0] neg_hi:[1,0,0]
	v_pk_fma_f32 v[160:161], v[98:99], v[8:9], v[160:161] neg_lo:[1,0,0] neg_hi:[1,0,0]
	s_waitcnt lgkmcnt(9)
	v_pk_fma_f32 v[160:161], v[100:101], v[10:11], v[160:161] neg_lo:[1,0,0] neg_hi:[1,0,0]
	v_pk_fma_f32 v[160:161], v[102:103], v[12:13], v[160:161] neg_lo:[1,0,0] neg_hi:[1,0,0]
	s_waitcnt lgkmcnt(8)
	v_pk_fma_f32 v[160:161], v[104:105], v[14:15], v[160:161] neg_lo:[1,0,0] neg_hi:[1,0,0]
	v_pk_fma_f32 v[160:161], v[106:107], v[16:17], v[160:161] neg_lo:[1,0,0] neg_hi:[1,0,0]
	s_waitcnt lgkmcnt(7)
	v_pk_fma_f32 v[160:161], v[108:109], v[18:19], v[160:161] neg_lo:[1,0,0] neg_hi:[1,0,0]
	v_pk_fma_f32 v[160:161], v[110:111], v[20:21], v[160:161] neg_lo:[1,0,0] neg_hi:[1,0,0]
	s_waitcnt lgkmcnt(6)
	v_pk_fma_f32 v[160:161], v[112:113], v[22:23], v[160:161] neg_lo:[1,0,0] neg_hi:[1,0,0]
	v_pk_fma_f32 v[160:161], v[114:115], v[24:25], v[160:161] neg_lo:[1,0,0] neg_hi:[1,0,0]
	s_waitcnt lgkmcnt(5)
	v_pk_fma_f32 v[160:161], v[116:117], v[26:27], v[160:161] neg_lo:[1,0,0] neg_hi:[1,0,0]
	v_pk_fma_f32 v[160:161], v[118:119], v[28:29], v[160:161] neg_lo:[1,0,0] neg_hi:[1,0,0]
	s_waitcnt lgkmcnt(4)
	v_pk_fma_f32 v[160:161], v[120:121], v[30:31], v[160:161] neg_lo:[1,0,0] neg_hi:[1,0,0]
	v_pk_fma_f32 v[160:161], v[122:123], v[32:33], v[160:161] neg_lo:[1,0,0] neg_hi:[1,0,0]
	s_waitcnt lgkmcnt(3)
	v_pk_fma_f32 v[160:161], v[124:125], v[34:35], v[160:161] neg_lo:[1,0,0] neg_hi:[1,0,0]
	v_pk_fma_f32 v[160:161], v[126:127], v[36:37], v[160:161] neg_lo:[1,0,0] neg_hi:[1,0,0]
	s_waitcnt lgkmcnt(2)
	v_pk_fma_f32 v[160:161], v[134:135], v[38:39], v[160:161] neg_lo:[1,0,0] neg_hi:[1,0,0]
	v_pk_fma_f32 v[160:161], v[136:137], v[40:41], v[160:161] neg_lo:[1,0,0] neg_hi:[1,0,0]
	s_waitcnt lgkmcnt(1)
	v_pk_fma_f32 v[160:161], v[138:139], v[42:43], v[160:161] neg_lo:[1,0,0] neg_hi:[1,0,0]
	v_pk_fma_f32 v[160:161], v[140:141], v[44:45], v[160:161] neg_lo:[1,0,0] neg_hi:[1,0,0]
	s_waitcnt lgkmcnt(0)
	v_pk_fma_f32 v[160:161], v[142:143], v[46:47], v[160:161] neg_lo:[1,0,0] neg_hi:[1,0,0]
	v_add_f32_e32 v48, v160, v161
	ds_read_b128 v[92:95], v74 offset:12032
	ds_read_b128 v[96:99], v74 offset:12048
	ds_read_b128 v[100:103], v74 offset:12064
	ds_read_b128 v[104:107], v74 offset:12080
	ds_read_b128 v[108:111], v74 offset:12096
	ds_read_b128 v[112:115], v74 offset:12112
	ds_read_b128 v[116:119], v74 offset:12128
	ds_read_b128 v[120:123], v74 offset:12144
	ds_read_b128 v[124:127], v74 offset:12160
	ds_read_b128 v[134:137], v74 offset:12176
	ds_read_b128 v[138:141], v74 offset:12192
	ds_read_b128 v[142:145], v74 offset:12208
	s_waitcnt lgkmcnt(11)
	v_mul_f32_e32 v91, v2, v92
	v_fma_f32 v160, v49, v90, -v91
	v_fma_f32 v161, -v3, v93, 0
	v_pk_fma_f32 v[160:161], v[94:95], v[4:5], v[160:161] neg_lo:[1,0,0] neg_hi:[1,0,0]
	s_waitcnt lgkmcnt(10)
	v_pk_fma_f32 v[160:161], v[96:97], v[6:7], v[160:161] neg_lo:[1,0,0] neg_hi:[1,0,0]
	v_pk_fma_f32 v[160:161], v[98:99], v[8:9], v[160:161] neg_lo:[1,0,0] neg_hi:[1,0,0]
	s_waitcnt lgkmcnt(9)
	v_pk_fma_f32 v[160:161], v[100:101], v[10:11], v[160:161] neg_lo:[1,0,0] neg_hi:[1,0,0]
	v_pk_fma_f32 v[160:161], v[102:103], v[12:13], v[160:161] neg_lo:[1,0,0] neg_hi:[1,0,0]
	s_waitcnt lgkmcnt(8)
	v_pk_fma_f32 v[160:161], v[104:105], v[14:15], v[160:161] neg_lo:[1,0,0] neg_hi:[1,0,0]
	v_pk_fma_f32 v[160:161], v[106:107], v[16:17], v[160:161] neg_lo:[1,0,0] neg_hi:[1,0,0]
	s_waitcnt lgkmcnt(7)
	v_pk_fma_f32 v[160:161], v[108:109], v[18:19], v[160:161] neg_lo:[1,0,0] neg_hi:[1,0,0]
	v_pk_fma_f32 v[160:161], v[110:111], v[20:21], v[160:161] neg_lo:[1,0,0] neg_hi:[1,0,0]
	s_waitcnt lgkmcnt(6)
	v_pk_fma_f32 v[160:161], v[112:113], v[22:23], v[160:161] neg_lo:[1,0,0] neg_hi:[1,0,0]
	v_pk_fma_f32 v[160:161], v[114:115], v[24:25], v[160:161] neg_lo:[1,0,0] neg_hi:[1,0,0]
	s_waitcnt lgkmcnt(5)
	v_pk_fma_f32 v[160:161], v[116:117], v[26:27], v[160:161] neg_lo:[1,0,0] neg_hi:[1,0,0]
	v_pk_fma_f32 v[160:161], v[118:119], v[28:29], v[160:161] neg_lo:[1,0,0] neg_hi:[1,0,0]
	s_waitcnt lgkmcnt(4)
	v_pk_fma_f32 v[160:161], v[120:121], v[30:31], v[160:161] neg_lo:[1,0,0] neg_hi:[1,0,0]
	v_pk_fma_f32 v[160:161], v[122:123], v[32:33], v[160:161] neg_lo:[1,0,0] neg_hi:[1,0,0]
	s_waitcnt lgkmcnt(3)
	v_pk_fma_f32 v[160:161], v[124:125], v[34:35], v[160:161] neg_lo:[1,0,0] neg_hi:[1,0,0]
	v_pk_fma_f32 v[160:161], v[126:127], v[36:37], v[160:161] neg_lo:[1,0,0] neg_hi:[1,0,0]
	s_waitcnt lgkmcnt(2)
	v_pk_fma_f32 v[160:161], v[134:135], v[38:39], v[160:161] neg_lo:[1,0,0] neg_hi:[1,0,0]
	v_pk_fma_f32 v[160:161], v[136:137], v[40:41], v[160:161] neg_lo:[1,0,0] neg_hi:[1,0,0]
	s_waitcnt lgkmcnt(1)
	v_pk_fma_f32 v[160:161], v[138:139], v[42:43], v[160:161] neg_lo:[1,0,0] neg_hi:[1,0,0]
	v_pk_fma_f32 v[160:161], v[140:141], v[44:45], v[160:161] neg_lo:[1,0,0] neg_hi:[1,0,0]
	s_waitcnt lgkmcnt(0)
	v_pk_fma_f32 v[160:161], v[142:143], v[46:47], v[160:161] neg_lo:[1,0,0] neg_hi:[1,0,0]
	v_fma_f32 v160, -v48, v144, v160
	v_add_f32_e32 v49, v160, v161
	ds_read_b128 v[90:93], v74 offset:12288
	ds_read_b128 v[94:97], v74 offset:12304
	ds_read_b128 v[98:101], v74 offset:12320
	ds_read_b128 v[102:105], v74 offset:12336
	ds_read_b128 v[106:109], v74 offset:12352
	ds_read_b128 v[110:113], v74 offset:12368
	ds_read_b128 v[114:117], v74 offset:12384
	ds_read_b128 v[118:121], v74 offset:12400
	ds_read_b128 v[122:125], v74 offset:12416
	ds_read_b128 v[126:129], v74 offset:12432
	ds_read_b128 v[134:137], v74 offset:12448
	ds_read_b128 v[138:141], v74 offset:12464
	s_waitcnt lgkmcnt(11)
	v_mul_f32_e32 v90, v2, v90
	v_fma_f32 v160, v50, v89, -v90
	v_fma_f32 v161, -v3, v91, 0
	v_pk_fma_f32 v[160:161], v[92:93], v[4:5], v[160:161] neg_lo:[1,0,0] neg_hi:[1,0,0]
	s_waitcnt lgkmcnt(10)
	v_pk_fma_f32 v[160:161], v[94:95], v[6:7], v[160:161] neg_lo:[1,0,0] neg_hi:[1,0,0]
	v_pk_fma_f32 v[160:161], v[96:97], v[8:9], v[160:161] neg_lo:[1,0,0] neg_hi:[1,0,0]
	s_waitcnt lgkmcnt(9)
	v_pk_fma_f32 v[160:161], v[98:99], v[10:11], v[160:161] neg_lo:[1,0,0] neg_hi:[1,0,0]
	v_pk_fma_f32 v[160:161], v[100:101], v[12:13], v[160:161] neg_lo:[1,0,0] neg_hi:[1,0,0]
	s_waitcnt lgkmcnt(8)
	v_pk_fma_f32 v[160:161], v[102:103], v[14:15], v[160:161] neg_lo:[1,0,0] neg_hi:[1,0,0]
	v_pk_fma_f32 v[160:161], v[104:105], v[16:17], v[160:161] neg_lo:[1,0,0] neg_hi:[1,0,0]
	s_waitcnt lgkmcnt(7)
	v_pk_fma_f32 v[160:161], v[106:107], v[18:19], v[160:161] neg_lo:[1,0,0] neg_hi:[1,0,0]
	v_pk_fma_f32 v[160:161], v[108:109], v[20:21], v[160:161] neg_lo:[1,0,0] neg_hi:[1,0,0]
	s_waitcnt lgkmcnt(6)
	v_pk_fma_f32 v[160:161], v[110:111], v[22:23], v[160:161] neg_lo:[1,0,0] neg_hi:[1,0,0]
	v_pk_fma_f32 v[160:161], v[112:113], v[24:25], v[160:161] neg_lo:[1,0,0] neg_hi:[1,0,0]
	s_waitcnt lgkmcnt(5)
	v_pk_fma_f32 v[160:161], v[114:115], v[26:27], v[160:161] neg_lo:[1,0,0] neg_hi:[1,0,0]
	v_pk_fma_f32 v[160:161], v[116:117], v[28:29], v[160:161] neg_lo:[1,0,0] neg_hi:[1,0,0]
	s_waitcnt lgkmcnt(4)
	v_pk_fma_f32 v[160:161], v[118:119], v[30:31], v[160:161] neg_lo:[1,0,0] neg_hi:[1,0,0]
	v_pk_fma_f32 v[160:161], v[120:121], v[32:33], v[160:161] neg_lo:[1,0,0] neg_hi:[1,0,0]
	s_waitcnt lgkmcnt(3)
	v_pk_fma_f32 v[160:161], v[122:123], v[34:35], v[160:161] neg_lo:[1,0,0] neg_hi:[1,0,0]
	v_pk_fma_f32 v[160:161], v[124:125], v[36:37], v[160:161] neg_lo:[1,0,0] neg_hi:[1,0,0]
	s_waitcnt lgkmcnt(2)
	v_pk_fma_f32 v[160:161], v[126:127], v[38:39], v[160:161] neg_lo:[1,0,0] neg_hi:[1,0,0]
	v_pk_fma_f32 v[160:161], v[128:129], v[40:41], v[160:161] neg_lo:[1,0,0] neg_hi:[1,0,0]
	s_waitcnt lgkmcnt(1)
	v_pk_fma_f32 v[160:161], v[134:135], v[42:43], v[160:161] neg_lo:[1,0,0] neg_hi:[1,0,0]
	v_pk_fma_f32 v[160:161], v[136:137], v[44:45], v[160:161] neg_lo:[1,0,0] neg_hi:[1,0,0]
	s_waitcnt lgkmcnt(0)
	v_pk_fma_f32 v[160:161], v[138:139], v[46:47], v[160:161] neg_lo:[1,0,0] neg_hi:[1,0,0]
	v_pk_fma_f32 v[160:161], v[140:141], v[48:49], v[160:161] neg_lo:[1,0,0] neg_hi:[1,0,0]
	v_add_f32_e32 v50, v160, v161
	ds_read_b128 v[90:93], v74 offset:12544
	ds_read_b128 v[94:97], v74 offset:12560
	ds_read_b128 v[98:101], v74 offset:12576
	ds_read_b128 v[102:105], v74 offset:12592
	ds_read_b128 v[106:109], v74 offset:12608
	ds_read_b128 v[110:113], v74 offset:12624
	ds_read_b128 v[114:117], v74 offset:12640
	ds_read_b128 v[118:121], v74 offset:12656
	ds_read_b128 v[122:125], v74 offset:12672
	ds_read_b128 v[126:129], v74 offset:12688
	ds_read_b128 v[134:137], v74 offset:12704
	ds_read_b128 v[138:141], v74 offset:12720
	ds_read_b128 v[142:145], v74 offset:12736
	s_waitcnt lgkmcnt(12)
	v_mul_f32_e32 v89, v2, v90
	v_fma_f32 v160, v51, v88, -v89
	v_fma_f32 v161, -v3, v91, 0
	v_pk_fma_f32 v[160:161], v[92:93], v[4:5], v[160:161] neg_lo:[1,0,0] neg_hi:[1,0,0]
	s_waitcnt lgkmcnt(11)
	v_pk_fma_f32 v[160:161], v[94:95], v[6:7], v[160:161] neg_lo:[1,0,0] neg_hi:[1,0,0]
	v_pk_fma_f32 v[160:161], v[96:97], v[8:9], v[160:161] neg_lo:[1,0,0] neg_hi:[1,0,0]
	s_waitcnt lgkmcnt(10)
	v_pk_fma_f32 v[160:161], v[98:99], v[10:11], v[160:161] neg_lo:[1,0,0] neg_hi:[1,0,0]
	v_pk_fma_f32 v[160:161], v[100:101], v[12:13], v[160:161] neg_lo:[1,0,0] neg_hi:[1,0,0]
	s_waitcnt lgkmcnt(9)
	v_pk_fma_f32 v[160:161], v[102:103], v[14:15], v[160:161] neg_lo:[1,0,0] neg_hi:[1,0,0]
	v_pk_fma_f32 v[160:161], v[104:105], v[16:17], v[160:161] neg_lo:[1,0,0] neg_hi:[1,0,0]
	s_waitcnt lgkmcnt(8)
	v_pk_fma_f32 v[160:161], v[106:107], v[18:19], v[160:161] neg_lo:[1,0,0] neg_hi:[1,0,0]
	v_pk_fma_f32 v[160:161], v[108:109], v[20:21], v[160:161] neg_lo:[1,0,0] neg_hi:[1,0,0]
	s_waitcnt lgkmcnt(7)
	v_pk_fma_f32 v[160:161], v[110:111], v[22:23], v[160:161] neg_lo:[1,0,0] neg_hi:[1,0,0]
	v_pk_fma_f32 v[160:161], v[112:113], v[24:25], v[160:161] neg_lo:[1,0,0] neg_hi:[1,0,0]
	s_waitcnt lgkmcnt(6)
	v_pk_fma_f32 v[160:161], v[114:115], v[26:27], v[160:161] neg_lo:[1,0,0] neg_hi:[1,0,0]
	v_pk_fma_f32 v[160:161], v[116:117], v[28:29], v[160:161] neg_lo:[1,0,0] neg_hi:[1,0,0]
	s_waitcnt lgkmcnt(5)
	v_pk_fma_f32 v[160:161], v[118:119], v[30:31], v[160:161] neg_lo:[1,0,0] neg_hi:[1,0,0]
	v_pk_fma_f32 v[160:161], v[120:121], v[32:33], v[160:161] neg_lo:[1,0,0] neg_hi:[1,0,0]
	s_waitcnt lgkmcnt(4)
	v_pk_fma_f32 v[160:161], v[122:123], v[34:35], v[160:161] neg_lo:[1,0,0] neg_hi:[1,0,0]
	v_pk_fma_f32 v[160:161], v[124:125], v[36:37], v[160:161] neg_lo:[1,0,0] neg_hi:[1,0,0]
	s_waitcnt lgkmcnt(3)
	v_pk_fma_f32 v[160:161], v[126:127], v[38:39], v[160:161] neg_lo:[1,0,0] neg_hi:[1,0,0]
	v_pk_fma_f32 v[160:161], v[128:129], v[40:41], v[160:161] neg_lo:[1,0,0] neg_hi:[1,0,0]
	s_waitcnt lgkmcnt(2)
	v_pk_fma_f32 v[160:161], v[134:135], v[42:43], v[160:161] neg_lo:[1,0,0] neg_hi:[1,0,0]
	v_pk_fma_f32 v[160:161], v[136:137], v[44:45], v[160:161] neg_lo:[1,0,0] neg_hi:[1,0,0]
	s_waitcnt lgkmcnt(1)
	v_pk_fma_f32 v[160:161], v[138:139], v[46:47], v[160:161] neg_lo:[1,0,0] neg_hi:[1,0,0]
	v_pk_fma_f32 v[160:161], v[140:141], v[48:49], v[160:161] neg_lo:[1,0,0] neg_hi:[1,0,0]
	s_waitcnt lgkmcnt(0)
	v_fma_f32 v160, -v50, v142, v160
	v_add_f32_e32 v51, v160, v161
	ds_read_b128 v[88:91], v74 offset:12800
	ds_read_b128 v[92:95], v74 offset:12816
	ds_read_b128 v[96:99], v74 offset:12832
	ds_read_b128 v[100:103], v74 offset:12848
	ds_read_b128 v[104:107], v74 offset:12864
	ds_read_b128 v[108:111], v74 offset:12880
	ds_read_b128 v[112:115], v74 offset:12896
	ds_read_b128 v[116:119], v74 offset:12912
	ds_read_b128 v[120:123], v74 offset:12928
	ds_read_b128 v[124:127], v74 offset:12944
	ds_read_b128 v[134:137], v74 offset:12960
	ds_read_b128 v[138:141], v74 offset:12976
	ds_read_b128 v[142:145], v74 offset:12992
	s_waitcnt lgkmcnt(12)
	v_mul_f32_e32 v88, v2, v88
	v_fma_f32 v160, v52, v87, -v88
	v_fma_f32 v161, -v3, v89, 0
	v_pk_fma_f32 v[160:161], v[90:91], v[4:5], v[160:161] neg_lo:[1,0,0] neg_hi:[1,0,0]
	s_waitcnt lgkmcnt(11)
	v_pk_fma_f32 v[160:161], v[92:93], v[6:7], v[160:161] neg_lo:[1,0,0] neg_hi:[1,0,0]
	v_pk_fma_f32 v[160:161], v[94:95], v[8:9], v[160:161] neg_lo:[1,0,0] neg_hi:[1,0,0]
	s_waitcnt lgkmcnt(10)
	v_pk_fma_f32 v[160:161], v[96:97], v[10:11], v[160:161] neg_lo:[1,0,0] neg_hi:[1,0,0]
	v_pk_fma_f32 v[160:161], v[98:99], v[12:13], v[160:161] neg_lo:[1,0,0] neg_hi:[1,0,0]
	s_waitcnt lgkmcnt(9)
	v_pk_fma_f32 v[160:161], v[100:101], v[14:15], v[160:161] neg_lo:[1,0,0] neg_hi:[1,0,0]
	v_pk_fma_f32 v[160:161], v[102:103], v[16:17], v[160:161] neg_lo:[1,0,0] neg_hi:[1,0,0]
	s_waitcnt lgkmcnt(8)
	v_pk_fma_f32 v[160:161], v[104:105], v[18:19], v[160:161] neg_lo:[1,0,0] neg_hi:[1,0,0]
	v_pk_fma_f32 v[160:161], v[106:107], v[20:21], v[160:161] neg_lo:[1,0,0] neg_hi:[1,0,0]
	s_waitcnt lgkmcnt(7)
	v_pk_fma_f32 v[160:161], v[108:109], v[22:23], v[160:161] neg_lo:[1,0,0] neg_hi:[1,0,0]
	v_pk_fma_f32 v[160:161], v[110:111], v[24:25], v[160:161] neg_lo:[1,0,0] neg_hi:[1,0,0]
	s_waitcnt lgkmcnt(6)
	v_pk_fma_f32 v[160:161], v[112:113], v[26:27], v[160:161] neg_lo:[1,0,0] neg_hi:[1,0,0]
	v_pk_fma_f32 v[160:161], v[114:115], v[28:29], v[160:161] neg_lo:[1,0,0] neg_hi:[1,0,0]
	s_waitcnt lgkmcnt(5)
	v_pk_fma_f32 v[160:161], v[116:117], v[30:31], v[160:161] neg_lo:[1,0,0] neg_hi:[1,0,0]
	v_pk_fma_f32 v[160:161], v[118:119], v[32:33], v[160:161] neg_lo:[1,0,0] neg_hi:[1,0,0]
	s_waitcnt lgkmcnt(4)
	v_pk_fma_f32 v[160:161], v[120:121], v[34:35], v[160:161] neg_lo:[1,0,0] neg_hi:[1,0,0]
	v_pk_fma_f32 v[160:161], v[122:123], v[36:37], v[160:161] neg_lo:[1,0,0] neg_hi:[1,0,0]
	s_waitcnt lgkmcnt(3)
	v_pk_fma_f32 v[160:161], v[124:125], v[38:39], v[160:161] neg_lo:[1,0,0] neg_hi:[1,0,0]
	v_pk_fma_f32 v[160:161], v[126:127], v[40:41], v[160:161] neg_lo:[1,0,0] neg_hi:[1,0,0]
	s_waitcnt lgkmcnt(2)
	v_pk_fma_f32 v[160:161], v[134:135], v[42:43], v[160:161] neg_lo:[1,0,0] neg_hi:[1,0,0]
	v_pk_fma_f32 v[160:161], v[136:137], v[44:45], v[160:161] neg_lo:[1,0,0] neg_hi:[1,0,0]
	s_waitcnt lgkmcnt(1)
	v_pk_fma_f32 v[160:161], v[138:139], v[46:47], v[160:161] neg_lo:[1,0,0] neg_hi:[1,0,0]
	v_pk_fma_f32 v[160:161], v[140:141], v[48:49], v[160:161] neg_lo:[1,0,0] neg_hi:[1,0,0]
	s_waitcnt lgkmcnt(0)
	v_pk_fma_f32 v[160:161], v[142:143], v[50:51], v[160:161] neg_lo:[1,0,0] neg_hi:[1,0,0]
	v_add_f32_e32 v52, v160, v161
	ds_read_b128 v[88:91], v74 offset:13056
	ds_read_b128 v[92:95], v74 offset:13072
	ds_read_b128 v[96:99], v74 offset:13088
	ds_read_b128 v[100:103], v74 offset:13104
	ds_read_b128 v[104:107], v74 offset:13120
	ds_read_b128 v[108:111], v74 offset:13136
	ds_read_b128 v[112:115], v74 offset:13152
	ds_read_b128 v[116:119], v74 offset:13168
	ds_read_b128 v[120:123], v74 offset:13184
	ds_read_b128 v[124:127], v74 offset:13200
	ds_read_b128 v[134:137], v74 offset:13216
	ds_read_b128 v[138:141], v74 offset:13232
	ds_read_b128 v[142:145], v74 offset:13248
	s_waitcnt lgkmcnt(12)
	v_mul_f32_e32 v87, v2, v88
	v_fma_f32 v160, v53, v86, -v87
	v_fma_f32 v161, -v3, v89, 0
	v_pk_fma_f32 v[160:161], v[90:91], v[4:5], v[160:161] neg_lo:[1,0,0] neg_hi:[1,0,0]
	s_waitcnt lgkmcnt(11)
	v_pk_fma_f32 v[160:161], v[92:93], v[6:7], v[160:161] neg_lo:[1,0,0] neg_hi:[1,0,0]
	v_pk_fma_f32 v[160:161], v[94:95], v[8:9], v[160:161] neg_lo:[1,0,0] neg_hi:[1,0,0]
	s_waitcnt lgkmcnt(10)
	v_pk_fma_f32 v[160:161], v[96:97], v[10:11], v[160:161] neg_lo:[1,0,0] neg_hi:[1,0,0]
	v_pk_fma_f32 v[160:161], v[98:99], v[12:13], v[160:161] neg_lo:[1,0,0] neg_hi:[1,0,0]
	s_waitcnt lgkmcnt(9)
	v_pk_fma_f32 v[160:161], v[100:101], v[14:15], v[160:161] neg_lo:[1,0,0] neg_hi:[1,0,0]
	v_pk_fma_f32 v[160:161], v[102:103], v[16:17], v[160:161] neg_lo:[1,0,0] neg_hi:[1,0,0]
	s_waitcnt lgkmcnt(8)
	v_pk_fma_f32 v[160:161], v[104:105], v[18:19], v[160:161] neg_lo:[1,0,0] neg_hi:[1,0,0]
	v_pk_fma_f32 v[160:161], v[106:107], v[20:21], v[160:161] neg_lo:[1,0,0] neg_hi:[1,0,0]
	s_waitcnt lgkmcnt(7)
	v_pk_fma_f32 v[160:161], v[108:109], v[22:23], v[160:161] neg_lo:[1,0,0] neg_hi:[1,0,0]
	v_pk_fma_f32 v[160:161], v[110:111], v[24:25], v[160:161] neg_lo:[1,0,0] neg_hi:[1,0,0]
	s_waitcnt lgkmcnt(6)
	v_pk_fma_f32 v[160:161], v[112:113], v[26:27], v[160:161] neg_lo:[1,0,0] neg_hi:[1,0,0]
	v_pk_fma_f32 v[160:161], v[114:115], v[28:29], v[160:161] neg_lo:[1,0,0] neg_hi:[1,0,0]
	s_waitcnt lgkmcnt(5)
	v_pk_fma_f32 v[160:161], v[116:117], v[30:31], v[160:161] neg_lo:[1,0,0] neg_hi:[1,0,0]
	v_pk_fma_f32 v[160:161], v[118:119], v[32:33], v[160:161] neg_lo:[1,0,0] neg_hi:[1,0,0]
	s_waitcnt lgkmcnt(4)
	v_pk_fma_f32 v[160:161], v[120:121], v[34:35], v[160:161] neg_lo:[1,0,0] neg_hi:[1,0,0]
	v_pk_fma_f32 v[160:161], v[122:123], v[36:37], v[160:161] neg_lo:[1,0,0] neg_hi:[1,0,0]
	s_waitcnt lgkmcnt(3)
	v_pk_fma_f32 v[160:161], v[124:125], v[38:39], v[160:161] neg_lo:[1,0,0] neg_hi:[1,0,0]
	v_pk_fma_f32 v[160:161], v[126:127], v[40:41], v[160:161] neg_lo:[1,0,0] neg_hi:[1,0,0]
	s_waitcnt lgkmcnt(2)
	v_pk_fma_f32 v[160:161], v[134:135], v[42:43], v[160:161] neg_lo:[1,0,0] neg_hi:[1,0,0]
	v_pk_fma_f32 v[160:161], v[136:137], v[44:45], v[160:161] neg_lo:[1,0,0] neg_hi:[1,0,0]
	s_waitcnt lgkmcnt(1)
	v_pk_fma_f32 v[160:161], v[138:139], v[46:47], v[160:161] neg_lo:[1,0,0] neg_hi:[1,0,0]
	v_pk_fma_f32 v[160:161], v[140:141], v[48:49], v[160:161] neg_lo:[1,0,0] neg_hi:[1,0,0]
	s_waitcnt lgkmcnt(0)
	v_pk_fma_f32 v[160:161], v[142:143], v[50:51], v[160:161] neg_lo:[1,0,0] neg_hi:[1,0,0]
	v_fma_f32 v160, -v52, v144, v160
	v_add_f32_e32 v53, v160, v161
	ds_read_b128 v[86:89], v74 offset:13312
	ds_read_b128 v[90:93], v74 offset:13328
	ds_read_b128 v[94:97], v74 offset:13344
	ds_read_b128 v[98:101], v74 offset:13360
	ds_read_b128 v[102:105], v74 offset:13376
	ds_read_b128 v[106:109], v74 offset:13392
	ds_read_b128 v[110:113], v74 offset:13408
	ds_read_b128 v[114:117], v74 offset:13424
	ds_read_b128 v[118:121], v74 offset:13440
	ds_read_b128 v[122:125], v74 offset:13456
	ds_read_b128 v[126:129], v74 offset:13472
	ds_read_b128 v[134:137], v74 offset:13488
	ds_read_b128 v[138:141], v74 offset:13504
	s_waitcnt lgkmcnt(12)
	v_mul_f32_e32 v86, v2, v86
	v_fma_f32 v160, v54, v85, -v86
	v_fma_f32 v161, -v3, v87, 0
	v_pk_fma_f32 v[160:161], v[88:89], v[4:5], v[160:161] neg_lo:[1,0,0] neg_hi:[1,0,0]
	s_waitcnt lgkmcnt(11)
	v_pk_fma_f32 v[160:161], v[90:91], v[6:7], v[160:161] neg_lo:[1,0,0] neg_hi:[1,0,0]
	v_pk_fma_f32 v[160:161], v[92:93], v[8:9], v[160:161] neg_lo:[1,0,0] neg_hi:[1,0,0]
	s_waitcnt lgkmcnt(10)
	v_pk_fma_f32 v[160:161], v[94:95], v[10:11], v[160:161] neg_lo:[1,0,0] neg_hi:[1,0,0]
	v_pk_fma_f32 v[160:161], v[96:97], v[12:13], v[160:161] neg_lo:[1,0,0] neg_hi:[1,0,0]
	s_waitcnt lgkmcnt(9)
	v_pk_fma_f32 v[160:161], v[98:99], v[14:15], v[160:161] neg_lo:[1,0,0] neg_hi:[1,0,0]
	v_pk_fma_f32 v[160:161], v[100:101], v[16:17], v[160:161] neg_lo:[1,0,0] neg_hi:[1,0,0]
	s_waitcnt lgkmcnt(8)
	v_pk_fma_f32 v[160:161], v[102:103], v[18:19], v[160:161] neg_lo:[1,0,0] neg_hi:[1,0,0]
	v_pk_fma_f32 v[160:161], v[104:105], v[20:21], v[160:161] neg_lo:[1,0,0] neg_hi:[1,0,0]
	s_waitcnt lgkmcnt(7)
	v_pk_fma_f32 v[160:161], v[106:107], v[22:23], v[160:161] neg_lo:[1,0,0] neg_hi:[1,0,0]
	v_pk_fma_f32 v[160:161], v[108:109], v[24:25], v[160:161] neg_lo:[1,0,0] neg_hi:[1,0,0]
	s_waitcnt lgkmcnt(6)
	v_pk_fma_f32 v[160:161], v[110:111], v[26:27], v[160:161] neg_lo:[1,0,0] neg_hi:[1,0,0]
	v_pk_fma_f32 v[160:161], v[112:113], v[28:29], v[160:161] neg_lo:[1,0,0] neg_hi:[1,0,0]
	s_waitcnt lgkmcnt(5)
	v_pk_fma_f32 v[160:161], v[114:115], v[30:31], v[160:161] neg_lo:[1,0,0] neg_hi:[1,0,0]
	v_pk_fma_f32 v[160:161], v[116:117], v[32:33], v[160:161] neg_lo:[1,0,0] neg_hi:[1,0,0]
	s_waitcnt lgkmcnt(4)
	v_pk_fma_f32 v[160:161], v[118:119], v[34:35], v[160:161] neg_lo:[1,0,0] neg_hi:[1,0,0]
	v_pk_fma_f32 v[160:161], v[120:121], v[36:37], v[160:161] neg_lo:[1,0,0] neg_hi:[1,0,0]
	s_waitcnt lgkmcnt(3)
	v_pk_fma_f32 v[160:161], v[122:123], v[38:39], v[160:161] neg_lo:[1,0,0] neg_hi:[1,0,0]
	v_pk_fma_f32 v[160:161], v[124:125], v[40:41], v[160:161] neg_lo:[1,0,0] neg_hi:[1,0,0]
	s_waitcnt lgkmcnt(2)
	v_pk_fma_f32 v[160:161], v[126:127], v[42:43], v[160:161] neg_lo:[1,0,0] neg_hi:[1,0,0]
	v_pk_fma_f32 v[160:161], v[128:129], v[44:45], v[160:161] neg_lo:[1,0,0] neg_hi:[1,0,0]
	s_waitcnt lgkmcnt(1)
	v_pk_fma_f32 v[160:161], v[134:135], v[46:47], v[160:161] neg_lo:[1,0,0] neg_hi:[1,0,0]
	v_pk_fma_f32 v[160:161], v[136:137], v[48:49], v[160:161] neg_lo:[1,0,0] neg_hi:[1,0,0]
	s_waitcnt lgkmcnt(0)
	v_pk_fma_f32 v[160:161], v[138:139], v[50:51], v[160:161] neg_lo:[1,0,0] neg_hi:[1,0,0]
	v_pk_fma_f32 v[160:161], v[140:141], v[52:53], v[160:161] neg_lo:[1,0,0] neg_hi:[1,0,0]
	v_add_f32_e32 v54, v160, v161
	ds_read_b128 v[86:89], v74 offset:13568
	ds_read_b128 v[90:93], v74 offset:13584
	ds_read_b128 v[94:97], v74 offset:13600
	ds_read_b128 v[98:101], v74 offset:13616
	ds_read_b128 v[102:105], v74 offset:13632
	ds_read_b128 v[106:109], v74 offset:13648
	ds_read_b128 v[110:113], v74 offset:13664
	ds_read_b128 v[114:117], v74 offset:13680
	ds_read_b128 v[118:121], v74 offset:13696
	ds_read_b128 v[122:125], v74 offset:13712
	ds_read_b128 v[126:129], v74 offset:13728
	ds_read_b128 v[134:137], v74 offset:13744
	ds_read_b128 v[138:141], v74 offset:13760
	ds_read_b128 v[142:145], v74 offset:13776
	s_waitcnt lgkmcnt(13)
	v_mul_f32_e32 v85, v2, v86
	v_fma_f32 v160, v55, v84, -v85
	v_fma_f32 v161, -v3, v87, 0
	v_pk_fma_f32 v[160:161], v[88:89], v[4:5], v[160:161] neg_lo:[1,0,0] neg_hi:[1,0,0]
	s_waitcnt lgkmcnt(12)
	v_pk_fma_f32 v[160:161], v[90:91], v[6:7], v[160:161] neg_lo:[1,0,0] neg_hi:[1,0,0]
	v_pk_fma_f32 v[160:161], v[92:93], v[8:9], v[160:161] neg_lo:[1,0,0] neg_hi:[1,0,0]
	s_waitcnt lgkmcnt(11)
	v_pk_fma_f32 v[160:161], v[94:95], v[10:11], v[160:161] neg_lo:[1,0,0] neg_hi:[1,0,0]
	v_pk_fma_f32 v[160:161], v[96:97], v[12:13], v[160:161] neg_lo:[1,0,0] neg_hi:[1,0,0]
	s_waitcnt lgkmcnt(10)
	v_pk_fma_f32 v[160:161], v[98:99], v[14:15], v[160:161] neg_lo:[1,0,0] neg_hi:[1,0,0]
	v_pk_fma_f32 v[160:161], v[100:101], v[16:17], v[160:161] neg_lo:[1,0,0] neg_hi:[1,0,0]
	s_waitcnt lgkmcnt(9)
	v_pk_fma_f32 v[160:161], v[102:103], v[18:19], v[160:161] neg_lo:[1,0,0] neg_hi:[1,0,0]
	v_pk_fma_f32 v[160:161], v[104:105], v[20:21], v[160:161] neg_lo:[1,0,0] neg_hi:[1,0,0]
	s_waitcnt lgkmcnt(8)
	v_pk_fma_f32 v[160:161], v[106:107], v[22:23], v[160:161] neg_lo:[1,0,0] neg_hi:[1,0,0]
	v_pk_fma_f32 v[160:161], v[108:109], v[24:25], v[160:161] neg_lo:[1,0,0] neg_hi:[1,0,0]
	s_waitcnt lgkmcnt(7)
	v_pk_fma_f32 v[160:161], v[110:111], v[26:27], v[160:161] neg_lo:[1,0,0] neg_hi:[1,0,0]
	v_pk_fma_f32 v[160:161], v[112:113], v[28:29], v[160:161] neg_lo:[1,0,0] neg_hi:[1,0,0]
	s_waitcnt lgkmcnt(6)
	v_pk_fma_f32 v[160:161], v[114:115], v[30:31], v[160:161] neg_lo:[1,0,0] neg_hi:[1,0,0]
	v_pk_fma_f32 v[160:161], v[116:117], v[32:33], v[160:161] neg_lo:[1,0,0] neg_hi:[1,0,0]
	s_waitcnt lgkmcnt(5)
	v_pk_fma_f32 v[160:161], v[118:119], v[34:35], v[160:161] neg_lo:[1,0,0] neg_hi:[1,0,0]
	v_pk_fma_f32 v[160:161], v[120:121], v[36:37], v[160:161] neg_lo:[1,0,0] neg_hi:[1,0,0]
	s_waitcnt lgkmcnt(4)
	v_pk_fma_f32 v[160:161], v[122:123], v[38:39], v[160:161] neg_lo:[1,0,0] neg_hi:[1,0,0]
	v_pk_fma_f32 v[160:161], v[124:125], v[40:41], v[160:161] neg_lo:[1,0,0] neg_hi:[1,0,0]
	s_waitcnt lgkmcnt(3)
	v_pk_fma_f32 v[160:161], v[126:127], v[42:43], v[160:161] neg_lo:[1,0,0] neg_hi:[1,0,0]
	v_pk_fma_f32 v[160:161], v[128:129], v[44:45], v[160:161] neg_lo:[1,0,0] neg_hi:[1,0,0]
	s_waitcnt lgkmcnt(2)
	v_pk_fma_f32 v[160:161], v[134:135], v[46:47], v[160:161] neg_lo:[1,0,0] neg_hi:[1,0,0]
	v_pk_fma_f32 v[160:161], v[136:137], v[48:49], v[160:161] neg_lo:[1,0,0] neg_hi:[1,0,0]
	s_waitcnt lgkmcnt(1)
	v_pk_fma_f32 v[160:161], v[138:139], v[50:51], v[160:161] neg_lo:[1,0,0] neg_hi:[1,0,0]
	v_pk_fma_f32 v[160:161], v[140:141], v[52:53], v[160:161] neg_lo:[1,0,0] neg_hi:[1,0,0]
	s_waitcnt lgkmcnt(0)
	v_fma_f32 v160, -v54, v142, v160
	v_add_f32_e32 v55, v160, v161
	ds_read_b128 v[84:87], v74 offset:13824
	ds_read_b128 v[88:91], v74 offset:13840
	ds_read_b128 v[92:95], v74 offset:13856
	ds_read_b128 v[96:99], v74 offset:13872
	ds_read_b128 v[100:103], v74 offset:13888
	ds_read_b128 v[104:107], v74 offset:13904
	ds_read_b128 v[108:111], v74 offset:13920
	ds_read_b128 v[112:115], v74 offset:13936
	ds_read_b128 v[116:119], v74 offset:13952
	ds_read_b128 v[120:123], v74 offset:13968
	ds_read_b128 v[124:127], v74 offset:13984
	ds_read_b128 v[134:137], v74 offset:14000
	ds_read_b128 v[138:141], v74 offset:14016
	ds_read_b128 v[142:145], v74 offset:14032
	s_waitcnt lgkmcnt(13)
	v_mul_f32_e32 v84, v2, v84
	v_fma_f32 v160, v56, v83, -v84
	v_fma_f32 v161, -v3, v85, 0
	v_pk_fma_f32 v[160:161], v[86:87], v[4:5], v[160:161] neg_lo:[1,0,0] neg_hi:[1,0,0]
	s_waitcnt lgkmcnt(12)
	v_pk_fma_f32 v[160:161], v[88:89], v[6:7], v[160:161] neg_lo:[1,0,0] neg_hi:[1,0,0]
	v_pk_fma_f32 v[160:161], v[90:91], v[8:9], v[160:161] neg_lo:[1,0,0] neg_hi:[1,0,0]
	s_waitcnt lgkmcnt(11)
	v_pk_fma_f32 v[160:161], v[92:93], v[10:11], v[160:161] neg_lo:[1,0,0] neg_hi:[1,0,0]
	v_pk_fma_f32 v[160:161], v[94:95], v[12:13], v[160:161] neg_lo:[1,0,0] neg_hi:[1,0,0]
	s_waitcnt lgkmcnt(10)
	v_pk_fma_f32 v[160:161], v[96:97], v[14:15], v[160:161] neg_lo:[1,0,0] neg_hi:[1,0,0]
	v_pk_fma_f32 v[160:161], v[98:99], v[16:17], v[160:161] neg_lo:[1,0,0] neg_hi:[1,0,0]
	s_waitcnt lgkmcnt(9)
	v_pk_fma_f32 v[160:161], v[100:101], v[18:19], v[160:161] neg_lo:[1,0,0] neg_hi:[1,0,0]
	v_pk_fma_f32 v[160:161], v[102:103], v[20:21], v[160:161] neg_lo:[1,0,0] neg_hi:[1,0,0]
	s_waitcnt lgkmcnt(8)
	v_pk_fma_f32 v[160:161], v[104:105], v[22:23], v[160:161] neg_lo:[1,0,0] neg_hi:[1,0,0]
	v_pk_fma_f32 v[160:161], v[106:107], v[24:25], v[160:161] neg_lo:[1,0,0] neg_hi:[1,0,0]
	s_waitcnt lgkmcnt(7)
	v_pk_fma_f32 v[160:161], v[108:109], v[26:27], v[160:161] neg_lo:[1,0,0] neg_hi:[1,0,0]
	v_pk_fma_f32 v[160:161], v[110:111], v[28:29], v[160:161] neg_lo:[1,0,0] neg_hi:[1,0,0]
	s_waitcnt lgkmcnt(6)
	v_pk_fma_f32 v[160:161], v[112:113], v[30:31], v[160:161] neg_lo:[1,0,0] neg_hi:[1,0,0]
	v_pk_fma_f32 v[160:161], v[114:115], v[32:33], v[160:161] neg_lo:[1,0,0] neg_hi:[1,0,0]
	s_waitcnt lgkmcnt(5)
	v_pk_fma_f32 v[160:161], v[116:117], v[34:35], v[160:161] neg_lo:[1,0,0] neg_hi:[1,0,0]
	v_pk_fma_f32 v[160:161], v[118:119], v[36:37], v[160:161] neg_lo:[1,0,0] neg_hi:[1,0,0]
	s_waitcnt lgkmcnt(4)
	v_pk_fma_f32 v[160:161], v[120:121], v[38:39], v[160:161] neg_lo:[1,0,0] neg_hi:[1,0,0]
	v_pk_fma_f32 v[160:161], v[122:123], v[40:41], v[160:161] neg_lo:[1,0,0] neg_hi:[1,0,0]
	s_waitcnt lgkmcnt(3)
	v_pk_fma_f32 v[160:161], v[124:125], v[42:43], v[160:161] neg_lo:[1,0,0] neg_hi:[1,0,0]
	v_pk_fma_f32 v[160:161], v[126:127], v[44:45], v[160:161] neg_lo:[1,0,0] neg_hi:[1,0,0]
	s_waitcnt lgkmcnt(2)
	v_pk_fma_f32 v[160:161], v[134:135], v[46:47], v[160:161] neg_lo:[1,0,0] neg_hi:[1,0,0]
	v_pk_fma_f32 v[160:161], v[136:137], v[48:49], v[160:161] neg_lo:[1,0,0] neg_hi:[1,0,0]
	s_waitcnt lgkmcnt(1)
	v_pk_fma_f32 v[160:161], v[138:139], v[50:51], v[160:161] neg_lo:[1,0,0] neg_hi:[1,0,0]
	v_pk_fma_f32 v[160:161], v[140:141], v[52:53], v[160:161] neg_lo:[1,0,0] neg_hi:[1,0,0]
	s_waitcnt lgkmcnt(0)
	v_pk_fma_f32 v[160:161], v[142:143], v[54:55], v[160:161] neg_lo:[1,0,0] neg_hi:[1,0,0]
	v_add_f32_e32 v56, v160, v161
	ds_read_b128 v[84:87], v74 offset:14080
	ds_read_b128 v[88:91], v74 offset:14096
	ds_read_b128 v[92:95], v74 offset:14112
	ds_read_b128 v[96:99], v74 offset:14128
	ds_read_b128 v[100:103], v74 offset:14144
	ds_read_b128 v[104:107], v74 offset:14160
	ds_read_b128 v[108:111], v74 offset:14176
	ds_read_b128 v[112:115], v74 offset:14192
	ds_read_b128 v[116:119], v74 offset:14208
	ds_read_b128 v[120:123], v74 offset:14224
	ds_read_b128 v[124:127], v74 offset:14240
	ds_read_b128 v[134:137], v74 offset:14256
	ds_read_b128 v[138:141], v74 offset:14272
	ds_read_b128 v[142:145], v74 offset:14288
	s_waitcnt lgkmcnt(13)
	v_mul_f32_e32 v83, v2, v84
	v_fma_f32 v160, v57, v82, -v83
	v_fma_f32 v161, -v3, v85, 0
	v_pk_fma_f32 v[160:161], v[86:87], v[4:5], v[160:161] neg_lo:[1,0,0] neg_hi:[1,0,0]
	s_waitcnt lgkmcnt(12)
	v_pk_fma_f32 v[160:161], v[88:89], v[6:7], v[160:161] neg_lo:[1,0,0] neg_hi:[1,0,0]
	v_pk_fma_f32 v[160:161], v[90:91], v[8:9], v[160:161] neg_lo:[1,0,0] neg_hi:[1,0,0]
	s_waitcnt lgkmcnt(11)
	v_pk_fma_f32 v[160:161], v[92:93], v[10:11], v[160:161] neg_lo:[1,0,0] neg_hi:[1,0,0]
	v_pk_fma_f32 v[160:161], v[94:95], v[12:13], v[160:161] neg_lo:[1,0,0] neg_hi:[1,0,0]
	s_waitcnt lgkmcnt(10)
	v_pk_fma_f32 v[160:161], v[96:97], v[14:15], v[160:161] neg_lo:[1,0,0] neg_hi:[1,0,0]
	v_pk_fma_f32 v[160:161], v[98:99], v[16:17], v[160:161] neg_lo:[1,0,0] neg_hi:[1,0,0]
	s_waitcnt lgkmcnt(9)
	v_pk_fma_f32 v[160:161], v[100:101], v[18:19], v[160:161] neg_lo:[1,0,0] neg_hi:[1,0,0]
	v_pk_fma_f32 v[160:161], v[102:103], v[20:21], v[160:161] neg_lo:[1,0,0] neg_hi:[1,0,0]
	s_waitcnt lgkmcnt(8)
	v_pk_fma_f32 v[160:161], v[104:105], v[22:23], v[160:161] neg_lo:[1,0,0] neg_hi:[1,0,0]
	v_pk_fma_f32 v[160:161], v[106:107], v[24:25], v[160:161] neg_lo:[1,0,0] neg_hi:[1,0,0]
	s_waitcnt lgkmcnt(7)
	v_pk_fma_f32 v[160:161], v[108:109], v[26:27], v[160:161] neg_lo:[1,0,0] neg_hi:[1,0,0]
	v_pk_fma_f32 v[160:161], v[110:111], v[28:29], v[160:161] neg_lo:[1,0,0] neg_hi:[1,0,0]
	s_waitcnt lgkmcnt(6)
	v_pk_fma_f32 v[160:161], v[112:113], v[30:31], v[160:161] neg_lo:[1,0,0] neg_hi:[1,0,0]
	v_pk_fma_f32 v[160:161], v[114:115], v[32:33], v[160:161] neg_lo:[1,0,0] neg_hi:[1,0,0]
	s_waitcnt lgkmcnt(5)
	v_pk_fma_f32 v[160:161], v[116:117], v[34:35], v[160:161] neg_lo:[1,0,0] neg_hi:[1,0,0]
	v_pk_fma_f32 v[160:161], v[118:119], v[36:37], v[160:161] neg_lo:[1,0,0] neg_hi:[1,0,0]
	s_waitcnt lgkmcnt(4)
	v_pk_fma_f32 v[160:161], v[120:121], v[38:39], v[160:161] neg_lo:[1,0,0] neg_hi:[1,0,0]
	v_pk_fma_f32 v[160:161], v[122:123], v[40:41], v[160:161] neg_lo:[1,0,0] neg_hi:[1,0,0]
	s_waitcnt lgkmcnt(3)
	v_pk_fma_f32 v[160:161], v[124:125], v[42:43], v[160:161] neg_lo:[1,0,0] neg_hi:[1,0,0]
	v_pk_fma_f32 v[160:161], v[126:127], v[44:45], v[160:161] neg_lo:[1,0,0] neg_hi:[1,0,0]
	s_waitcnt lgkmcnt(2)
	v_pk_fma_f32 v[160:161], v[134:135], v[46:47], v[160:161] neg_lo:[1,0,0] neg_hi:[1,0,0]
	v_pk_fma_f32 v[160:161], v[136:137], v[48:49], v[160:161] neg_lo:[1,0,0] neg_hi:[1,0,0]
	s_waitcnt lgkmcnt(1)
	v_pk_fma_f32 v[160:161], v[138:139], v[50:51], v[160:161] neg_lo:[1,0,0] neg_hi:[1,0,0]
	v_pk_fma_f32 v[160:161], v[140:141], v[52:53], v[160:161] neg_lo:[1,0,0] neg_hi:[1,0,0]
	s_waitcnt lgkmcnt(0)
	v_pk_fma_f32 v[160:161], v[142:143], v[54:55], v[160:161] neg_lo:[1,0,0] neg_hi:[1,0,0]
	v_fma_f32 v160, -v56, v144, v160
	v_add_f32_e32 v57, v160, v161
	ds_read_b128 v[82:85], v74 offset:14336
	ds_read_b128 v[86:89], v74 offset:14352
	ds_read_b128 v[90:93], v74 offset:14368
	ds_read_b128 v[94:97], v74 offset:14384
	ds_read_b128 v[98:101], v74 offset:14400
	ds_read_b128 v[102:105], v74 offset:14416
	ds_read_b128 v[106:109], v74 offset:14432
	ds_read_b128 v[110:113], v74 offset:14448
	ds_read_b128 v[114:117], v74 offset:14464
	ds_read_b128 v[118:121], v74 offset:14480
	ds_read_b128 v[122:125], v74 offset:14496
	ds_read_b128 v[126:129], v74 offset:14512
	ds_read_b128 v[134:137], v74 offset:14528
	ds_read_b128 v[138:141], v74 offset:14544
	s_waitcnt lgkmcnt(13)
	v_mul_f32_e32 v82, v2, v82
	v_fma_f32 v160, v58, v81, -v82
	v_fma_f32 v161, -v3, v83, 0
	v_pk_fma_f32 v[160:161], v[84:85], v[4:5], v[160:161] neg_lo:[1,0,0] neg_hi:[1,0,0]
	s_waitcnt lgkmcnt(12)
	v_pk_fma_f32 v[160:161], v[86:87], v[6:7], v[160:161] neg_lo:[1,0,0] neg_hi:[1,0,0]
	v_pk_fma_f32 v[160:161], v[88:89], v[8:9], v[160:161] neg_lo:[1,0,0] neg_hi:[1,0,0]
	s_waitcnt lgkmcnt(11)
	v_pk_fma_f32 v[160:161], v[90:91], v[10:11], v[160:161] neg_lo:[1,0,0] neg_hi:[1,0,0]
	v_pk_fma_f32 v[160:161], v[92:93], v[12:13], v[160:161] neg_lo:[1,0,0] neg_hi:[1,0,0]
	s_waitcnt lgkmcnt(10)
	v_pk_fma_f32 v[160:161], v[94:95], v[14:15], v[160:161] neg_lo:[1,0,0] neg_hi:[1,0,0]
	v_pk_fma_f32 v[160:161], v[96:97], v[16:17], v[160:161] neg_lo:[1,0,0] neg_hi:[1,0,0]
	s_waitcnt lgkmcnt(9)
	v_pk_fma_f32 v[160:161], v[98:99], v[18:19], v[160:161] neg_lo:[1,0,0] neg_hi:[1,0,0]
	v_pk_fma_f32 v[160:161], v[100:101], v[20:21], v[160:161] neg_lo:[1,0,0] neg_hi:[1,0,0]
	s_waitcnt lgkmcnt(8)
	v_pk_fma_f32 v[160:161], v[102:103], v[22:23], v[160:161] neg_lo:[1,0,0] neg_hi:[1,0,0]
	v_pk_fma_f32 v[160:161], v[104:105], v[24:25], v[160:161] neg_lo:[1,0,0] neg_hi:[1,0,0]
	s_waitcnt lgkmcnt(7)
	v_pk_fma_f32 v[160:161], v[106:107], v[26:27], v[160:161] neg_lo:[1,0,0] neg_hi:[1,0,0]
	v_pk_fma_f32 v[160:161], v[108:109], v[28:29], v[160:161] neg_lo:[1,0,0] neg_hi:[1,0,0]
	s_waitcnt lgkmcnt(6)
	v_pk_fma_f32 v[160:161], v[110:111], v[30:31], v[160:161] neg_lo:[1,0,0] neg_hi:[1,0,0]
	v_pk_fma_f32 v[160:161], v[112:113], v[32:33], v[160:161] neg_lo:[1,0,0] neg_hi:[1,0,0]
	s_waitcnt lgkmcnt(5)
	v_pk_fma_f32 v[160:161], v[114:115], v[34:35], v[160:161] neg_lo:[1,0,0] neg_hi:[1,0,0]
	v_pk_fma_f32 v[160:161], v[116:117], v[36:37], v[160:161] neg_lo:[1,0,0] neg_hi:[1,0,0]
	s_waitcnt lgkmcnt(4)
	v_pk_fma_f32 v[160:161], v[118:119], v[38:39], v[160:161] neg_lo:[1,0,0] neg_hi:[1,0,0]
	v_pk_fma_f32 v[160:161], v[120:121], v[40:41], v[160:161] neg_lo:[1,0,0] neg_hi:[1,0,0]
	s_waitcnt lgkmcnt(3)
	v_pk_fma_f32 v[160:161], v[122:123], v[42:43], v[160:161] neg_lo:[1,0,0] neg_hi:[1,0,0]
	v_pk_fma_f32 v[160:161], v[124:125], v[44:45], v[160:161] neg_lo:[1,0,0] neg_hi:[1,0,0]
	s_waitcnt lgkmcnt(2)
	v_pk_fma_f32 v[160:161], v[126:127], v[46:47], v[160:161] neg_lo:[1,0,0] neg_hi:[1,0,0]
	v_pk_fma_f32 v[160:161], v[128:129], v[48:49], v[160:161] neg_lo:[1,0,0] neg_hi:[1,0,0]
	s_waitcnt lgkmcnt(1)
	v_pk_fma_f32 v[160:161], v[134:135], v[50:51], v[160:161] neg_lo:[1,0,0] neg_hi:[1,0,0]
	v_pk_fma_f32 v[160:161], v[136:137], v[52:53], v[160:161] neg_lo:[1,0,0] neg_hi:[1,0,0]
	s_waitcnt lgkmcnt(0)
	v_pk_fma_f32 v[160:161], v[138:139], v[54:55], v[160:161] neg_lo:[1,0,0] neg_hi:[1,0,0]
	v_pk_fma_f32 v[160:161], v[140:141], v[56:57], v[160:161] neg_lo:[1,0,0] neg_hi:[1,0,0]
	v_add_f32_e32 v58, v160, v161
	ds_read_b128 v[82:85], v74 offset:14592
	ds_read_b128 v[86:89], v74 offset:14608
	ds_read_b128 v[90:93], v74 offset:14624
	ds_read_b128 v[94:97], v74 offset:14640
	ds_read_b128 v[98:101], v74 offset:14656
	ds_read_b128 v[102:105], v74 offset:14672
	ds_read_b128 v[106:109], v74 offset:14688
	ds_read_b128 v[110:113], v74 offset:14704
	ds_read_b128 v[114:117], v74 offset:14720
	ds_read_b128 v[118:121], v74 offset:14736
	ds_read_b128 v[122:125], v74 offset:14752
	ds_read_b128 v[126:129], v74 offset:14768
	ds_read_b128 v[134:137], v74 offset:14784
	ds_read_b128 v[138:141], v74 offset:14800
	ds_read_b128 v[142:145], v74 offset:14816
	s_waitcnt lgkmcnt(14)
	v_mul_f32_e32 v81, v2, v82
	v_fma_f32 v160, v59, v80, -v81
	v_fma_f32 v161, -v3, v83, 0
	v_pk_fma_f32 v[160:161], v[84:85], v[4:5], v[160:161] neg_lo:[1,0,0] neg_hi:[1,0,0]
	s_waitcnt lgkmcnt(13)
	v_pk_fma_f32 v[160:161], v[86:87], v[6:7], v[160:161] neg_lo:[1,0,0] neg_hi:[1,0,0]
	v_pk_fma_f32 v[160:161], v[88:89], v[8:9], v[160:161] neg_lo:[1,0,0] neg_hi:[1,0,0]
	s_waitcnt lgkmcnt(12)
	v_pk_fma_f32 v[160:161], v[90:91], v[10:11], v[160:161] neg_lo:[1,0,0] neg_hi:[1,0,0]
	v_pk_fma_f32 v[160:161], v[92:93], v[12:13], v[160:161] neg_lo:[1,0,0] neg_hi:[1,0,0]
	s_waitcnt lgkmcnt(11)
	v_pk_fma_f32 v[160:161], v[94:95], v[14:15], v[160:161] neg_lo:[1,0,0] neg_hi:[1,0,0]
	v_pk_fma_f32 v[160:161], v[96:97], v[16:17], v[160:161] neg_lo:[1,0,0] neg_hi:[1,0,0]
	s_waitcnt lgkmcnt(10)
	v_pk_fma_f32 v[160:161], v[98:99], v[18:19], v[160:161] neg_lo:[1,0,0] neg_hi:[1,0,0]
	v_pk_fma_f32 v[160:161], v[100:101], v[20:21], v[160:161] neg_lo:[1,0,0] neg_hi:[1,0,0]
	s_waitcnt lgkmcnt(9)
	v_pk_fma_f32 v[160:161], v[102:103], v[22:23], v[160:161] neg_lo:[1,0,0] neg_hi:[1,0,0]
	v_pk_fma_f32 v[160:161], v[104:105], v[24:25], v[160:161] neg_lo:[1,0,0] neg_hi:[1,0,0]
	s_waitcnt lgkmcnt(8)
	v_pk_fma_f32 v[160:161], v[106:107], v[26:27], v[160:161] neg_lo:[1,0,0] neg_hi:[1,0,0]
	v_pk_fma_f32 v[160:161], v[108:109], v[28:29], v[160:161] neg_lo:[1,0,0] neg_hi:[1,0,0]
	s_waitcnt lgkmcnt(7)
	v_pk_fma_f32 v[160:161], v[110:111], v[30:31], v[160:161] neg_lo:[1,0,0] neg_hi:[1,0,0]
	v_pk_fma_f32 v[160:161], v[112:113], v[32:33], v[160:161] neg_lo:[1,0,0] neg_hi:[1,0,0]
	s_waitcnt lgkmcnt(6)
	v_pk_fma_f32 v[160:161], v[114:115], v[34:35], v[160:161] neg_lo:[1,0,0] neg_hi:[1,0,0]
	v_pk_fma_f32 v[160:161], v[116:117], v[36:37], v[160:161] neg_lo:[1,0,0] neg_hi:[1,0,0]
	s_waitcnt lgkmcnt(5)
	v_pk_fma_f32 v[160:161], v[118:119], v[38:39], v[160:161] neg_lo:[1,0,0] neg_hi:[1,0,0]
	v_pk_fma_f32 v[160:161], v[120:121], v[40:41], v[160:161] neg_lo:[1,0,0] neg_hi:[1,0,0]
	s_waitcnt lgkmcnt(4)
	v_pk_fma_f32 v[160:161], v[122:123], v[42:43], v[160:161] neg_lo:[1,0,0] neg_hi:[1,0,0]
	v_pk_fma_f32 v[160:161], v[124:125], v[44:45], v[160:161] neg_lo:[1,0,0] neg_hi:[1,0,0]
	s_waitcnt lgkmcnt(3)
	v_pk_fma_f32 v[160:161], v[126:127], v[46:47], v[160:161] neg_lo:[1,0,0] neg_hi:[1,0,0]
	v_pk_fma_f32 v[160:161], v[128:129], v[48:49], v[160:161] neg_lo:[1,0,0] neg_hi:[1,0,0]
	s_waitcnt lgkmcnt(2)
	v_pk_fma_f32 v[160:161], v[134:135], v[50:51], v[160:161] neg_lo:[1,0,0] neg_hi:[1,0,0]
	v_pk_fma_f32 v[160:161], v[136:137], v[52:53], v[160:161] neg_lo:[1,0,0] neg_hi:[1,0,0]
	s_waitcnt lgkmcnt(1)
	v_pk_fma_f32 v[160:161], v[138:139], v[54:55], v[160:161] neg_lo:[1,0,0] neg_hi:[1,0,0]
	v_pk_fma_f32 v[160:161], v[140:141], v[56:57], v[160:161] neg_lo:[1,0,0] neg_hi:[1,0,0]
	s_waitcnt lgkmcnt(0)
	v_fma_f32 v160, -v58, v142, v160
	v_add_f32_e32 v59, v160, v161
	ds_read_b128 v[80:83], v74 offset:14848
	ds_read_b128 v[84:87], v74 offset:14864
	ds_read_b128 v[88:91], v74 offset:14880
	ds_read_b128 v[92:95], v74 offset:14896
	ds_read_b128 v[96:99], v74 offset:14912
	ds_read_b128 v[100:103], v74 offset:14928
	ds_read_b128 v[104:107], v74 offset:14944
	ds_read_b128 v[108:111], v74 offset:14960
	ds_read_b128 v[112:115], v74 offset:14976
	ds_read_b128 v[116:119], v74 offset:14992
	ds_read_b128 v[120:123], v74 offset:15008
	ds_read_b128 v[124:127], v74 offset:15024
	ds_read_b128 v[134:137], v74 offset:15040
	ds_read_b128 v[138:141], v74 offset:15056
	ds_read_b128 v[142:145], v74 offset:15072
	s_waitcnt lgkmcnt(14)
	v_mul_f32_e32 v80, v2, v80
	v_fma_f32 v160, v60, v79, -v80
	v_fma_f32 v161, -v3, v81, 0
	v_pk_fma_f32 v[160:161], v[82:83], v[4:5], v[160:161] neg_lo:[1,0,0] neg_hi:[1,0,0]
	s_waitcnt lgkmcnt(13)
	v_pk_fma_f32 v[160:161], v[84:85], v[6:7], v[160:161] neg_lo:[1,0,0] neg_hi:[1,0,0]
	v_pk_fma_f32 v[160:161], v[86:87], v[8:9], v[160:161] neg_lo:[1,0,0] neg_hi:[1,0,0]
	s_waitcnt lgkmcnt(12)
	v_pk_fma_f32 v[160:161], v[88:89], v[10:11], v[160:161] neg_lo:[1,0,0] neg_hi:[1,0,0]
	v_pk_fma_f32 v[160:161], v[90:91], v[12:13], v[160:161] neg_lo:[1,0,0] neg_hi:[1,0,0]
	s_waitcnt lgkmcnt(11)
	v_pk_fma_f32 v[160:161], v[92:93], v[14:15], v[160:161] neg_lo:[1,0,0] neg_hi:[1,0,0]
	v_pk_fma_f32 v[160:161], v[94:95], v[16:17], v[160:161] neg_lo:[1,0,0] neg_hi:[1,0,0]
	s_waitcnt lgkmcnt(10)
	v_pk_fma_f32 v[160:161], v[96:97], v[18:19], v[160:161] neg_lo:[1,0,0] neg_hi:[1,0,0]
	v_pk_fma_f32 v[160:161], v[98:99], v[20:21], v[160:161] neg_lo:[1,0,0] neg_hi:[1,0,0]
	s_waitcnt lgkmcnt(9)
	v_pk_fma_f32 v[160:161], v[100:101], v[22:23], v[160:161] neg_lo:[1,0,0] neg_hi:[1,0,0]
	v_pk_fma_f32 v[160:161], v[102:103], v[24:25], v[160:161] neg_lo:[1,0,0] neg_hi:[1,0,0]
	s_waitcnt lgkmcnt(8)
	v_pk_fma_f32 v[160:161], v[104:105], v[26:27], v[160:161] neg_lo:[1,0,0] neg_hi:[1,0,0]
	v_pk_fma_f32 v[160:161], v[106:107], v[28:29], v[160:161] neg_lo:[1,0,0] neg_hi:[1,0,0]
	s_waitcnt lgkmcnt(7)
	v_pk_fma_f32 v[160:161], v[108:109], v[30:31], v[160:161] neg_lo:[1,0,0] neg_hi:[1,0,0]
	v_pk_fma_f32 v[160:161], v[110:111], v[32:33], v[160:161] neg_lo:[1,0,0] neg_hi:[1,0,0]
	s_waitcnt lgkmcnt(6)
	v_pk_fma_f32 v[160:161], v[112:113], v[34:35], v[160:161] neg_lo:[1,0,0] neg_hi:[1,0,0]
	v_pk_fma_f32 v[160:161], v[114:115], v[36:37], v[160:161] neg_lo:[1,0,0] neg_hi:[1,0,0]
	s_waitcnt lgkmcnt(5)
	v_pk_fma_f32 v[160:161], v[116:117], v[38:39], v[160:161] neg_lo:[1,0,0] neg_hi:[1,0,0]
	v_pk_fma_f32 v[160:161], v[118:119], v[40:41], v[160:161] neg_lo:[1,0,0] neg_hi:[1,0,0]
	s_waitcnt lgkmcnt(4)
	v_pk_fma_f32 v[160:161], v[120:121], v[42:43], v[160:161] neg_lo:[1,0,0] neg_hi:[1,0,0]
	v_pk_fma_f32 v[160:161], v[122:123], v[44:45], v[160:161] neg_lo:[1,0,0] neg_hi:[1,0,0]
	s_waitcnt lgkmcnt(3)
	v_pk_fma_f32 v[160:161], v[124:125], v[46:47], v[160:161] neg_lo:[1,0,0] neg_hi:[1,0,0]
	v_pk_fma_f32 v[160:161], v[126:127], v[48:49], v[160:161] neg_lo:[1,0,0] neg_hi:[1,0,0]
	s_waitcnt lgkmcnt(2)
	v_pk_fma_f32 v[160:161], v[134:135], v[50:51], v[160:161] neg_lo:[1,0,0] neg_hi:[1,0,0]
	v_pk_fma_f32 v[160:161], v[136:137], v[52:53], v[160:161] neg_lo:[1,0,0] neg_hi:[1,0,0]
	s_waitcnt lgkmcnt(1)
	v_pk_fma_f32 v[160:161], v[138:139], v[54:55], v[160:161] neg_lo:[1,0,0] neg_hi:[1,0,0]
	v_pk_fma_f32 v[160:161], v[140:141], v[56:57], v[160:161] neg_lo:[1,0,0] neg_hi:[1,0,0]
	s_waitcnt lgkmcnt(0)
	v_pk_fma_f32 v[160:161], v[142:143], v[58:59], v[160:161] neg_lo:[1,0,0] neg_hi:[1,0,0]
	v_add_f32_e32 v60, v160, v161
	ds_read_b128 v[80:83], v74 offset:15104
	ds_read_b128 v[84:87], v74 offset:15120
	ds_read_b128 v[88:91], v74 offset:15136
	ds_read_b128 v[92:95], v74 offset:15152
	ds_read_b128 v[96:99], v74 offset:15168
	ds_read_b128 v[100:103], v74 offset:15184
	ds_read_b128 v[104:107], v74 offset:15200
	ds_read_b128 v[108:111], v74 offset:15216
	ds_read_b128 v[112:115], v74 offset:15232
	ds_read_b128 v[116:119], v74 offset:15248
	ds_read_b128 v[120:123], v74 offset:15264
	ds_read_b128 v[124:127], v74 offset:15280
	ds_read_b128 v[134:137], v74 offset:15296
	ds_read_b128 v[138:141], v74 offset:15312
	ds_read_b128 v[142:145], v74 offset:15328
	s_waitcnt lgkmcnt(14)
	v_mul_f32_e32 v79, v2, v80
	v_fma_f32 v160, v61, v78, -v79
	v_fma_f32 v161, -v3, v81, 0
	v_pk_fma_f32 v[160:161], v[82:83], v[4:5], v[160:161] neg_lo:[1,0,0] neg_hi:[1,0,0]
	s_waitcnt lgkmcnt(13)
	v_pk_fma_f32 v[160:161], v[84:85], v[6:7], v[160:161] neg_lo:[1,0,0] neg_hi:[1,0,0]
	v_pk_fma_f32 v[160:161], v[86:87], v[8:9], v[160:161] neg_lo:[1,0,0] neg_hi:[1,0,0]
	s_waitcnt lgkmcnt(12)
	v_pk_fma_f32 v[160:161], v[88:89], v[10:11], v[160:161] neg_lo:[1,0,0] neg_hi:[1,0,0]
	v_pk_fma_f32 v[160:161], v[90:91], v[12:13], v[160:161] neg_lo:[1,0,0] neg_hi:[1,0,0]
	s_waitcnt lgkmcnt(11)
	v_pk_fma_f32 v[160:161], v[92:93], v[14:15], v[160:161] neg_lo:[1,0,0] neg_hi:[1,0,0]
	v_pk_fma_f32 v[160:161], v[94:95], v[16:17], v[160:161] neg_lo:[1,0,0] neg_hi:[1,0,0]
	s_waitcnt lgkmcnt(10)
	v_pk_fma_f32 v[160:161], v[96:97], v[18:19], v[160:161] neg_lo:[1,0,0] neg_hi:[1,0,0]
	v_pk_fma_f32 v[160:161], v[98:99], v[20:21], v[160:161] neg_lo:[1,0,0] neg_hi:[1,0,0]
	s_waitcnt lgkmcnt(9)
	v_pk_fma_f32 v[160:161], v[100:101], v[22:23], v[160:161] neg_lo:[1,0,0] neg_hi:[1,0,0]
	v_pk_fma_f32 v[160:161], v[102:103], v[24:25], v[160:161] neg_lo:[1,0,0] neg_hi:[1,0,0]
	s_waitcnt lgkmcnt(8)
	v_pk_fma_f32 v[160:161], v[104:105], v[26:27], v[160:161] neg_lo:[1,0,0] neg_hi:[1,0,0]
	v_pk_fma_f32 v[160:161], v[106:107], v[28:29], v[160:161] neg_lo:[1,0,0] neg_hi:[1,0,0]
	s_waitcnt lgkmcnt(7)
	v_pk_fma_f32 v[160:161], v[108:109], v[30:31], v[160:161] neg_lo:[1,0,0] neg_hi:[1,0,0]
	v_pk_fma_f32 v[160:161], v[110:111], v[32:33], v[160:161] neg_lo:[1,0,0] neg_hi:[1,0,0]
	s_waitcnt lgkmcnt(6)
	v_pk_fma_f32 v[160:161], v[112:113], v[34:35], v[160:161] neg_lo:[1,0,0] neg_hi:[1,0,0]
	v_pk_fma_f32 v[160:161], v[114:115], v[36:37], v[160:161] neg_lo:[1,0,0] neg_hi:[1,0,0]
	s_waitcnt lgkmcnt(5)
	v_pk_fma_f32 v[160:161], v[116:117], v[38:39], v[160:161] neg_lo:[1,0,0] neg_hi:[1,0,0]
	v_pk_fma_f32 v[160:161], v[118:119], v[40:41], v[160:161] neg_lo:[1,0,0] neg_hi:[1,0,0]
	s_waitcnt lgkmcnt(4)
	v_pk_fma_f32 v[160:161], v[120:121], v[42:43], v[160:161] neg_lo:[1,0,0] neg_hi:[1,0,0]
	v_pk_fma_f32 v[160:161], v[122:123], v[44:45], v[160:161] neg_lo:[1,0,0] neg_hi:[1,0,0]
	s_waitcnt lgkmcnt(3)
	v_pk_fma_f32 v[160:161], v[124:125], v[46:47], v[160:161] neg_lo:[1,0,0] neg_hi:[1,0,0]
	v_pk_fma_f32 v[160:161], v[126:127], v[48:49], v[160:161] neg_lo:[1,0,0] neg_hi:[1,0,0]
	s_waitcnt lgkmcnt(2)
	v_pk_fma_f32 v[160:161], v[134:135], v[50:51], v[160:161] neg_lo:[1,0,0] neg_hi:[1,0,0]
	v_pk_fma_f32 v[160:161], v[136:137], v[52:53], v[160:161] neg_lo:[1,0,0] neg_hi:[1,0,0]
	s_waitcnt lgkmcnt(1)
	v_pk_fma_f32 v[160:161], v[138:139], v[54:55], v[160:161] neg_lo:[1,0,0] neg_hi:[1,0,0]
	v_pk_fma_f32 v[160:161], v[140:141], v[56:57], v[160:161] neg_lo:[1,0,0] neg_hi:[1,0,0]
	s_waitcnt lgkmcnt(0)
	v_pk_fma_f32 v[160:161], v[142:143], v[58:59], v[160:161] neg_lo:[1,0,0] neg_hi:[1,0,0]
	v_fma_f32 v160, -v60, v144, v160
	v_add_f32_e32 v61, v160, v161
	ds_read_b128 v[78:81], v74 offset:15360
	ds_read_b128 v[82:85], v74 offset:15376
	ds_read_b128 v[86:89], v74 offset:15392
	ds_read_b128 v[90:93], v74 offset:15408
	ds_read_b128 v[94:97], v74 offset:15424
	ds_read_b128 v[98:101], v74 offset:15440
	ds_read_b128 v[102:105], v74 offset:15456
	ds_read_b128 v[106:109], v74 offset:15472
	ds_read_b128 v[110:113], v74 offset:15488
	ds_read_b128 v[114:117], v74 offset:15504
	ds_read_b128 v[118:121], v74 offset:15520
	ds_read_b128 v[122:125], v74 offset:15536
	ds_read_b128 v[126:129], v74 offset:15552
	ds_read_b128 v[134:137], v74 offset:15568
	ds_read_b128 v[138:141], v74 offset:15584
	s_waitcnt lgkmcnt(14)
	v_mul_f32_e32 v78, v2, v78
	v_fma_f32 v160, v62, v77, -v78
	v_fma_f32 v161, -v3, v79, 0
	v_pk_fma_f32 v[160:161], v[80:81], v[4:5], v[160:161] neg_lo:[1,0,0] neg_hi:[1,0,0]
	s_waitcnt lgkmcnt(13)
	v_pk_fma_f32 v[160:161], v[82:83], v[6:7], v[160:161] neg_lo:[1,0,0] neg_hi:[1,0,0]
	v_pk_fma_f32 v[160:161], v[84:85], v[8:9], v[160:161] neg_lo:[1,0,0] neg_hi:[1,0,0]
	s_waitcnt lgkmcnt(12)
	v_pk_fma_f32 v[160:161], v[86:87], v[10:11], v[160:161] neg_lo:[1,0,0] neg_hi:[1,0,0]
	v_pk_fma_f32 v[160:161], v[88:89], v[12:13], v[160:161] neg_lo:[1,0,0] neg_hi:[1,0,0]
	s_waitcnt lgkmcnt(11)
	v_pk_fma_f32 v[160:161], v[90:91], v[14:15], v[160:161] neg_lo:[1,0,0] neg_hi:[1,0,0]
	v_pk_fma_f32 v[160:161], v[92:93], v[16:17], v[160:161] neg_lo:[1,0,0] neg_hi:[1,0,0]
	s_waitcnt lgkmcnt(10)
	v_pk_fma_f32 v[160:161], v[94:95], v[18:19], v[160:161] neg_lo:[1,0,0] neg_hi:[1,0,0]
	v_pk_fma_f32 v[160:161], v[96:97], v[20:21], v[160:161] neg_lo:[1,0,0] neg_hi:[1,0,0]
	s_waitcnt lgkmcnt(9)
	v_pk_fma_f32 v[160:161], v[98:99], v[22:23], v[160:161] neg_lo:[1,0,0] neg_hi:[1,0,0]
	v_pk_fma_f32 v[160:161], v[100:101], v[24:25], v[160:161] neg_lo:[1,0,0] neg_hi:[1,0,0]
	s_waitcnt lgkmcnt(8)
	v_pk_fma_f32 v[160:161], v[102:103], v[26:27], v[160:161] neg_lo:[1,0,0] neg_hi:[1,0,0]
	v_pk_fma_f32 v[160:161], v[104:105], v[28:29], v[160:161] neg_lo:[1,0,0] neg_hi:[1,0,0]
	s_waitcnt lgkmcnt(7)
	v_pk_fma_f32 v[160:161], v[106:107], v[30:31], v[160:161] neg_lo:[1,0,0] neg_hi:[1,0,0]
	v_pk_fma_f32 v[160:161], v[108:109], v[32:33], v[160:161] neg_lo:[1,0,0] neg_hi:[1,0,0]
	s_waitcnt lgkmcnt(6)
	v_pk_fma_f32 v[160:161], v[110:111], v[34:35], v[160:161] neg_lo:[1,0,0] neg_hi:[1,0,0]
	v_pk_fma_f32 v[160:161], v[112:113], v[36:37], v[160:161] neg_lo:[1,0,0] neg_hi:[1,0,0]
	s_waitcnt lgkmcnt(5)
	v_pk_fma_f32 v[160:161], v[114:115], v[38:39], v[160:161] neg_lo:[1,0,0] neg_hi:[1,0,0]
	v_pk_fma_f32 v[160:161], v[116:117], v[40:41], v[160:161] neg_lo:[1,0,0] neg_hi:[1,0,0]
	s_waitcnt lgkmcnt(4)
	v_pk_fma_f32 v[160:161], v[118:119], v[42:43], v[160:161] neg_lo:[1,0,0] neg_hi:[1,0,0]
	v_pk_fma_f32 v[160:161], v[120:121], v[44:45], v[160:161] neg_lo:[1,0,0] neg_hi:[1,0,0]
	s_waitcnt lgkmcnt(3)
	v_pk_fma_f32 v[160:161], v[122:123], v[46:47], v[160:161] neg_lo:[1,0,0] neg_hi:[1,0,0]
	v_pk_fma_f32 v[160:161], v[124:125], v[48:49], v[160:161] neg_lo:[1,0,0] neg_hi:[1,0,0]
	s_waitcnt lgkmcnt(2)
	v_pk_fma_f32 v[160:161], v[126:127], v[50:51], v[160:161] neg_lo:[1,0,0] neg_hi:[1,0,0]
	v_pk_fma_f32 v[160:161], v[128:129], v[52:53], v[160:161] neg_lo:[1,0,0] neg_hi:[1,0,0]
	s_waitcnt lgkmcnt(1)
	v_pk_fma_f32 v[160:161], v[134:135], v[54:55], v[160:161] neg_lo:[1,0,0] neg_hi:[1,0,0]
	v_pk_fma_f32 v[160:161], v[136:137], v[56:57], v[160:161] neg_lo:[1,0,0] neg_hi:[1,0,0]
	s_waitcnt lgkmcnt(0)
	v_pk_fma_f32 v[160:161], v[138:139], v[58:59], v[160:161] neg_lo:[1,0,0] neg_hi:[1,0,0]
	v_pk_fma_f32 v[160:161], v[140:141], v[60:61], v[160:161] neg_lo:[1,0,0] neg_hi:[1,0,0]
	v_add_f32_e32 v62, v160, v161
	ds_read_b128 v[78:81], v74 offset:15616
	ds_read_b128 v[82:85], v74 offset:15632
	ds_read_b128 v[86:89], v74 offset:15648
	ds_read_b128 v[90:93], v74 offset:15664
	ds_read_b128 v[94:97], v74 offset:15680
	ds_read_b128 v[98:101], v74 offset:15696
	ds_read_b128 v[102:105], v74 offset:15712
	ds_read_b128 v[106:109], v74 offset:15728
	ds_read_b128 v[110:113], v74 offset:15744
	ds_read_b128 v[114:117], v74 offset:15760
	ds_read_b128 v[118:121], v74 offset:15776
	ds_read_b128 v[122:125], v74 offset:15792
	ds_read_b128 v[126:129], v74 offset:15808
	ds_read_b128 v[134:137], v74 offset:15824
	ds_read_b128 v[138:141], v74 offset:15840
	ds_read_b128 v[142:145], v74 offset:15856
	s_waitcnt lgkmcnt(15)
	v_mul_f32_e32 v77, v2, v78
	v_fma_f32 v160, v63, v76, -v77
	v_fma_f32 v161, -v3, v79, 0
	v_pk_fma_f32 v[160:161], v[80:81], v[4:5], v[160:161] neg_lo:[1,0,0] neg_hi:[1,0,0]
	s_waitcnt lgkmcnt(14)
	v_pk_fma_f32 v[160:161], v[82:83], v[6:7], v[160:161] neg_lo:[1,0,0] neg_hi:[1,0,0]
	v_pk_fma_f32 v[160:161], v[84:85], v[8:9], v[160:161] neg_lo:[1,0,0] neg_hi:[1,0,0]
	s_waitcnt lgkmcnt(13)
	v_pk_fma_f32 v[160:161], v[86:87], v[10:11], v[160:161] neg_lo:[1,0,0] neg_hi:[1,0,0]
	v_pk_fma_f32 v[160:161], v[88:89], v[12:13], v[160:161] neg_lo:[1,0,0] neg_hi:[1,0,0]
	s_waitcnt lgkmcnt(12)
	v_pk_fma_f32 v[160:161], v[90:91], v[14:15], v[160:161] neg_lo:[1,0,0] neg_hi:[1,0,0]
	v_pk_fma_f32 v[160:161], v[92:93], v[16:17], v[160:161] neg_lo:[1,0,0] neg_hi:[1,0,0]
	s_waitcnt lgkmcnt(11)
	v_pk_fma_f32 v[160:161], v[94:95], v[18:19], v[160:161] neg_lo:[1,0,0] neg_hi:[1,0,0]
	v_pk_fma_f32 v[160:161], v[96:97], v[20:21], v[160:161] neg_lo:[1,0,0] neg_hi:[1,0,0]
	s_waitcnt lgkmcnt(10)
	v_pk_fma_f32 v[160:161], v[98:99], v[22:23], v[160:161] neg_lo:[1,0,0] neg_hi:[1,0,0]
	v_pk_fma_f32 v[160:161], v[100:101], v[24:25], v[160:161] neg_lo:[1,0,0] neg_hi:[1,0,0]
	s_waitcnt lgkmcnt(9)
	v_pk_fma_f32 v[160:161], v[102:103], v[26:27], v[160:161] neg_lo:[1,0,0] neg_hi:[1,0,0]
	v_pk_fma_f32 v[160:161], v[104:105], v[28:29], v[160:161] neg_lo:[1,0,0] neg_hi:[1,0,0]
	s_waitcnt lgkmcnt(8)
	v_pk_fma_f32 v[160:161], v[106:107], v[30:31], v[160:161] neg_lo:[1,0,0] neg_hi:[1,0,0]
	v_pk_fma_f32 v[160:161], v[108:109], v[32:33], v[160:161] neg_lo:[1,0,0] neg_hi:[1,0,0]
	s_waitcnt lgkmcnt(7)
	v_pk_fma_f32 v[160:161], v[110:111], v[34:35], v[160:161] neg_lo:[1,0,0] neg_hi:[1,0,0]
	v_pk_fma_f32 v[160:161], v[112:113], v[36:37], v[160:161] neg_lo:[1,0,0] neg_hi:[1,0,0]
	s_waitcnt lgkmcnt(6)
	v_pk_fma_f32 v[160:161], v[114:115], v[38:39], v[160:161] neg_lo:[1,0,0] neg_hi:[1,0,0]
	v_pk_fma_f32 v[160:161], v[116:117], v[40:41], v[160:161] neg_lo:[1,0,0] neg_hi:[1,0,0]
	s_waitcnt lgkmcnt(5)
	v_pk_fma_f32 v[160:161], v[118:119], v[42:43], v[160:161] neg_lo:[1,0,0] neg_hi:[1,0,0]
	v_pk_fma_f32 v[160:161], v[120:121], v[44:45], v[160:161] neg_lo:[1,0,0] neg_hi:[1,0,0]
	s_waitcnt lgkmcnt(4)
	v_pk_fma_f32 v[160:161], v[122:123], v[46:47], v[160:161] neg_lo:[1,0,0] neg_hi:[1,0,0]
	v_pk_fma_f32 v[160:161], v[124:125], v[48:49], v[160:161] neg_lo:[1,0,0] neg_hi:[1,0,0]
	s_waitcnt lgkmcnt(3)
	v_pk_fma_f32 v[160:161], v[126:127], v[50:51], v[160:161] neg_lo:[1,0,0] neg_hi:[1,0,0]
	v_pk_fma_f32 v[160:161], v[128:129], v[52:53], v[160:161] neg_lo:[1,0,0] neg_hi:[1,0,0]
	s_waitcnt lgkmcnt(2)
	v_pk_fma_f32 v[160:161], v[134:135], v[54:55], v[160:161] neg_lo:[1,0,0] neg_hi:[1,0,0]
	v_pk_fma_f32 v[160:161], v[136:137], v[56:57], v[160:161] neg_lo:[1,0,0] neg_hi:[1,0,0]
	s_waitcnt lgkmcnt(1)
	v_pk_fma_f32 v[160:161], v[138:139], v[58:59], v[160:161] neg_lo:[1,0,0] neg_hi:[1,0,0]
	v_pk_fma_f32 v[160:161], v[140:141], v[60:61], v[160:161] neg_lo:[1,0,0] neg_hi:[1,0,0]
	s_waitcnt lgkmcnt(0)
	v_fma_f32 v160, -v62, v142, v160
	v_add_f32_e32 v63, v160, v161
	ds_read_b128 v[76:79], v74 offset:15872
	ds_read_b128 v[80:83], v74 offset:15888
	ds_read_b128 v[84:87], v74 offset:15904
	ds_read_b128 v[88:91], v74 offset:15920
	ds_read_b128 v[92:95], v74 offset:15936
	ds_read_b128 v[96:99], v74 offset:15952
	ds_read_b128 v[100:103], v74 offset:15968
	ds_read_b128 v[104:107], v74 offset:15984
	ds_read_b128 v[108:111], v74 offset:16000
	ds_read_b128 v[112:115], v74 offset:16016
	ds_read_b128 v[116:119], v74 offset:16032
	ds_read_b128 v[120:123], v74 offset:16048
	ds_read_b128 v[124:127], v74 offset:16064
	ds_read_b128 v[134:137], v74 offset:16080
	ds_read_b128 v[138:141], v74 offset:16096
	ds_read_b128 v[142:145], v74 offset:16112
	s_waitcnt lgkmcnt(15)
	v_mul_f32_e32 v76, v2, v76
	v_fma_f32 v160, v64, v75, -v76
	v_fma_f32 v161, -v3, v77, 0
	v_pk_fma_f32 v[160:161], v[78:79], v[4:5], v[160:161] neg_lo:[1,0,0] neg_hi:[1,0,0]
	s_waitcnt lgkmcnt(14)
	v_pk_fma_f32 v[160:161], v[80:81], v[6:7], v[160:161] neg_lo:[1,0,0] neg_hi:[1,0,0]
	v_pk_fma_f32 v[160:161], v[82:83], v[8:9], v[160:161] neg_lo:[1,0,0] neg_hi:[1,0,0]
	s_waitcnt lgkmcnt(13)
	v_pk_fma_f32 v[160:161], v[84:85], v[10:11], v[160:161] neg_lo:[1,0,0] neg_hi:[1,0,0]
	v_pk_fma_f32 v[160:161], v[86:87], v[12:13], v[160:161] neg_lo:[1,0,0] neg_hi:[1,0,0]
	s_waitcnt lgkmcnt(12)
	v_pk_fma_f32 v[160:161], v[88:89], v[14:15], v[160:161] neg_lo:[1,0,0] neg_hi:[1,0,0]
	v_pk_fma_f32 v[160:161], v[90:91], v[16:17], v[160:161] neg_lo:[1,0,0] neg_hi:[1,0,0]
	s_waitcnt lgkmcnt(11)
	v_pk_fma_f32 v[160:161], v[92:93], v[18:19], v[160:161] neg_lo:[1,0,0] neg_hi:[1,0,0]
	v_pk_fma_f32 v[160:161], v[94:95], v[20:21], v[160:161] neg_lo:[1,0,0] neg_hi:[1,0,0]
	s_waitcnt lgkmcnt(10)
	v_pk_fma_f32 v[160:161], v[96:97], v[22:23], v[160:161] neg_lo:[1,0,0] neg_hi:[1,0,0]
	v_pk_fma_f32 v[160:161], v[98:99], v[24:25], v[160:161] neg_lo:[1,0,0] neg_hi:[1,0,0]
	s_waitcnt lgkmcnt(9)
	v_pk_fma_f32 v[160:161], v[100:101], v[26:27], v[160:161] neg_lo:[1,0,0] neg_hi:[1,0,0]
	v_pk_fma_f32 v[160:161], v[102:103], v[28:29], v[160:161] neg_lo:[1,0,0] neg_hi:[1,0,0]
	s_waitcnt lgkmcnt(8)
	v_pk_fma_f32 v[160:161], v[104:105], v[30:31], v[160:161] neg_lo:[1,0,0] neg_hi:[1,0,0]
	v_pk_fma_f32 v[160:161], v[106:107], v[32:33], v[160:161] neg_lo:[1,0,0] neg_hi:[1,0,0]
	s_waitcnt lgkmcnt(7)
	v_pk_fma_f32 v[160:161], v[108:109], v[34:35], v[160:161] neg_lo:[1,0,0] neg_hi:[1,0,0]
	v_pk_fma_f32 v[160:161], v[110:111], v[36:37], v[160:161] neg_lo:[1,0,0] neg_hi:[1,0,0]
	s_waitcnt lgkmcnt(6)
	v_pk_fma_f32 v[160:161], v[112:113], v[38:39], v[160:161] neg_lo:[1,0,0] neg_hi:[1,0,0]
	v_pk_fma_f32 v[160:161], v[114:115], v[40:41], v[160:161] neg_lo:[1,0,0] neg_hi:[1,0,0]
	s_waitcnt lgkmcnt(5)
	v_pk_fma_f32 v[160:161], v[116:117], v[42:43], v[160:161] neg_lo:[1,0,0] neg_hi:[1,0,0]
	v_pk_fma_f32 v[160:161], v[118:119], v[44:45], v[160:161] neg_lo:[1,0,0] neg_hi:[1,0,0]
	s_waitcnt lgkmcnt(4)
	v_pk_fma_f32 v[160:161], v[120:121], v[46:47], v[160:161] neg_lo:[1,0,0] neg_hi:[1,0,0]
	v_pk_fma_f32 v[160:161], v[122:123], v[48:49], v[160:161] neg_lo:[1,0,0] neg_hi:[1,0,0]
	s_waitcnt lgkmcnt(3)
	v_pk_fma_f32 v[160:161], v[124:125], v[50:51], v[160:161] neg_lo:[1,0,0] neg_hi:[1,0,0]
	v_pk_fma_f32 v[160:161], v[126:127], v[52:53], v[160:161] neg_lo:[1,0,0] neg_hi:[1,0,0]
	s_waitcnt lgkmcnt(2)
	v_pk_fma_f32 v[160:161], v[134:135], v[54:55], v[160:161] neg_lo:[1,0,0] neg_hi:[1,0,0]
	v_pk_fma_f32 v[160:161], v[136:137], v[56:57], v[160:161] neg_lo:[1,0,0] neg_hi:[1,0,0]
	s_waitcnt lgkmcnt(1)
	v_pk_fma_f32 v[160:161], v[138:139], v[58:59], v[160:161] neg_lo:[1,0,0] neg_hi:[1,0,0]
	v_pk_fma_f32 v[160:161], v[140:141], v[60:61], v[160:161] neg_lo:[1,0,0] neg_hi:[1,0,0]
	s_waitcnt lgkmcnt(0)
	v_pk_fma_f32 v[160:161], v[142:143], v[62:63], v[160:161] neg_lo:[1,0,0] neg_hi:[1,0,0]
	v_add_f32_e32 v64, v160, v161
	ds_read_b128 v[76:79], v74 offset:16128
	ds_read_b128 v[80:83], v74 offset:16144
	ds_read_b128 v[84:87], v74 offset:16160
	ds_read_b128 v[88:91], v74 offset:16176
	ds_read_b128 v[92:95], v74 offset:16192
	ds_read_b128 v[96:99], v74 offset:16208
	ds_read_b128 v[100:103], v74 offset:16224
	ds_read_b128 v[104:107], v74 offset:16240
	ds_read_b128 v[108:111], v74 offset:16256
	ds_read_b128 v[112:115], v74 offset:16272
	ds_read_b128 v[116:119], v74 offset:16288
	ds_read_b128 v[120:123], v74 offset:16304
	ds_read_b128 v[124:127], v74 offset:16320
	ds_read_b128 v[134:137], v74 offset:16336
	ds_read_b128 v[138:141], v74 offset:16352
	ds_read_b128 v[142:145], v74 offset:16368
	s_waitcnt lgkmcnt(15)
	v_mul_f32_e32 v74, v2, v76
	v_fma_f32 v160, v65, v73, -v74
	v_fma_f32 v161, -v3, v77, 0
	v_pk_fma_f32 v[160:161], v[78:79], v[4:5], v[160:161] neg_lo:[1,0,0] neg_hi:[1,0,0]
	s_waitcnt lgkmcnt(14)
	v_pk_fma_f32 v[160:161], v[80:81], v[6:7], v[160:161] neg_lo:[1,0,0] neg_hi:[1,0,0]
	v_pk_fma_f32 v[160:161], v[82:83], v[8:9], v[160:161] neg_lo:[1,0,0] neg_hi:[1,0,0]
	s_waitcnt lgkmcnt(13)
	v_pk_fma_f32 v[160:161], v[84:85], v[10:11], v[160:161] neg_lo:[1,0,0] neg_hi:[1,0,0]
	v_pk_fma_f32 v[160:161], v[86:87], v[12:13], v[160:161] neg_lo:[1,0,0] neg_hi:[1,0,0]
	s_waitcnt lgkmcnt(12)
	v_pk_fma_f32 v[160:161], v[88:89], v[14:15], v[160:161] neg_lo:[1,0,0] neg_hi:[1,0,0]
	v_pk_fma_f32 v[160:161], v[90:91], v[16:17], v[160:161] neg_lo:[1,0,0] neg_hi:[1,0,0]
	s_waitcnt lgkmcnt(11)
	v_pk_fma_f32 v[160:161], v[92:93], v[18:19], v[160:161] neg_lo:[1,0,0] neg_hi:[1,0,0]
	v_pk_fma_f32 v[160:161], v[94:95], v[20:21], v[160:161] neg_lo:[1,0,0] neg_hi:[1,0,0]
	s_waitcnt lgkmcnt(10)
	v_pk_fma_f32 v[160:161], v[96:97], v[22:23], v[160:161] neg_lo:[1,0,0] neg_hi:[1,0,0]
	v_pk_fma_f32 v[160:161], v[98:99], v[24:25], v[160:161] neg_lo:[1,0,0] neg_hi:[1,0,0]
	s_waitcnt lgkmcnt(9)
	v_pk_fma_f32 v[160:161], v[100:101], v[26:27], v[160:161] neg_lo:[1,0,0] neg_hi:[1,0,0]
	v_pk_fma_f32 v[160:161], v[102:103], v[28:29], v[160:161] neg_lo:[1,0,0] neg_hi:[1,0,0]
	s_waitcnt lgkmcnt(8)
	v_pk_fma_f32 v[160:161], v[104:105], v[30:31], v[160:161] neg_lo:[1,0,0] neg_hi:[1,0,0]
	v_pk_fma_f32 v[160:161], v[106:107], v[32:33], v[160:161] neg_lo:[1,0,0] neg_hi:[1,0,0]
	s_waitcnt lgkmcnt(7)
	v_pk_fma_f32 v[160:161], v[108:109], v[34:35], v[160:161] neg_lo:[1,0,0] neg_hi:[1,0,0]
	v_pk_fma_f32 v[160:161], v[110:111], v[36:37], v[160:161] neg_lo:[1,0,0] neg_hi:[1,0,0]
	s_waitcnt lgkmcnt(6)
	v_pk_fma_f32 v[160:161], v[112:113], v[38:39], v[160:161] neg_lo:[1,0,0] neg_hi:[1,0,0]
	v_pk_fma_f32 v[160:161], v[114:115], v[40:41], v[160:161] neg_lo:[1,0,0] neg_hi:[1,0,0]
	s_waitcnt lgkmcnt(5)
	v_pk_fma_f32 v[160:161], v[116:117], v[42:43], v[160:161] neg_lo:[1,0,0] neg_hi:[1,0,0]
	v_pk_fma_f32 v[160:161], v[118:119], v[44:45], v[160:161] neg_lo:[1,0,0] neg_hi:[1,0,0]
	s_waitcnt lgkmcnt(4)
	v_pk_fma_f32 v[160:161], v[120:121], v[46:47], v[160:161] neg_lo:[1,0,0] neg_hi:[1,0,0]
	v_pk_fma_f32 v[160:161], v[122:123], v[48:49], v[160:161] neg_lo:[1,0,0] neg_hi:[1,0,0]
	s_waitcnt lgkmcnt(3)
	v_pk_fma_f32 v[160:161], v[124:125], v[50:51], v[160:161] neg_lo:[1,0,0] neg_hi:[1,0,0]
	v_pk_fma_f32 v[160:161], v[126:127], v[52:53], v[160:161] neg_lo:[1,0,0] neg_hi:[1,0,0]
	s_waitcnt lgkmcnt(2)
	v_pk_fma_f32 v[160:161], v[134:135], v[54:55], v[160:161] neg_lo:[1,0,0] neg_hi:[1,0,0]
	v_pk_fma_f32 v[160:161], v[136:137], v[56:57], v[160:161] neg_lo:[1,0,0] neg_hi:[1,0,0]
	s_waitcnt lgkmcnt(1)
	v_pk_fma_f32 v[160:161], v[138:139], v[58:59], v[160:161] neg_lo:[1,0,0] neg_hi:[1,0,0]
	v_pk_fma_f32 v[160:161], v[140:141], v[60:61], v[160:161] neg_lo:[1,0,0] neg_hi:[1,0,0]
	s_waitcnt lgkmcnt(0)
	v_pk_fma_f32 v[160:161], v[142:143], v[62:63], v[160:161] neg_lo:[1,0,0] neg_hi:[1,0,0]
	v_fma_f32 v160, -v64, v144, v160
	v_add_f32_e32 v65, v160, v161
	s_and_saveexec_b64 s[8:9], s[6:7]
	s_xor_b64 s[6:7], exec, s[8:9]
	s_cbranch_execz .LBB0_1188
	v_lshlrev_b32_e32 v68, 1, v72
	v_and_b32_e32 v68, 24, v68
	v_bfe_u32 v70, v132, 5, 1
	v_and_or_b32 v68, v69, 4, v68
	v_or_b32_e32 v69, v68, v66
	v_xor_b32_e32 v2, 0x80000000, v2
	v_and_or_b32 v70, v71, 8, v70
	v_add_u32_e32 v0, v130, v0
	v_bfe_u32 v72, v2, 16, 1
	v_lshlrev_b32_e32 v69, 1, v69
	v_lshlrev_b32_e32 v70, 10, v70
	v_add3_u32 v2, v2, v72, s84
	v_add3_u32 v69, v0, v69, v70
	ds_write_b16_d16_hi v69, v2 offset:33792
	v_xor_b32_e32 v2, 0x80000000, v3
	v_bfe_u32 v3, v2, 16, 1
	v_add3_u32 v2, v2, v3, s84
	ds_write_b16_d16_hi v69, v2 offset:33856
	v_xor_b32_e32 v2, 0x80000000, v4
	v_bfe_u32 v3, v2, 16, 1
	v_add3_u32 v2, v2, v3, s84
	ds_write_b16_d16_hi v69, v2 offset:33920
	v_xor_b32_e32 v2, 0x80000000, v5
	v_bfe_u32 v3, v2, 16, 1
	v_add3_u32 v2, v2, v3, s84
	ds_write_b16_d16_hi v69, v2 offset:33984
	v_xor_b32_e32 v2, 0x80000000, v6
	v_bfe_u32 v3, v2, 16, 1
	v_add3_u32 v2, v2, v3, s84
	ds_write_b16_d16_hi v69, v2 offset:34048
	v_xor_b32_e32 v2, 0x80000000, v7
	v_bfe_u32 v3, v2, 16, 1
	v_add3_u32 v2, v2, v3, s84
	ds_write_b16_d16_hi v69, v2 offset:34112
	v_xor_b32_e32 v2, 0x80000000, v8
	v_bfe_u32 v3, v2, 16, 1
	v_add3_u32 v2, v2, v3, s84
	ds_write_b16_d16_hi v69, v2 offset:34176
	v_xor_b32_e32 v2, 0x80000000, v9
	v_bfe_u32 v3, v2, 16, 1
	v_add3_u32 v2, v2, v3, s84
	ds_write_b16_d16_hi v69, v2 offset:34240
	v_xor_b32_e32 v2, 0x80000000, v10
	v_bfe_u32 v3, v2, 16, 1
	v_add3_u32 v2, v2, v3, s84
	v_bitop3_b32 v3, v68, 16, v66 bitop3:0x36
	v_lshlrev_b32_e32 v3, 1, v3
	v_add3_u32 v0, v0, v3, v70
	ds_write_b16_d16_hi v0, v2 offset:34304
	v_xor_b32_e32 v2, 0x80000000, v11
	v_bfe_u32 v3, v2, 16, 1
	v_add3_u32 v2, v2, v3, s84
	ds_write_b16_d16_hi v0, v2 offset:34368
	v_xor_b32_e32 v2, 0x80000000, v12
	v_bfe_u32 v3, v2, 16, 1
	v_add3_u32 v2, v2, v3, s84
	ds_write_b16_d16_hi v0, v2 offset:34432
	v_xor_b32_e32 v2, 0x80000000, v13
	v_bfe_u32 v3, v2, 16, 1
	v_add3_u32 v2, v2, v3, s84
	ds_write_b16_d16_hi v0, v2 offset:34496
	v_xor_b32_e32 v2, 0x80000000, v14
	v_bfe_u32 v3, v2, 16, 1
	v_add3_u32 v2, v2, v3, s84
	ds_write_b16_d16_hi v0, v2 offset:34560
	v_xor_b32_e32 v2, 0x80000000, v15
	v_bfe_u32 v3, v2, 16, 1
	v_add3_u32 v2, v2, v3, s84
	ds_write_b16_d16_hi v0, v2 offset:34624
	v_xor_b32_e32 v2, 0x80000000, v16
	v_bfe_u32 v3, v2, 16, 1
	v_add3_u32 v2, v2, v3, s84
	ds_write_b16_d16_hi v0, v2 offset:34688
	v_xor_b32_e32 v2, 0x80000000, v17
	v_bfe_u32 v3, v2, 16, 1
	v_add3_u32 v2, v2, v3, s84
	ds_write_b16_d16_hi v0, v2 offset:34752
	v_xor_b32_e32 v2, 0x80000000, v18
	v_bfe_u32 v3, v2, 16, 1
	v_add3_u32 v2, v2, v3, s84
	ds_write_b16_d16_hi v69, v2 offset:35840
	v_xor_b32_e32 v2, 0x80000000, v19
	v_bfe_u32 v3, v2, 16, 1
	v_add3_u32 v2, v2, v3, s84
	ds_write_b16_d16_hi v69, v2 offset:35904
	v_xor_b32_e32 v2, 0x80000000, v20
	v_bfe_u32 v3, v2, 16, 1
	v_add3_u32 v2, v2, v3, s84
	ds_write_b16_d16_hi v69, v2 offset:35968
	v_xor_b32_e32 v2, 0x80000000, v21
	v_bfe_u32 v3, v2, 16, 1
	v_add3_u32 v2, v2, v3, s84
	ds_write_b16_d16_hi v69, v2 offset:36032
	v_xor_b32_e32 v2, 0x80000000, v22
	v_bfe_u32 v3, v2, 16, 1
	v_add3_u32 v2, v2, v3, s84
	ds_write_b16_d16_hi v69, v2 offset:36096
	v_xor_b32_e32 v2, 0x80000000, v23
	v_bfe_u32 v3, v2, 16, 1
	v_add3_u32 v2, v2, v3, s84
	ds_write_b16_d16_hi v69, v2 offset:36160
	v_xor_b32_e32 v2, 0x80000000, v24
	v_bfe_u32 v3, v2, 16, 1
	v_add3_u32 v2, v2, v3, s84
	ds_write_b16_d16_hi v69, v2 offset:36224
	v_xor_b32_e32 v2, 0x80000000, v25
	v_bfe_u32 v3, v2, 16, 1
	v_add3_u32 v2, v2, v3, s84
	ds_write_b16_d16_hi v69, v2 offset:36288
	v_xor_b32_e32 v2, 0x80000000, v26
	v_bfe_u32 v3, v2, 16, 1
	v_add3_u32 v2, v2, v3, s84
	ds_write_b16_d16_hi v0, v2 offset:36352
	v_xor_b32_e32 v2, 0x80000000, v27
	v_bfe_u32 v3, v2, 16, 1
	v_add3_u32 v2, v2, v3, s84
	ds_write_b16_d16_hi v0, v2 offset:36416
	v_xor_b32_e32 v2, 0x80000000, v28
	v_bfe_u32 v3, v2, 16, 1
	v_add3_u32 v2, v2, v3, s84
	ds_write_b16_d16_hi v0, v2 offset:36480
	v_xor_b32_e32 v2, 0x80000000, v29
	v_bfe_u32 v3, v2, 16, 1
	v_add3_u32 v2, v2, v3, s84
	ds_write_b16_d16_hi v0, v2 offset:36544
	v_xor_b32_e32 v2, 0x80000000, v30
	v_bfe_u32 v3, v2, 16, 1
	v_add3_u32 v2, v2, v3, s84
	ds_write_b16_d16_hi v0, v2 offset:36608
	v_xor_b32_e32 v2, 0x80000000, v31
	v_bfe_u32 v3, v2, 16, 1
	v_add3_u32 v2, v2, v3, s84
	ds_write_b16_d16_hi v0, v2 offset:36672
	v_xor_b32_e32 v2, 0x80000000, v32
	v_bfe_u32 v3, v2, 16, 1
	v_add3_u32 v2, v2, v3, s84
	ds_write_b16_d16_hi v0, v2 offset:36736
	v_xor_b32_e32 v2, 0x80000000, v33
	v_bfe_u32 v3, v2, 16, 1
	v_add3_u32 v2, v2, v3, s84
	ds_write_b16_d16_hi v0, v2 offset:36800
	v_xor_b32_e32 v2, 0x80000000, v34
	v_bfe_u32 v3, v2, 16, 1
	v_add3_u32 v2, v2, v3, s84
	ds_write_b16_d16_hi v69, v2 offset:37888
	v_xor_b32_e32 v2, 0x80000000, v35
	v_bfe_u32 v3, v2, 16, 1
	v_add3_u32 v2, v2, v3, s84
	ds_write_b16_d16_hi v69, v2 offset:37952
	v_xor_b32_e32 v2, 0x80000000, v36
	v_bfe_u32 v3, v2, 16, 1
	v_add3_u32 v2, v2, v3, s84
	ds_write_b16_d16_hi v69, v2 offset:38016
	v_xor_b32_e32 v2, 0x80000000, v37
	v_bfe_u32 v3, v2, 16, 1
	v_add3_u32 v2, v2, v3, s84
	ds_write_b16_d16_hi v69, v2 offset:38080
	v_xor_b32_e32 v2, 0x80000000, v38
	v_bfe_u32 v3, v2, 16, 1
	v_add3_u32 v2, v2, v3, s84
	ds_write_b16_d16_hi v69, v2 offset:38144
	v_xor_b32_e32 v2, 0x80000000, v39
	v_bfe_u32 v3, v2, 16, 1
	v_add3_u32 v2, v2, v3, s84
	ds_write_b16_d16_hi v69, v2 offset:38208
	v_xor_b32_e32 v2, 0x80000000, v40
	v_bfe_u32 v3, v2, 16, 1
	v_add3_u32 v2, v2, v3, s84
	ds_write_b16_d16_hi v69, v2 offset:38272
	v_xor_b32_e32 v2, 0x80000000, v41
	v_bfe_u32 v3, v2, 16, 1
	v_add3_u32 v2, v2, v3, s84
	ds_write_b16_d16_hi v69, v2 offset:38336
	v_xor_b32_e32 v2, 0x80000000, v42
	v_bfe_u32 v3, v2, 16, 1
	v_add3_u32 v2, v2, v3, s84
	ds_write_b16_d16_hi v0, v2 offset:38400
	v_xor_b32_e32 v2, 0x80000000, v43
	v_bfe_u32 v3, v2, 16, 1
	v_add3_u32 v2, v2, v3, s84
	ds_write_b16_d16_hi v0, v2 offset:38464
	v_xor_b32_e32 v2, 0x80000000, v44
	v_bfe_u32 v3, v2, 16, 1
	v_add3_u32 v2, v2, v3, s84
	ds_write_b16_d16_hi v0, v2 offset:38528
	v_xor_b32_e32 v2, 0x80000000, v45
	v_bfe_u32 v3, v2, 16, 1
	v_add3_u32 v2, v2, v3, s84
	ds_write_b16_d16_hi v0, v2 offset:38592
	v_xor_b32_e32 v2, 0x80000000, v46
	v_bfe_u32 v3, v2, 16, 1
	v_add3_u32 v2, v2, v3, s84
	ds_write_b16_d16_hi v0, v2 offset:38656
	v_xor_b32_e32 v2, 0x80000000, v47
	v_bfe_u32 v3, v2, 16, 1
	v_add3_u32 v2, v2, v3, s84
	ds_write_b16_d16_hi v0, v2 offset:38720
	v_xor_b32_e32 v2, 0x80000000, v48
	v_bfe_u32 v3, v2, 16, 1
	v_add3_u32 v2, v2, v3, s84
	ds_write_b16_d16_hi v0, v2 offset:38784
	v_xor_b32_e32 v2, 0x80000000, v49
	v_bfe_u32 v3, v2, 16, 1
	v_add3_u32 v2, v2, v3, s84
	ds_write_b16_d16_hi v0, v2 offset:38848
	v_xor_b32_e32 v2, 0x80000000, v50
	v_bfe_u32 v3, v2, 16, 1
	v_add3_u32 v2, v2, v3, s84
	ds_write_b16_d16_hi v69, v2 offset:39936
	v_xor_b32_e32 v2, 0x80000000, v51
	v_bfe_u32 v3, v2, 16, 1
	v_add3_u32 v2, v2, v3, s84
	ds_write_b16_d16_hi v69, v2 offset:40000
	v_xor_b32_e32 v2, 0x80000000, v52
	v_bfe_u32 v3, v2, 16, 1
	v_add3_u32 v2, v2, v3, s84
	ds_write_b16_d16_hi v69, v2 offset:40064
	v_xor_b32_e32 v2, 0x80000000, v53
	v_bfe_u32 v3, v2, 16, 1
	v_add3_u32 v2, v2, v3, s84
	ds_write_b16_d16_hi v69, v2 offset:40128
	v_xor_b32_e32 v2, 0x80000000, v54
	v_bfe_u32 v3, v2, 16, 1
	v_add3_u32 v2, v2, v3, s84
	ds_write_b16_d16_hi v69, v2 offset:40192
	v_xor_b32_e32 v2, 0x80000000, v55
	v_bfe_u32 v3, v2, 16, 1
	v_add3_u32 v2, v2, v3, s84
	ds_write_b16_d16_hi v69, v2 offset:40256
	v_xor_b32_e32 v2, 0x80000000, v56
	v_bfe_u32 v3, v2, 16, 1
	v_add3_u32 v2, v2, v3, s84
	ds_write_b16_d16_hi v69, v2 offset:40320
	v_xor_b32_e32 v2, 0x80000000, v57
	v_bfe_u32 v3, v2, 16, 1
	v_add3_u32 v2, v2, v3, s84
	ds_write_b16_d16_hi v69, v2 offset:40384
	v_xor_b32_e32 v2, 0x80000000, v58
	v_bfe_u32 v3, v2, 16, 1
	v_add3_u32 v2, v2, v3, s84
	ds_write_b16_d16_hi v0, v2 offset:40448
	v_xor_b32_e32 v2, 0x80000000, v59
	v_bfe_u32 v3, v2, 16, 1
	v_add3_u32 v2, v2, v3, s84
	ds_write_b16_d16_hi v0, v2 offset:40512
	v_xor_b32_e32 v2, 0x80000000, v60
	v_bfe_u32 v3, v2, 16, 1
	v_add3_u32 v2, v2, v3, s84
	ds_write_b16_d16_hi v0, v2 offset:40576
	v_xor_b32_e32 v2, 0x80000000, v61
	v_bfe_u32 v3, v2, 16, 1
	v_add3_u32 v2, v2, v3, s84
	ds_write_b16_d16_hi v0, v2 offset:40640
	v_xor_b32_e32 v2, 0x80000000, v62
	v_bfe_u32 v3, v2, 16, 1
	v_add3_u32 v2, v2, v3, s84
	ds_write_b16_d16_hi v0, v2 offset:40704
	v_xor_b32_e32 v2, 0x80000000, v63
	v_bfe_u32 v3, v2, 16, 1
	v_add3_u32 v2, v2, v3, s84
	ds_write_b16_d16_hi v0, v2 offset:40768
	v_xor_b32_e32 v2, 0x80000000, v64
	v_bfe_u32 v3, v2, 16, 1
	v_add3_u32 v2, v2, v3, s84
	ds_write_b16_d16_hi v0, v2 offset:40832
	v_xor_b32_e32 v2, 0x80000000, v65
	v_bfe_u32 v3, v2, 16, 1
	v_add3_u32 v2, v2, v3, s84
	ds_write_b16_d16_hi v0, v2 offset:40896
